# GEMM loops: s_setprio 1 before the barrier that opens a MFMA segment, mid-segment priority flips removed
# speedup vs baseline: 1.0292x; 1.0017x over previous
; #define PG8_STAGE(bufoff, gbase, voff) do { _Pragma("unroll") for (int _i = 0; _i < 2; ++_i) \
;         __builtin_amdgcn_global_load_lds((const unsigned*)((const char*)(gbase) + (voff)[_i]), (PG8_LAS unsigned*)(lds + (bufoff) + ldsw + _i * 8192), 16, 0, 0); } while (0)
; #define PG8_LDA(dst, b, h) do { _Pragma("unroll") for (int m = 0; m < 4; ++m) _Pragma("unroll") for (int k = 0; k < 2; ++k) dst[m][k] = *(const PG8_LAS bf16x8*)(lds + PG8_SA(b, h) + aoff + m * 2048 + k * 1024); } while (0)
; #define PG8_LDB(dst, b, h) do { _Pragma("unroll") for (int n = 0; n < 2; ++n) _Pragma("unroll") for (int k = 0; k < 2; ++k) dst[n][k] = *(const PG8_LAS bf16x8*)(lds + PG8_SB(b, h) + boff + n * 2048 + k * 1024); } while (0)
; #define PG8_MMA(ai, bj, At, Bt) do { __builtin_amdgcn_s_setprio(1); _Pragma("unroll") for (int m = 0; m < 4; ++m) _Pragma("unroll") for (int n = 0; n < 2; ++n) _Pragma("unroll") for (int k = 0; k < 2; ++k) \
;         acc[ai][bj][m][n] = __builtin_amdgcn_mfma_f32_16x16x32_bf16(Bt[n][k], At[m][k], acc[ai][bj][m][n], 0, 0, 0); __builtin_amdgcn_s_setprio(0); } while (0)
; #define PG8_WAIT_V(n) asm volatile("s_waitcnt vmcnt(" #n ")" ::: "memory")
; #define PG8_WAIT_L(n) asm volatile("s_waitcnt lgkmcnt(" #n ")" ::: "memory")
; #define PG8_BAR __builtin_amdgcn_s_barrier()
; #define PG8_SCHED __builtin_amdgcn_sched_barrier(0)
;     ...
;             const bool last = (t == nt - 2);
;             const char* a1 = PG8_KADV(cA, (size_t)(t + 1) * kstep);
;             const char* a2 = last ? nA : PG8_KADV(cA, (size_t)(t + 2) * kstep); const char* b2 = last ? nB : PG8_KADV(cB, (size_t)(t + 2) * kstep);
;             const char* a3 = PG8_KADV(a2, kstep); const char* b3 = PG8_KADV(b2, kstep);
;             if (last && has_next) S.a_ready(nxt);
;             if constexpr (SP2) {
;             PG8_LDB(B0, 0, 0); PG8_LDB(B1, 0, 1); PG8_SCHED; PG8_LDA(At, 0, 0); PG8_STAGE(PG8_SA(1, 1), a1 + hstep, voffA);
;             PG8_WAIT_V(8); PG8_WAIT_L(0); PG8_BAR; PG8_MMA(0, 0, At, B0); PG8_MMA(0, 1, At, B1); PG8_BAR; PG8_SCHED;
;             PG8_LDA(At, 0, 1); PG8_STAGE(PG8_SB(0, 0), b2, voffB); PG8_STAGE(PG8_SB(0, 1), b2 + hstep, voffB); PG8_STAGE(PG8_SA(0, 0), a2, voffA);
;             PG8_WAIT_V(8); PG8_WAIT_L(0); PG8_BAR; PG8_MMA(1, 0, At, B0); PG8_MMA(1, 1, At, B1); PG8_BAR; PG8_SCHED;
.LBB0_230:
	s_add_u32 s12, s80, 0xfff80080
	s_addc_u32 s13, s81, -1
	s_add_i32 s30, 0, 0x10000
	s_cmp_eq_u32 s28, 28
	s_cselect_b32 s85, s15, s13
	s_cselect_b32 s84, s20, s12
	s_cselect_b32 s83, s21, s25
	s_cselect_b32 s82, s22, s23
	s_add_i32 s12, 0, 0x14000
	v_add_u32_e32 v156, s30, v141
	v_add_u32_e32 v168, s12, v141
	ds_read_b128 v[144:147], v156
	ds_read_b128 v[148:151], v156 offset:1024
	ds_read_b128 v[152:155], v156 offset:2048
	ds_read_b128 v[156:159], v156 offset:3072
	ds_read_b128 v[160:163], v168
	ds_read_b128 v[164:167], v168 offset:1024
	ds_read_b128 v[182:185], v168 offset:2048
	ds_read_b128 v[186:189], v168 offset:3072
	s_add_i32 m0, s1, 0xc000
	ds_read_b128 v[190:193], v143
	ds_read_b128 v[194:197], v143 offset:1024
	ds_read_b128 v[198:201], v143 offset:2048
	ds_read_b128 v[202:205], v143 offset:3072
	ds_read_b128 v[206:209], v143 offset:4096
	ds_read_b128 v[210:213], v143 offset:5120
	ds_read_b128 v[214:217], v143 offset:6144
	ds_read_b128 v[218:221], v143 offset:7168
	global_load_lds_dwordx4 v136, s[80:81]
	s_add_i32 m0, s1, 0xe000
	s_nop 0
	global_load_lds_dwordx4 v138, s[80:81]
	s_waitcnt vmcnt(8)
	s_waitcnt lgkmcnt(0)
	s_setprio 1
	s_barrier
	v_mfma_f32_16x16x32_bf16 v[124:127], v[144:147], v[190:193], v[124:127]
	v_mfma_f32_16x16x32_bf16 v[124:127], v[148:151], v[194:197], v[124:127]
	v_mfma_f32_16x16x32_bf16 v[108:111], v[144:147], v[198:201], v[108:111]
	v_mfma_f32_16x16x32_bf16 v[108:111], v[148:151], v[202:205], v[108:111]
	v_mfma_f32_16x16x32_bf16 v[92:95], v[144:147], v[206:209], v[92:95]
	v_mfma_f32_16x16x32_bf16 v[92:95], v[148:151], v[210:213], v[92:95]
	v_mfma_f32_16x16x32_bf16 v[76:79], v[144:147], v[214:217], v[76:79]
	v_mfma_f32_16x16x32_bf16 v[76:79], v[148:151], v[218:221], v[76:79]
	v_mfma_f32_16x16x32_bf16 v[120:123], v[152:155], v[190:193], v[120:123]
	v_mfma_f32_16x16x32_bf16 v[120:123], v[156:159], v[194:197], v[120:123]
	v_mfma_f32_16x16x32_bf16 v[104:107], v[152:155], v[198:201], v[104:107]
	v_mfma_f32_16x16x32_bf16 v[104:107], v[156:159], v[202:205], v[104:107]
	v_mfma_f32_16x16x32_bf16 v[88:91], v[152:155], v[206:209], v[88:91]
	v_mfma_f32_16x16x32_bf16 v[88:91], v[156:159], v[210:213], v[88:91]
	v_mfma_f32_16x16x32_bf16 v[72:75], v[152:155], v[214:217], v[72:75]
	v_mfma_f32_16x16x32_bf16 v[72:75], v[156:159], v[218:221], v[72:75]
	v_mfma_f32_16x16x32_bf16 v[116:119], v[160:163], v[190:193], v[116:119]
	v_mfma_f32_16x16x32_bf16 v[116:119], v[164:167], v[194:197], v[116:119]
	v_mfma_f32_16x16x32_bf16 v[100:103], v[160:163], v[198:201], v[100:103]
	v_mfma_f32_16x16x32_bf16 v[100:103], v[164:167], v[202:205], v[100:103]
	v_mfma_f32_16x16x32_bf16 v[84:87], v[160:163], v[206:209], v[84:87]
	v_mfma_f32_16x16x32_bf16 v[84:87], v[164:167], v[210:213], v[84:87]
	v_mfma_f32_16x16x32_bf16 v[68:71], v[160:163], v[214:217], v[68:71]
	v_mfma_f32_16x16x32_bf16 v[68:71], v[164:167], v[218:221], v[68:71]
	v_mfma_f32_16x16x32_bf16 v[112:115], v[182:185], v[190:193], v[112:115]
	v_mfma_f32_16x16x32_bf16 v[112:115], v[186:189], v[194:197], v[112:115]
	v_mfma_f32_16x16x32_bf16 v[96:99], v[182:185], v[198:201], v[96:99]
	v_mfma_f32_16x16x32_bf16 v[96:99], v[186:189], v[202:205], v[96:99]
	v_mfma_f32_16x16x32_bf16 v[80:83], v[182:185], v[206:209], v[80:83]
	v_mfma_f32_16x16x32_bf16 v[80:83], v[186:189], v[210:213], v[80:83]
	v_mfma_f32_16x16x32_bf16 v[64:67], v[182:185], v[214:217], v[64:67]
	v_mfma_f32_16x16x32_bf16 v[64:67], v[186:189], v[218:221], v[64:67]
	s_barrier
	s_setprio 0
	s_add_i32 s13, s30, s0
	s_mov_b32 m0, s13
	ds_read_b128 v[190:193], v143 offset:16384
	ds_read_b128 v[194:197], v143 offset:17408
	ds_read_b128 v[198:201], v143 offset:18432
	ds_read_b128 v[202:205], v143 offset:19456
	ds_read_b128 v[206:209], v143 offset:20480
	ds_read_b128 v[210:213], v143 offset:21504
	ds_read_b128 v[214:217], v143 offset:22528
	ds_read_b128 v[218:221], v143 offset:23552
	global_load_lds_dwordx4 v132, s[82:83]
	s_add_i32 m0, s13, 0x2000
	s_add_u32 s42, s82, 0x80000
	s_addc_u32 s43, s83, 0
	s_add_i32 s12, s12, s0
	global_load_lds_dwordx4 v128, s[82:83]
	s_mov_b32 m0, s12
	s_nop 0
	global_load_lds_dwordx4 v132, s[42:43]
	s_add_i32 m0, s12, 0x2000
	s_nop 0
	global_load_lds_dwordx4 v128, s[42:43]
	s_mov_b32 m0, s1
	s_nop 0
	global_load_lds_dwordx4 v134, s[84:85]
	s_mov_b32 m0, s2
	s_nop 0
	global_load_lds_dwordx4 v130, s[84:85]
	s_waitcnt vmcnt(8)
	s_waitcnt lgkmcnt(0)
	s_setprio 1
	s_barrier
	v_mfma_f32_16x16x32_bf16 v[60:63], v[144:147], v[190:193], v[60:63]
	v_mfma_f32_16x16x32_bf16 v[60:63], v[148:151], v[194:197], v[60:63]
	v_mfma_f32_16x16x32_bf16 v[44:47], v[144:147], v[198:201], v[44:47]
	v_mfma_f32_16x16x32_bf16 v[44:47], v[148:151], v[202:205], v[44:47]
	v_mfma_f32_16x16x32_bf16 v[28:31], v[144:147], v[206:209], v[28:31]
	v_mfma_f32_16x16x32_bf16 v[28:31], v[148:151], v[210:213], v[28:31]
	v_mfma_f32_16x16x32_bf16 v[12:15], v[144:147], v[214:217], v[12:15]
	v_mfma_f32_16x16x32_bf16 v[12:15], v[148:151], v[218:221], v[12:15]
	v_mfma_f32_16x16x32_bf16 v[56:59], v[152:155], v[190:193], v[56:59]
	v_mfma_f32_16x16x32_bf16 v[56:59], v[156:159], v[194:197], v[56:59]
	v_mfma_f32_16x16x32_bf16 v[40:43], v[152:155], v[198:201], v[40:43]
	v_mfma_f32_16x16x32_bf16 v[40:43], v[156:159], v[202:205], v[40:43]
	v_mfma_f32_16x16x32_bf16 v[24:27], v[152:155], v[206:209], v[24:27]
	v_mfma_f32_16x16x32_bf16 v[24:27], v[156:159], v[210:213], v[24:27]
	v_mfma_f32_16x16x32_bf16 v[8:11], v[152:155], v[214:217], v[8:11]
	v_mfma_f32_16x16x32_bf16 v[8:11], v[156:159], v[218:221], v[8:11]
	v_mfma_f32_16x16x32_bf16 v[52:55], v[160:163], v[190:193], v[52:55]
	v_mfma_f32_16x16x32_bf16 v[52:55], v[164:167], v[194:197], v[52:55]
	v_mfma_f32_16x16x32_bf16 v[36:39], v[160:163], v[198:201], v[36:39]
	v_mfma_f32_16x16x32_bf16 v[36:39], v[164:167], v[202:205], v[36:39]
	v_mfma_f32_16x16x32_bf16 v[20:23], v[160:163], v[206:209], v[20:23]
	v_mfma_f32_16x16x32_bf16 v[20:23], v[164:167], v[210:213], v[20:23]
	v_mfma_f32_16x16x32_bf16 v[4:7], v[160:163], v[214:217], v[4:7]
	v_mfma_f32_16x16x32_bf16 v[4:7], v[164:167], v[218:221], v[4:7]
	v_mfma_f32_16x16x32_bf16 v[48:51], v[182:185], v[190:193], v[48:51]
	v_mfma_f32_16x16x32_bf16 v[48:51], v[186:189], v[194:197], v[48:51]
	v_mfma_f32_16x16x32_bf16 v[32:35], v[182:185], v[198:201], v[32:35]
	v_mfma_f32_16x16x32_bf16 v[32:35], v[186:189], v[202:205], v[32:35]
	v_mfma_f32_16x16x32_bf16 v[16:19], v[182:185], v[206:209], v[16:19]
	v_mfma_f32_16x16x32_bf16 v[16:19], v[186:189], v[210:213], v[16:19]
	v_mfma_f32_16x16x32_bf16 v[0:3], v[182:185], v[214:217], v[0:3]
	v_mfma_f32_16x16x32_bf16 v[0:3], v[186:189], v[218:221], v[0:3]
	s_barrier
; #define PG8_STAGE(bufoff, gbase, voff) do { _Pragma("unroll") for (int _i = 0; _i < 2; ++_i) \
;         __builtin_amdgcn_global_load_lds((const unsigned*)((const char*)(gbase) + (voff)[_i]), (PG8_LAS unsigned*)(lds + (bufoff) + ldsw + _i * 8192), 16, 0, 0); } while (0)
; #define PG8_LDA(dst, b, h) do { _Pragma("unroll") for (int m = 0; m < 4; ++m) _Pragma("unroll") for (int k = 0; k < 2; ++k) dst[m][k] = *(const PG8_LAS bf16x8*)(lds + PG8_SA(b, h) + aoff + m * 2048 + k * 1024); } while (0)
; #define PG8_LDB(dst, b, h) do { _Pragma("unroll") for (int n = 0; n < 2; ++n) _Pragma("unroll") for (int k = 0; k < 2; ++k) dst[n][k] = *(const PG8_LAS bf16x8*)(lds + PG8_SB(b, h) + boff + n * 2048 + k * 1024); } while (0)
; #define PG8_MMA(ai, bj, At, Bt) do { __builtin_amdgcn_s_setprio(1); _Pragma("unroll") for (int m = 0; m < 4; ++m) _Pragma("unroll") for (int n = 0; n < 2; ++n) _Pragma("unroll") for (int k = 0; k < 2; ++k) \
;         acc[ai][bj][m][n] = __builtin_amdgcn_mfma_f32_16x16x32_bf16(Bt[n][k], At[m][k], acc[ai][bj][m][n], 0, 0, 0); __builtin_amdgcn_s_setprio(0); } while (0)
; #define PG8_WAIT_V(n) asm volatile("s_waitcnt vmcnt(" #n ")" ::: "memory")
; #define PG8_WAIT_L(n) asm volatile("s_waitcnt lgkmcnt(" #n ")" ::: "memory")
; #define PG8_BAR __builtin_amdgcn_s_barrier()
; #define PG8_SCHED __builtin_amdgcn_sched_barrier(0)
;     ...
;             PG8_LDB(B0, 1, 0); PG8_LDB(B1, 1, 1); PG8_SCHED; PG8_LDA(At, 1, 0); PG8_STAGE(PG8_SA(0, 1), a2 + hstep, voffA);
;             PG8_WAIT_V(8); PG8_WAIT_L(0); PG8_BAR; PG8_MMA(0, 0, At, B0); PG8_MMA(0, 1, At, B1); PG8_BAR; PG8_SCHED;
;             PG8_LDA(At, 1, 1); PG8_STAGE(PG8_SB(1, 0), b3, voffB); PG8_STAGE(PG8_SB(1, 1), b3 + hstep, voffB); PG8_STAGE(PG8_SA(1, 0), a3, voffA);
;             PG8_WAIT_V(8); PG8_WAIT_L(0); PG8_BAR; PG8_MMA(1, 0, At, B0); PG8_MMA(1, 1, At, B1); PG8_BAR; PG8_SCHED;
	s_setprio 0
	s_add_i32 s12, 0, 0x18000
	s_add_i32 s13, 0, 0x1c000
	v_add_u32_e32 v156, s12, v141
	v_add_u32_e32 v168, s13, v141
	ds_read_b128 v[144:147], v156
	ds_read_b128 v[148:151], v156 offset:1024
	ds_read_b128 v[152:155], v156 offset:2048
	ds_read_b128 v[156:159], v156 offset:3072
	ds_read_b128 v[160:163], v168
	ds_read_b128 v[164:167], v168 offset:1024
	ds_read_b128 v[182:185], v168 offset:2048
	ds_read_b128 v[186:189], v168 offset:3072
	s_add_u32 s42, s84, 0x80000
	s_addc_u32 s43, s85, 0
	s_mov_b32 m0, s3
	ds_read_b128 v[190:193], v143 offset:32768
	ds_read_b128 v[194:197], v143 offset:33792
	ds_read_b128 v[198:201], v143 offset:34816
	ds_read_b128 v[202:205], v143 offset:35840
	ds_read_b128 v[206:209], v143 offset:36864
	ds_read_b128 v[210:213], v143 offset:37888
	ds_read_b128 v[214:217], v143 offset:38912
	ds_read_b128 v[218:221], v143 offset:39936
	global_load_lds_dwordx4 v134, s[42:43]
	s_mov_b32 m0, s8
	s_nop 0
	global_load_lds_dwordx4 v130, s[42:43]
	s_waitcnt vmcnt(8)
	s_waitcnt lgkmcnt(0)
	s_setprio 1
	s_barrier
	v_mfma_f32_16x16x32_bf16 v[124:127], v[144:147], v[190:193], v[124:127]
	v_mfma_f32_16x16x32_bf16 v[124:127], v[148:151], v[194:197], v[124:127]
	v_mfma_f32_16x16x32_bf16 v[108:111], v[144:147], v[198:201], v[108:111]
	v_mfma_f32_16x16x32_bf16 v[108:111], v[148:151], v[202:205], v[108:111]
	v_mfma_f32_16x16x32_bf16 v[92:95], v[144:147], v[206:209], v[92:95]
	v_mfma_f32_16x16x32_bf16 v[92:95], v[148:151], v[210:213], v[92:95]
	v_mfma_f32_16x16x32_bf16 v[76:79], v[144:147], v[214:217], v[76:79]
	v_mfma_f32_16x16x32_bf16 v[76:79], v[148:151], v[218:221], v[76:79]
	v_mfma_f32_16x16x32_bf16 v[120:123], v[152:155], v[190:193], v[120:123]
	v_mfma_f32_16x16x32_bf16 v[120:123], v[156:159], v[194:197], v[120:123]
	v_mfma_f32_16x16x32_bf16 v[104:107], v[152:155], v[198:201], v[104:107]
	v_mfma_f32_16x16x32_bf16 v[104:107], v[156:159], v[202:205], v[104:107]
	v_mfma_f32_16x16x32_bf16 v[88:91], v[152:155], v[206:209], v[88:91]
	v_mfma_f32_16x16x32_bf16 v[88:91], v[156:159], v[210:213], v[88:91]
	v_mfma_f32_16x16x32_bf16 v[72:75], v[152:155], v[214:217], v[72:75]
	v_mfma_f32_16x16x32_bf16 v[72:75], v[156:159], v[218:221], v[72:75]
	v_mfma_f32_16x16x32_bf16 v[116:119], v[160:163], v[190:193], v[116:119]
	v_mfma_f32_16x16x32_bf16 v[116:119], v[164:167], v[194:197], v[116:119]
	v_mfma_f32_16x16x32_bf16 v[100:103], v[160:163], v[198:201], v[100:103]
	v_mfma_f32_16x16x32_bf16 v[100:103], v[164:167], v[202:205], v[100:103]
	v_mfma_f32_16x16x32_bf16 v[84:87], v[160:163], v[206:209], v[84:87]
	v_mfma_f32_16x16x32_bf16 v[84:87], v[164:167], v[210:213], v[84:87]
	v_mfma_f32_16x16x32_bf16 v[68:71], v[160:163], v[214:217], v[68:71]
	v_mfma_f32_16x16x32_bf16 v[68:71], v[164:167], v[218:221], v[68:71]
	v_mfma_f32_16x16x32_bf16 v[112:115], v[182:185], v[190:193], v[112:115]
	v_mfma_f32_16x16x32_bf16 v[112:115], v[186:189], v[194:197], v[112:115]
	v_mfma_f32_16x16x32_bf16 v[96:99], v[182:185], v[198:201], v[96:99]
	v_mfma_f32_16x16x32_bf16 v[96:99], v[186:189], v[202:205], v[96:99]
	v_mfma_f32_16x16x32_bf16 v[80:83], v[182:185], v[206:209], v[80:83]
	v_mfma_f32_16x16x32_bf16 v[80:83], v[186:189], v[210:213], v[80:83]
	v_mfma_f32_16x16x32_bf16 v[64:67], v[182:185], v[214:217], v[64:67]
	v_mfma_f32_16x16x32_bf16 v[64:67], v[186:189], v[218:221], v[64:67]
	s_barrier
	s_setprio 0
	s_add_i32 s12, s12, s0
	s_mov_b32 m0, s12
	ds_read_b128 v[190:193], v143 offset:49152
	ds_read_b128 v[194:197], v143 offset:50176
	ds_read_b128 v[198:201], v143 offset:51200
	ds_read_b128 v[202:205], v143 offset:52224
	ds_read_b128 v[206:209], v143 offset:53248
	ds_read_b128 v[210:213], v143 offset:54272
	ds_read_b128 v[214:217], v143 offset:55296
	ds_read_b128 v[218:221], v143 offset:56320
	s_add_u32 s100, s82, s16
	s_addc_u32 s101, s83, s17
	global_load_lds_dwordx4 v132, s[100:101]
	s_add_i32 m0, s12, 0x2000
	s_add_u32 s42, s82, 0x80080
	s_addc_u32 s43, s83, 0
	s_add_i32 s12, s13, s0
	global_load_lds_dwordx4 v128, s[100:101]
	s_mov_b32 m0, s12
	s_nop 0
	global_load_lds_dwordx4 v132, s[42:43]
	s_add_i32 m0, s12, 0x2000
	s_nop 0
	global_load_lds_dwordx4 v128, s[42:43]
	s_mov_b32 m0, s9
	s_nop 0
	s_add_u32 s100, s84, s16
	s_addc_u32 s101, s85, s17
	global_load_lds_dwordx4 v134, s[100:101]
	s_mov_b32 m0, s10
	s_nop 0
	global_load_lds_dwordx4 v130, s[100:101]
	s_waitcnt vmcnt(8)
	s_waitcnt lgkmcnt(0)
	s_setprio 1
	s_barrier
	v_mfma_f32_16x16x32_bf16 v[60:63], v[144:147], v[190:193], v[60:63]
	v_mfma_f32_16x16x32_bf16 v[60:63], v[148:151], v[194:197], v[60:63]
	v_mfma_f32_16x16x32_bf16 v[44:47], v[144:147], v[198:201], v[44:47]
	v_mfma_f32_16x16x32_bf16 v[44:47], v[148:151], v[202:205], v[44:47]
	v_mfma_f32_16x16x32_bf16 v[28:31], v[144:147], v[206:209], v[28:31]
	v_mfma_f32_16x16x32_bf16 v[28:31], v[148:151], v[210:213], v[28:31]
	v_mfma_f32_16x16x32_bf16 v[12:15], v[144:147], v[214:217], v[12:15]
	v_mfma_f32_16x16x32_bf16 v[12:15], v[148:151], v[218:221], v[12:15]
	v_mfma_f32_16x16x32_bf16 v[56:59], v[152:155], v[190:193], v[56:59]
	v_mfma_f32_16x16x32_bf16 v[56:59], v[156:159], v[194:197], v[56:59]
	v_mfma_f32_16x16x32_bf16 v[40:43], v[152:155], v[198:201], v[40:43]
	v_mfma_f32_16x16x32_bf16 v[40:43], v[156:159], v[202:205], v[40:43]
	v_mfma_f32_16x16x32_bf16 v[24:27], v[152:155], v[206:209], v[24:27]
	v_mfma_f32_16x16x32_bf16 v[24:27], v[156:159], v[210:213], v[24:27]
	v_mfma_f32_16x16x32_bf16 v[8:11], v[152:155], v[214:217], v[8:11]
	v_mfma_f32_16x16x32_bf16 v[8:11], v[156:159], v[218:221], v[8:11]
	v_mfma_f32_16x16x32_bf16 v[52:55], v[160:163], v[190:193], v[52:55]
	v_mfma_f32_16x16x32_bf16 v[52:55], v[164:167], v[194:197], v[52:55]
	v_mfma_f32_16x16x32_bf16 v[36:39], v[160:163], v[198:201], v[36:39]
	v_mfma_f32_16x16x32_bf16 v[36:39], v[164:167], v[202:205], v[36:39]
	v_mfma_f32_16x16x32_bf16 v[20:23], v[160:163], v[206:209], v[20:23]
	v_mfma_f32_16x16x32_bf16 v[20:23], v[164:167], v[210:213], v[20:23]
	v_mfma_f32_16x16x32_bf16 v[4:7], v[160:163], v[214:217], v[4:7]
	v_mfma_f32_16x16x32_bf16 v[4:7], v[164:167], v[218:221], v[4:7]
	v_mfma_f32_16x16x32_bf16 v[48:51], v[182:185], v[190:193], v[48:51]
	v_mfma_f32_16x16x32_bf16 v[48:51], v[186:189], v[194:197], v[48:51]
	v_mfma_f32_16x16x32_bf16 v[32:35], v[182:185], v[198:201], v[32:35]
	v_mfma_f32_16x16x32_bf16 v[32:35], v[186:189], v[202:205], v[32:35]
	v_mfma_f32_16x16x32_bf16 v[16:19], v[182:185], v[206:209], v[16:19]
	v_mfma_f32_16x16x32_bf16 v[16:19], v[186:189], v[210:213], v[16:19]
	v_mfma_f32_16x16x32_bf16 v[0:3], v[182:185], v[214:217], v[0:3]
	v_mfma_f32_16x16x32_bf16 v[0:3], v[186:189], v[218:221], v[0:3]
	s_barrier
	s_setprio 0
	s_add_i32 s28, s28, 2
	s_add_u32 s80, s80, 0x100
	s_addc_u32 s81, s81, 0
	s_add_u32 s23, s23, 0x100
	s_addc_u32 s25, s25, 0
	s_cmp_gt_u32 s28, 29
	s_cbranch_scc0 .LBB0_230
	s_and_b64 vcc, exec, s[68:69]
	s_cbranch_vccz .LBB0_233
	s_barrier

; #define PG8_STAGE(bufoff, gbase, voff) do { _Pragma("unroll") for (int _i = 0; _i < 2; ++_i) \
;         __builtin_amdgcn_global_load_lds((const unsigned*)((const char*)(gbase) + (voff)[_i]), (PG8_LAS unsigned*)(lds + (bufoff) + ldsw + _i * 8192), 16, 0, 0); } while (0)
; #define PG8_LDA(dst, b, h) do { _Pragma("unroll") for (int m = 0; m < 4; ++m) _Pragma("unroll") for (int k = 0; k < 2; ++k) dst[m][k] = *(const PG8_LAS bf16x8*)(lds + PG8_SA(b, h) + aoff + m * 2048 + k * 1024); } while (0)
; #define PG8_LDB(dst, b, h) do { _Pragma("unroll") for (int n = 0; n < 2; ++n) _Pragma("unroll") for (int k = 0; k < 2; ++k) dst[n][k] = *(const PG8_LAS bf16x8*)(lds + PG8_SB(b, h) + boff + n * 2048 + k * 1024); } while (0)
; #define PG8_MMA(ai, bj, At, Bt) do { __builtin_amdgcn_s_setprio(1); _Pragma("unroll") for (int m = 0; m < 4; ++m) _Pragma("unroll") for (int n = 0; n < 2; ++n) _Pragma("unroll") for (int k = 0; k < 2; ++k) \
;         acc[ai][bj][m][n] = __builtin_amdgcn_mfma_f32_16x16x32_bf16(Bt[n][k], At[m][k], acc[ai][bj][m][n], 0, 0, 0); __builtin_amdgcn_s_setprio(0); } while (0)
; #define PG8_WAIT_V(n) asm volatile("s_waitcnt vmcnt(" #n ")" ::: "memory")
; #define PG8_WAIT_L(n) asm volatile("s_waitcnt lgkmcnt(" #n ")" ::: "memory")
; #define PG8_BAR __builtin_amdgcn_s_barrier()
; #define PG8_SCHED __builtin_amdgcn_sched_barrier(0)
;     ...
;             const bool last = (t == nt - 2);
;             const char* a1 = PG8_KADV(cA, (size_t)(t + 1) * kstep);
;             const char* a2 = last ? nA : PG8_KADV(cA, (size_t)(t + 2) * kstep); const char* b2 = last ? nB : PG8_KADV(cB, (size_t)(t + 2) * kstep);
;             const char* a3 = PG8_KADV(a2, kstep); const char* b3 = PG8_KADV(b2, kstep);
;             if (last && has_next) S.a_ready(nxt);
;             if constexpr (SP2) {
;             PG8_LDB(B0, 0, 0); PG8_LDB(B1, 0, 1); PG8_SCHED; PG8_LDA(At, 0, 0); PG8_STAGE(PG8_SA(1, 1), a1 + hstep, voffA);
;             PG8_WAIT_V(8); PG8_WAIT_L(0); PG8_BAR; PG8_MMA(0, 0, At, B0); PG8_MMA(0, 1, At, B1); PG8_BAR; PG8_SCHED;
;             PG8_LDA(At, 0, 1); PG8_STAGE(PG8_SB(0, 0), b2, voffB); PG8_STAGE(PG8_SB(0, 1), b2 + hstep, voffB); PG8_STAGE(PG8_SA(0, 0), a2, voffA);
;             PG8_WAIT_V(8); PG8_WAIT_L(0); PG8_BAR; PG8_MMA(1, 0, At, B0); PG8_MMA(1, 1, At, B1); PG8_BAR; PG8_SCHED;
.LBB0_313:
	s_add_u32 s78, s76, 0xffffff00
	s_addc_u32 s79, s77, -1
	s_add_i32 s12, 0, 0x10000
	s_cmpk_eq_i32 s3, 0x54
	s_cselect_b32 s83, s7, s79
	s_cselect_b32 s82, s6, s78
	s_cselect_b32 s81, s75, s30
	s_cselect_b32 s80, s74, s2
	s_add_i32 s13, 0, 0x14000
	v_add_u32_e32 v152, s12, v166
	v_add_u32_e32 v164, s13, v166
	ds_read_b128 v[128:131], v152
	ds_read_b128 v[132:135], v152 offset:1024
	ds_read_b128 v[148:151], v152 offset:2048
	ds_read_b128 v[152:155], v152 offset:3072
	ds_read_b128 v[156:159], v164
	ds_read_b128 v[160:163], v164 offset:1024
	ds_read_b128 v[170:173], v164 offset:2048
	ds_read_b128 v[178:181], v164 offset:3072
	s_add_i32 m0, s9, 0xc000
	ds_read_b128 v[184:187], v183
	ds_read_b128 v[188:191], v183 offset:1024
	ds_read_b128 v[192:195], v183 offset:2048
	ds_read_b128 v[196:199], v183 offset:3072
	ds_read_b128 v[200:203], v183 offset:4096
	ds_read_b128 v[204:207], v183 offset:5120
	ds_read_b128 v[208:211], v183 offset:6144
	ds_read_b128 v[212:215], v183 offset:7168
	global_load_lds_dwordx4 v144, s[76:77]
	s_add_i32 m0, s9, 0xe000
	s_nop 0
	global_load_lds_dwordx4 v146, s[76:77]
	s_waitcnt vmcnt(8)
	s_waitcnt lgkmcnt(0)
	s_setprio 1
	s_barrier
	v_mfma_f32_16x16x32_bf16 v[124:127], v[128:131], v[184:187], v[124:127]
	v_mfma_f32_16x16x32_bf16 v[124:127], v[132:135], v[188:191], v[124:127]
	v_mfma_f32_16x16x32_bf16 v[112:115], v[128:131], v[192:195], v[112:115]
	v_mfma_f32_16x16x32_bf16 v[112:115], v[132:135], v[196:199], v[112:115]
	v_mfma_f32_16x16x32_bf16 v[92:95], v[128:131], v[200:203], v[92:95]
	v_mfma_f32_16x16x32_bf16 v[92:95], v[132:135], v[204:207], v[92:95]
	v_mfma_f32_16x16x32_bf16 v[80:83], v[128:131], v[208:211], v[80:83]
	v_mfma_f32_16x16x32_bf16 v[80:83], v[132:135], v[212:215], v[80:83]
	v_mfma_f32_16x16x32_bf16 v[120:123], v[148:151], v[184:187], v[120:123]
	v_mfma_f32_16x16x32_bf16 v[120:123], v[152:155], v[188:191], v[120:123]
	v_mfma_f32_16x16x32_bf16 v[104:107], v[148:151], v[192:195], v[104:107]
	v_mfma_f32_16x16x32_bf16 v[104:107], v[152:155], v[196:199], v[104:107]
	v_mfma_f32_16x16x32_bf16 v[88:91], v[148:151], v[200:203], v[88:91]
	v_mfma_f32_16x16x32_bf16 v[88:91], v[152:155], v[204:207], v[88:91]
	v_mfma_f32_16x16x32_bf16 v[72:75], v[148:151], v[208:211], v[72:75]
	v_mfma_f32_16x16x32_bf16 v[72:75], v[152:155], v[212:215], v[72:75]
	v_mfma_f32_16x16x32_bf16 v[116:119], v[156:159], v[184:187], v[116:119]
	v_mfma_f32_16x16x32_bf16 v[116:119], v[160:163], v[188:191], v[116:119]
	v_mfma_f32_16x16x32_bf16 v[100:103], v[156:159], v[192:195], v[100:103]
	v_mfma_f32_16x16x32_bf16 v[100:103], v[160:163], v[196:199], v[100:103]
	v_mfma_f32_16x16x32_bf16 v[84:87], v[156:159], v[200:203], v[84:87]
	v_mfma_f32_16x16x32_bf16 v[84:87], v[160:163], v[204:207], v[84:87]
	v_mfma_f32_16x16x32_bf16 v[68:71], v[156:159], v[208:211], v[68:71]
	v_mfma_f32_16x16x32_bf16 v[68:71], v[160:163], v[212:215], v[68:71]
	v_mfma_f32_16x16x32_bf16 v[108:111], v[170:173], v[184:187], v[108:111]
	v_mfma_f32_16x16x32_bf16 v[108:111], v[178:181], v[188:191], v[108:111]
	v_mfma_f32_16x16x32_bf16 v[96:99], v[170:173], v[192:195], v[96:99]
	v_mfma_f32_16x16x32_bf16 v[96:99], v[178:181], v[196:199], v[96:99]
	v_mfma_f32_16x16x32_bf16 v[76:79], v[170:173], v[200:203], v[76:79]
	v_mfma_f32_16x16x32_bf16 v[76:79], v[178:181], v[204:207], v[76:79]
	v_mfma_f32_16x16x32_bf16 v[64:67], v[170:173], v[208:211], v[64:67]
	v_mfma_f32_16x16x32_bf16 v[64:67], v[178:181], v[212:215], v[64:67]
	s_barrier
	s_setprio 0
	s_add_i32 s12, s12, s8
	s_mov_b32 m0, s12
	ds_read_b128 v[184:187], v183 offset:16384
	ds_read_b128 v[188:191], v183 offset:17408
	ds_read_b128 v[192:195], v183 offset:18432
	ds_read_b128 v[196:199], v183 offset:19456
	ds_read_b128 v[200:203], v183 offset:20480
	ds_read_b128 v[204:207], v183 offset:21504
	ds_read_b128 v[208:211], v183 offset:22528
	ds_read_b128 v[212:215], v183 offset:23552
	global_load_lds_dwordx4 v138, s[80:81]
	s_add_i32 m0, s12, 0x2000
	s_add_u32 s42, s80, 0x160000
	s_addc_u32 s43, s81, 0
	s_add_i32 s12, s13, s8
	global_load_lds_dwordx4 v142, s[80:81]
	s_mov_b32 m0, s12
	s_nop 0
	global_load_lds_dwordx4 v138, s[42:43]
	s_add_i32 m0, s12, 0x2000
	s_nop 0
	global_load_lds_dwordx4 v142, s[42:43]
	s_mov_b32 m0, s9
	s_nop 0
	global_load_lds_dwordx4 v136, s[82:83]
	s_mov_b32 m0, s10
	s_nop 0
	global_load_lds_dwordx4 v140, s[82:83]
	s_waitcnt vmcnt(8)
	s_waitcnt lgkmcnt(0)
	s_setprio 1
	s_barrier
	v_mfma_f32_16x16x32_bf16 v[60:63], v[128:131], v[184:187], v[60:63]
	v_mfma_f32_16x16x32_bf16 v[60:63], v[132:135], v[188:191], v[60:63]
	v_mfma_f32_16x16x32_bf16 v[48:51], v[128:131], v[192:195], v[48:51]
	v_mfma_f32_16x16x32_bf16 v[48:51], v[132:135], v[196:199], v[48:51]
	v_mfma_f32_16x16x32_bf16 v[28:31], v[128:131], v[200:203], v[28:31]
	v_mfma_f32_16x16x32_bf16 v[28:31], v[132:135], v[204:207], v[28:31]
	v_mfma_f32_16x16x32_bf16 v[16:19], v[128:131], v[208:211], v[16:19]
	v_mfma_f32_16x16x32_bf16 v[16:19], v[132:135], v[212:215], v[16:19]
	v_mfma_f32_16x16x32_bf16 v[56:59], v[148:151], v[184:187], v[56:59]
	v_mfma_f32_16x16x32_bf16 v[56:59], v[152:155], v[188:191], v[56:59]
	v_mfma_f32_16x16x32_bf16 v[40:43], v[148:151], v[192:195], v[40:43]
	v_mfma_f32_16x16x32_bf16 v[40:43], v[152:155], v[196:199], v[40:43]
	v_mfma_f32_16x16x32_bf16 v[24:27], v[148:151], v[200:203], v[24:27]
	v_mfma_f32_16x16x32_bf16 v[24:27], v[152:155], v[204:207], v[24:27]
	v_mfma_f32_16x16x32_bf16 v[8:11], v[148:151], v[208:211], v[8:11]
	v_mfma_f32_16x16x32_bf16 v[8:11], v[152:155], v[212:215], v[8:11]
	v_mfma_f32_16x16x32_bf16 v[52:55], v[156:159], v[184:187], v[52:55]
	v_mfma_f32_16x16x32_bf16 v[52:55], v[160:163], v[188:191], v[52:55]
	v_mfma_f32_16x16x32_bf16 v[36:39], v[156:159], v[192:195], v[36:39]
	v_mfma_f32_16x16x32_bf16 v[36:39], v[160:163], v[196:199], v[36:39]
	v_mfma_f32_16x16x32_bf16 v[20:23], v[156:159], v[200:203], v[20:23]
	v_mfma_f32_16x16x32_bf16 v[20:23], v[160:163], v[204:207], v[20:23]
	v_mfma_f32_16x16x32_bf16 v[4:7], v[156:159], v[208:211], v[4:7]
	v_mfma_f32_16x16x32_bf16 v[4:7], v[160:163], v[212:215], v[4:7]
	v_mfma_f32_16x16x32_bf16 v[44:47], v[170:173], v[184:187], v[44:47]
	v_mfma_f32_16x16x32_bf16 v[44:47], v[178:181], v[188:191], v[44:47]
	v_mfma_f32_16x16x32_bf16 v[32:35], v[170:173], v[192:195], v[32:35]
	v_mfma_f32_16x16x32_bf16 v[32:35], v[178:181], v[196:199], v[32:35]
	v_mfma_f32_16x16x32_bf16 v[12:15], v[170:173], v[200:203], v[12:15]
	v_mfma_f32_16x16x32_bf16 v[12:15], v[178:181], v[204:207], v[12:15]
	v_mfma_f32_16x16x32_bf16 v[0:3], v[170:173], v[208:211], v[0:3]
	v_mfma_f32_16x16x32_bf16 v[0:3], v[178:181], v[212:215], v[0:3]
	s_barrier
; #define PG8_STAGE(bufoff, gbase, voff) do { _Pragma("unroll") for (int _i = 0; _i < 2; ++_i) \
;         __builtin_amdgcn_global_load_lds((const unsigned*)((const char*)(gbase) + (voff)[_i]), (PG8_LAS unsigned*)(lds + (bufoff) + ldsw + _i * 8192), 16, 0, 0); } while (0)
; #define PG8_LDA(dst, b, h) do { _Pragma("unroll") for (int m = 0; m < 4; ++m) _Pragma("unroll") for (int k = 0; k < 2; ++k) dst[m][k] = *(const PG8_LAS bf16x8*)(lds + PG8_SA(b, h) + aoff + m * 2048 + k * 1024); } while (0)
; #define PG8_LDB(dst, b, h) do { _Pragma("unroll") for (int n = 0; n < 2; ++n) _Pragma("unroll") for (int k = 0; k < 2; ++k) dst[n][k] = *(const PG8_LAS bf16x8*)(lds + PG8_SB(b, h) + boff + n * 2048 + k * 1024); } while (0)
; #define PG8_MMA(ai, bj, At, Bt) do { __builtin_amdgcn_s_setprio(1); _Pragma("unroll") for (int m = 0; m < 4; ++m) _Pragma("unroll") for (int n = 0; n < 2; ++n) _Pragma("unroll") for (int k = 0; k < 2; ++k) \
;         acc[ai][bj][m][n] = __builtin_amdgcn_mfma_f32_16x16x32_bf16(Bt[n][k], At[m][k], acc[ai][bj][m][n], 0, 0, 0); __builtin_amdgcn_s_setprio(0); } while (0)
; #define PG8_WAIT_V(n) asm volatile("s_waitcnt vmcnt(" #n ")" ::: "memory")
; #define PG8_WAIT_L(n) asm volatile("s_waitcnt lgkmcnt(" #n ")" ::: "memory")
; #define PG8_BAR __builtin_amdgcn_s_barrier()
; #define PG8_SCHED __builtin_amdgcn_sched_barrier(0)
;     ...
;             PG8_LDB(B0, 1, 0); PG8_LDB(B1, 1, 1); PG8_SCHED; PG8_LDA(At, 1, 0); PG8_STAGE(PG8_SA(0, 1), a2 + hstep, voffA);
;             PG8_WAIT_V(8); PG8_WAIT_L(0); PG8_BAR; PG8_MMA(0, 0, At, B0); PG8_MMA(0, 1, At, B1); PG8_BAR; PG8_SCHED;
;             PG8_LDA(At, 1, 1); PG8_STAGE(PG8_SB(1, 0), b3, voffB); PG8_STAGE(PG8_SB(1, 1), b3 + hstep, voffB); PG8_STAGE(PG8_SA(1, 0), a3, voffA);
;             PG8_WAIT_V(8); PG8_WAIT_L(0); PG8_BAR; PG8_MMA(1, 0, At, B0); PG8_MMA(1, 1, At, B1); PG8_BAR; PG8_SCHED;
	s_setprio 0
	s_add_i32 s12, 0, 0x18000
	s_add_i32 s13, 0, 0x1c000
	v_add_u32_e32 v152, s12, v166
	v_add_u32_e32 v168, s13, v166
	ds_read_b128 v[128:131], v152
	ds_read_b128 v[132:135], v152 offset:1024
	ds_read_b128 v[148:151], v152 offset:2048
	ds_read_b128 v[152:155], v152 offset:3072
	ds_read_b128 v[156:159], v168
	ds_read_b128 v[160:163], v168 offset:1024
	ds_read_b128 v[170:173], v168 offset:2048
	ds_read_b128 v[178:181], v168 offset:3072
	s_add_u32 s42, s82, 0x160000
	s_addc_u32 s43, s83, 0
	s_mov_b32 m0, s18
	ds_read_b128 v[184:187], v183 offset:32768
	ds_read_b128 v[188:191], v183 offset:33792
	ds_read_b128 v[192:195], v183 offset:34816
	ds_read_b128 v[196:199], v183 offset:35840
	ds_read_b128 v[200:203], v183 offset:36864
	ds_read_b128 v[204:207], v183 offset:37888
	ds_read_b128 v[208:211], v183 offset:38912
	ds_read_b128 v[212:215], v183 offset:39936
	global_load_lds_dwordx4 v136, s[42:43]
	s_mov_b32 m0, s19
	s_nop 0
	global_load_lds_dwordx4 v140, s[42:43]
	s_waitcnt vmcnt(8)
	s_waitcnt lgkmcnt(0)
	s_setprio 1
	s_barrier
	v_mfma_f32_16x16x32_bf16 v[124:127], v[128:131], v[184:187], v[124:127]
	v_mfma_f32_16x16x32_bf16 v[124:127], v[132:135], v[188:191], v[124:127]
	v_mfma_f32_16x16x32_bf16 v[112:115], v[128:131], v[192:195], v[112:115]
	v_mfma_f32_16x16x32_bf16 v[112:115], v[132:135], v[196:199], v[112:115]
	v_mfma_f32_16x16x32_bf16 v[92:95], v[128:131], v[200:203], v[92:95]
	v_mfma_f32_16x16x32_bf16 v[92:95], v[132:135], v[204:207], v[92:95]
	v_mfma_f32_16x16x32_bf16 v[80:83], v[128:131], v[208:211], v[80:83]
	v_mfma_f32_16x16x32_bf16 v[80:83], v[132:135], v[212:215], v[80:83]
	v_mfma_f32_16x16x32_bf16 v[120:123], v[148:151], v[184:187], v[120:123]
	v_mfma_f32_16x16x32_bf16 v[120:123], v[152:155], v[188:191], v[120:123]
	v_mfma_f32_16x16x32_bf16 v[104:107], v[148:151], v[192:195], v[104:107]
	v_mfma_f32_16x16x32_bf16 v[104:107], v[152:155], v[196:199], v[104:107]
	v_mfma_f32_16x16x32_bf16 v[88:91], v[148:151], v[200:203], v[88:91]
	v_mfma_f32_16x16x32_bf16 v[88:91], v[152:155], v[204:207], v[88:91]
	v_mfma_f32_16x16x32_bf16 v[72:75], v[148:151], v[208:211], v[72:75]
	v_mfma_f32_16x16x32_bf16 v[72:75], v[152:155], v[212:215], v[72:75]
	v_mfma_f32_16x16x32_bf16 v[116:119], v[156:159], v[184:187], v[116:119]
	v_mfma_f32_16x16x32_bf16 v[116:119], v[160:163], v[188:191], v[116:119]
	v_mfma_f32_16x16x32_bf16 v[100:103], v[156:159], v[192:195], v[100:103]
	v_mfma_f32_16x16x32_bf16 v[100:103], v[160:163], v[196:199], v[100:103]
	v_mfma_f32_16x16x32_bf16 v[84:87], v[156:159], v[200:203], v[84:87]
	v_mfma_f32_16x16x32_bf16 v[84:87], v[160:163], v[204:207], v[84:87]
	v_mfma_f32_16x16x32_bf16 v[68:71], v[156:159], v[208:211], v[68:71]
	v_mfma_f32_16x16x32_bf16 v[68:71], v[160:163], v[212:215], v[68:71]
	v_mfma_f32_16x16x32_bf16 v[108:111], v[170:173], v[184:187], v[108:111]
	v_mfma_f32_16x16x32_bf16 v[108:111], v[178:181], v[188:191], v[108:111]
	v_mfma_f32_16x16x32_bf16 v[96:99], v[170:173], v[192:195], v[96:99]
	v_mfma_f32_16x16x32_bf16 v[96:99], v[178:181], v[196:199], v[96:99]
	v_mfma_f32_16x16x32_bf16 v[76:79], v[170:173], v[200:203], v[76:79]
	v_mfma_f32_16x16x32_bf16 v[76:79], v[178:181], v[204:207], v[76:79]
	v_mfma_f32_16x16x32_bf16 v[64:67], v[170:173], v[208:211], v[64:67]
	v_mfma_f32_16x16x32_bf16 v[64:67], v[178:181], v[212:215], v[64:67]
	s_barrier
	s_setprio 0
	s_add_i32 s12, s12, s8
	s_mov_b32 m0, s12
	ds_read_b128 v[184:187], v183 offset:49152
	ds_read_b128 v[188:191], v183 offset:50176
	ds_read_b128 v[192:195], v183 offset:51200
	ds_read_b128 v[196:199], v183 offset:52224
	ds_read_b128 v[200:203], v183 offset:53248
	ds_read_b128 v[204:207], v183 offset:54272
	ds_read_b128 v[208:211], v183 offset:55296
	ds_read_b128 v[212:215], v183 offset:56320
	s_add_u32 s100, s80, s38
	s_addc_u32 s101, s81, s39
	global_load_lds_dwordx4 v138, s[100:101]
	s_add_i32 m0, s12, 0x2000
	s_add_u32 s42, s80, 0x15ff80
	s_addc_u32 s43, s81, 0
	s_add_i32 s12, s13, s8
	global_load_lds_dwordx4 v142, s[100:101]
	s_mov_b32 m0, s12
	s_nop 0
	global_load_lds_dwordx4 v138, s[42:43]
	s_add_i32 m0, s12, 0x2000
	s_nop 0
	global_load_lds_dwordx4 v142, s[42:43]
	s_mov_b32 m0, s20
	s_nop 0
	s_add_u32 s100, s82, s38
	s_addc_u32 s101, s83, s39
	global_load_lds_dwordx4 v136, s[100:101]
	s_mov_b32 m0, s21
	s_nop 0
	global_load_lds_dwordx4 v140, s[100:101]
	s_waitcnt vmcnt(8)
	s_waitcnt lgkmcnt(0)
	s_setprio 1
	s_barrier
	v_mfma_f32_16x16x32_bf16 v[60:63], v[128:131], v[184:187], v[60:63]
	v_mfma_f32_16x16x32_bf16 v[60:63], v[132:135], v[188:191], v[60:63]
	v_mfma_f32_16x16x32_bf16 v[48:51], v[128:131], v[192:195], v[48:51]
	v_mfma_f32_16x16x32_bf16 v[48:51], v[132:135], v[196:199], v[48:51]
	v_mfma_f32_16x16x32_bf16 v[28:31], v[128:131], v[200:203], v[28:31]
	v_mfma_f32_16x16x32_bf16 v[28:31], v[132:135], v[204:207], v[28:31]
	v_mfma_f32_16x16x32_bf16 v[16:19], v[128:131], v[208:211], v[16:19]
	v_mfma_f32_16x16x32_bf16 v[16:19], v[132:135], v[212:215], v[16:19]
	v_mfma_f32_16x16x32_bf16 v[56:59], v[148:151], v[184:187], v[56:59]
	v_mfma_f32_16x16x32_bf16 v[56:59], v[152:155], v[188:191], v[56:59]
	v_mfma_f32_16x16x32_bf16 v[40:43], v[148:151], v[192:195], v[40:43]
	v_mfma_f32_16x16x32_bf16 v[40:43], v[152:155], v[196:199], v[40:43]
	v_mfma_f32_16x16x32_bf16 v[24:27], v[148:151], v[200:203], v[24:27]
	v_mfma_f32_16x16x32_bf16 v[24:27], v[152:155], v[204:207], v[24:27]
	v_mfma_f32_16x16x32_bf16 v[8:11], v[148:151], v[208:211], v[8:11]
	v_mfma_f32_16x16x32_bf16 v[8:11], v[152:155], v[212:215], v[8:11]
	v_mfma_f32_16x16x32_bf16 v[52:55], v[156:159], v[184:187], v[52:55]
	v_mfma_f32_16x16x32_bf16 v[52:55], v[160:163], v[188:191], v[52:55]
	v_mfma_f32_16x16x32_bf16 v[36:39], v[156:159], v[192:195], v[36:39]
	v_mfma_f32_16x16x32_bf16 v[36:39], v[160:163], v[196:199], v[36:39]
	v_mfma_f32_16x16x32_bf16 v[20:23], v[156:159], v[200:203], v[20:23]
	v_mfma_f32_16x16x32_bf16 v[20:23], v[160:163], v[204:207], v[20:23]
	v_mfma_f32_16x16x32_bf16 v[4:7], v[156:159], v[208:211], v[4:7]
	v_mfma_f32_16x16x32_bf16 v[4:7], v[160:163], v[212:215], v[4:7]
	v_mfma_f32_16x16x32_bf16 v[44:47], v[170:173], v[184:187], v[44:47]
	v_mfma_f32_16x16x32_bf16 v[44:47], v[178:181], v[188:191], v[44:47]
	v_mfma_f32_16x16x32_bf16 v[32:35], v[170:173], v[192:195], v[32:35]
	v_mfma_f32_16x16x32_bf16 v[32:35], v[178:181], v[196:199], v[32:35]
	v_mfma_f32_16x16x32_bf16 v[12:15], v[170:173], v[200:203], v[12:15]
	v_mfma_f32_16x16x32_bf16 v[12:15], v[178:181], v[204:207], v[12:15]
	v_mfma_f32_16x16x32_bf16 v[0:3], v[170:173], v[208:211], v[0:3]
	v_mfma_f32_16x16x32_bf16 v[0:3], v[178:181], v[212:215], v[0:3]
	s_barrier
	s_setprio 0
	s_add_i32 s3, s3, 2
	s_add_u32 s2, s2, 0xffffff00
	s_addc_u32 s30, s30, -1
	s_cmpk_gt_u32 s3, 0x55
	s_mov_b64 s[76:77], s[78:79]
	s_cbranch_scc0 .LBB0_313
	s_and_b64 vcc, exec, s[72:73]
	s_cbranch_vccz .LBB0_316
	s_barrier

; #define PG8_STAGE(bufoff, gbase, voff) do { _Pragma("unroll") for (int _i = 0; _i < 2; ++_i) \
;         __builtin_amdgcn_global_load_lds((const unsigned*)((const char*)(gbase) + (voff)[_i]), (PG8_LAS unsigned*)(lds + (bufoff) + ldsw + _i * 8192), 16, 0, 0); } while (0)
; #define PG8_LDA(dst, b, h) do { _Pragma("unroll") for (int m = 0; m < 4; ++m) _Pragma("unroll") for (int k = 0; k < 2; ++k) dst[m][k] = *(const PG8_LAS bf16x8*)(lds + PG8_SA(b, h) + aoff + m * 2048 + k * 1024); } while (0)
; #define PG8_LDB(dst, b, h) do { _Pragma("unroll") for (int n = 0; n < 2; ++n) _Pragma("unroll") for (int k = 0; k < 2; ++k) dst[n][k] = *(const PG8_LAS bf16x8*)(lds + PG8_SB(b, h) + boff + n * 2048 + k * 1024); } while (0)
; #define PG8_MMA(ai, bj, At, Bt) do { __builtin_amdgcn_s_setprio(1); _Pragma("unroll") for (int m = 0; m < 4; ++m) _Pragma("unroll") for (int n = 0; n < 2; ++n) _Pragma("unroll") for (int k = 0; k < 2; ++k) \
;         acc[ai][bj][m][n] = __builtin_amdgcn_mfma_f32_16x16x32_bf16(Bt[n][k], At[m][k], acc[ai][bj][m][n], 0, 0, 0); __builtin_amdgcn_s_setprio(0); } while (0)
; #define PG8_WAIT_V(n) asm volatile("s_waitcnt vmcnt(" #n ")" ::: "memory")
; #define PG8_WAIT_L(n) asm volatile("s_waitcnt lgkmcnt(" #n ")" ::: "memory")
; #define PG8_BAR __builtin_amdgcn_s_barrier()
; #define PG8_SCHED __builtin_amdgcn_sched_barrier(0)
;     ...
;             const bool last = (t == nt - 2);
;             const char* a1 = PG8_KADV(cA, (size_t)(t + 1) * kstep);
;             const char* a2 = last ? nA : PG8_KADV(cA, (size_t)(t + 2) * kstep); const char* b2 = last ? nB : PG8_KADV(cB, (size_t)(t + 2) * kstep);
;             const char* a3 = PG8_KADV(a2, kstep); const char* b3 = PG8_KADV(b2, kstep);
;             if (last && has_next) S.a_ready(nxt);
;             if constexpr (SP2) {
;             PG8_LDB(B0, 0, 0); PG8_LDB(B1, 0, 1); PG8_SCHED; PG8_LDA(At, 0, 0); PG8_STAGE(PG8_SA(1, 1), a1 + hstep, voffA);
;             PG8_WAIT_V(8); PG8_WAIT_L(0); PG8_BAR; PG8_MMA(0, 0, At, B0); PG8_MMA(0, 1, At, B1); PG8_BAR; PG8_SCHED;
;             PG8_LDA(At, 0, 1); PG8_STAGE(PG8_SB(0, 0), b2, voffB); PG8_STAGE(PG8_SB(0, 1), b2 + hstep, voffB); PG8_STAGE(PG8_SA(0, 0), a2, voffA);
;             PG8_WAIT_V(8); PG8_WAIT_L(0); PG8_BAR; PG8_MMA(1, 0, At, B0); PG8_MMA(1, 1, At, B1); PG8_BAR; PG8_SCHED;
.LBB0_343:
	s_add_u32 s78, s76, 0xffffff00
	s_addc_u32 s79, s77, -1
	s_add_i32 s12, 0, 0x10000
	s_cmpk_eq_i32 s3, 0x54
	s_cselect_b32 s83, s7, s79
	s_cselect_b32 s82, s6, s78
	s_cselect_b32 s81, s75, s30
	s_cselect_b32 s80, s74, s2
	s_add_i32 s13, 0, 0x14000
	v_add_u32_e32 v140, s12, v233
	v_add_u32_e32 v156, s13, v233
	ds_read_b128 v[128:131], v140
	ds_read_b128 v[132:135], v140 offset:1024
	ds_read_b128 v[136:139], v140 offset:2048
	ds_read_b128 v[140:143], v140 offset:3072
	ds_read_b128 v[144:147], v156
	ds_read_b128 v[148:151], v156 offset:1024
	ds_read_b128 v[152:155], v156 offset:2048
	ds_read_b128 v[156:159], v156 offset:3072
	s_add_i32 m0, s9, 0xc000
	ds_read_b128 v[160:163], v236
	ds_read_b128 v[164:167], v236 offset:1024
	ds_read_b128 v[194:197], v236 offset:2048
	ds_read_b128 v[198:201], v236 offset:3072
	ds_read_b128 v[202:205], v236 offset:4096
	ds_read_b128 v[206:209], v236 offset:5120
	ds_read_b128 v[210:213], v236 offset:6144
	ds_read_b128 v[214:217], v236 offset:7168
	global_load_lds_dwordx4 v190, s[76:77]
	s_add_i32 m0, s9, 0xe000
	s_nop 0
	global_load_lds_dwordx4 v192, s[76:77]
	s_waitcnt vmcnt(8)
	s_waitcnt lgkmcnt(0)
	s_setprio 1
	s_barrier
	v_mfma_f32_16x16x32_bf16 v[124:127], v[128:131], v[160:163], v[124:127]
	v_mfma_f32_16x16x32_bf16 v[124:127], v[132:135], v[164:167], v[124:127]
	v_mfma_f32_16x16x32_bf16 v[108:111], v[128:131], v[194:197], v[108:111]
	v_mfma_f32_16x16x32_bf16 v[108:111], v[132:135], v[198:201], v[108:111]
	v_mfma_f32_16x16x32_bf16 v[100:103], v[128:131], v[202:205], v[100:103]
	v_mfma_f32_16x16x32_bf16 v[100:103], v[132:135], v[206:209], v[100:103]
	v_mfma_f32_16x16x32_bf16 v[84:87], v[128:131], v[210:213], v[84:87]
	v_mfma_f32_16x16x32_bf16 v[84:87], v[132:135], v[214:217], v[84:87]
	v_mfma_f32_16x16x32_bf16 v[120:123], v[136:139], v[160:163], v[120:123]
	v_mfma_f32_16x16x32_bf16 v[120:123], v[140:143], v[164:167], v[120:123]
	v_mfma_f32_16x16x32_bf16 v[104:107], v[136:139], v[194:197], v[104:107]
	v_mfma_f32_16x16x32_bf16 v[104:107], v[140:143], v[198:201], v[104:107]
	v_mfma_f32_16x16x32_bf16 v[92:95], v[136:139], v[202:205], v[92:95]
	v_mfma_f32_16x16x32_bf16 v[92:95], v[140:143], v[206:209], v[92:95]
	v_mfma_f32_16x16x32_bf16 v[76:79], v[136:139], v[210:213], v[76:79]
	v_mfma_f32_16x16x32_bf16 v[76:79], v[140:143], v[214:217], v[76:79]
	v_mfma_f32_16x16x32_bf16 v[116:119], v[144:147], v[160:163], v[116:119]
	v_mfma_f32_16x16x32_bf16 v[116:119], v[148:151], v[164:167], v[116:119]
	v_mfma_f32_16x16x32_bf16 v[96:99], v[144:147], v[194:197], v[96:99]
	v_mfma_f32_16x16x32_bf16 v[96:99], v[148:151], v[198:201], v[96:99]
	v_mfma_f32_16x16x32_bf16 v[80:83], v[144:147], v[202:205], v[80:83]
	v_mfma_f32_16x16x32_bf16 v[80:83], v[148:151], v[206:209], v[80:83]
	v_mfma_f32_16x16x32_bf16 v[68:71], v[144:147], v[210:213], v[68:71]
	v_mfma_f32_16x16x32_bf16 v[68:71], v[148:151], v[214:217], v[68:71]
	v_mfma_f32_16x16x32_bf16 v[112:115], v[152:155], v[160:163], v[112:115]
	v_mfma_f32_16x16x32_bf16 v[112:115], v[156:159], v[164:167], v[112:115]
	v_mfma_f32_16x16x32_bf16 v[88:91], v[152:155], v[194:197], v[88:91]
	v_mfma_f32_16x16x32_bf16 v[88:91], v[156:159], v[198:201], v[88:91]
	v_mfma_f32_16x16x32_bf16 v[72:75], v[152:155], v[202:205], v[72:75]
	v_mfma_f32_16x16x32_bf16 v[72:75], v[156:159], v[206:209], v[72:75]
	v_mfma_f32_16x16x32_bf16 v[64:67], v[152:155], v[210:213], v[64:67]
	v_mfma_f32_16x16x32_bf16 v[64:67], v[156:159], v[214:217], v[64:67]
	s_barrier
	s_setprio 0
	s_add_i32 s12, s12, s8
	s_mov_b32 m0, s12
	ds_read_b128 v[160:163], v236 offset:16384
	ds_read_b128 v[164:167], v236 offset:17408
	ds_read_b128 v[194:197], v236 offset:18432
	ds_read_b128 v[198:201], v236 offset:19456
	ds_read_b128 v[202:205], v236 offset:20480
	ds_read_b128 v[206:209], v236 offset:21504
	ds_read_b128 v[210:213], v236 offset:22528
	ds_read_b128 v[214:217], v236 offset:23552
	global_load_lds_dwordx4 v184, s[80:81]
	s_add_i32 m0, s12, 0x2000
	s_add_u32 s42, s80, 0x160000
	s_addc_u32 s43, s81, 0
	s_add_i32 s12, s13, s8
	global_load_lds_dwordx4 v188, s[80:81]
	s_mov_b32 m0, s12
	s_nop 0
	global_load_lds_dwordx4 v184, s[42:43]
	s_add_i32 m0, s12, 0x2000
	s_nop 0
	global_load_lds_dwordx4 v188, s[42:43]
	s_mov_b32 m0, s9
	s_nop 0
	global_load_lds_dwordx4 v182, s[82:83]
	s_mov_b32 m0, s10
	s_nop 0
	global_load_lds_dwordx4 v186, s[82:83]
	s_waitcnt vmcnt(8)
	s_waitcnt lgkmcnt(0)
	s_setprio 1
	s_barrier
	v_mfma_f32_16x16x32_bf16 v[60:63], v[128:131], v[160:163], v[60:63]
	v_mfma_f32_16x16x32_bf16 v[60:63], v[132:135], v[164:167], v[60:63]
	v_mfma_f32_16x16x32_bf16 v[52:55], v[128:131], v[194:197], v[52:55]
	v_mfma_f32_16x16x32_bf16 v[52:55], v[132:135], v[198:201], v[52:55]
	v_mfma_f32_16x16x32_bf16 v[36:39], v[128:131], v[202:205], v[36:39]
	v_mfma_f32_16x16x32_bf16 v[36:39], v[132:135], v[206:209], v[36:39]
	v_mfma_f32_16x16x32_bf16 v[20:23], v[128:131], v[210:213], v[20:23]
	v_mfma_f32_16x16x32_bf16 v[20:23], v[132:135], v[214:217], v[20:23]
	v_mfma_f32_16x16x32_bf16 v[56:59], v[136:139], v[160:163], v[56:59]
	v_mfma_f32_16x16x32_bf16 v[56:59], v[140:143], v[164:167], v[56:59]
	v_mfma_f32_16x16x32_bf16 v[44:47], v[136:139], v[194:197], v[44:47]
	v_mfma_f32_16x16x32_bf16 v[44:47], v[140:143], v[198:201], v[44:47]
	v_mfma_f32_16x16x32_bf16 v[28:31], v[136:139], v[202:205], v[28:31]
	v_mfma_f32_16x16x32_bf16 v[28:31], v[140:143], v[206:209], v[28:31]
	v_mfma_f32_16x16x32_bf16 v[12:15], v[136:139], v[210:213], v[12:15]
	v_mfma_f32_16x16x32_bf16 v[12:15], v[140:143], v[214:217], v[12:15]
	v_mfma_f32_16x16x32_bf16 v[48:51], v[144:147], v[160:163], v[48:51]
	v_mfma_f32_16x16x32_bf16 v[48:51], v[148:151], v[164:167], v[48:51]
	v_mfma_f32_16x16x32_bf16 v[32:35], v[144:147], v[194:197], v[32:35]
	v_mfma_f32_16x16x32_bf16 v[32:35], v[148:151], v[198:201], v[32:35]
	v_mfma_f32_16x16x32_bf16 v[16:19], v[144:147], v[202:205], v[16:19]
	v_mfma_f32_16x16x32_bf16 v[16:19], v[148:151], v[206:209], v[16:19]
	v_mfma_f32_16x16x32_bf16 v[4:7], v[144:147], v[210:213], v[4:7]
	v_mfma_f32_16x16x32_bf16 v[4:7], v[148:151], v[214:217], v[4:7]
	v_mfma_f32_16x16x32_bf16 v[40:43], v[152:155], v[160:163], v[40:43]
	v_mfma_f32_16x16x32_bf16 v[40:43], v[156:159], v[164:167], v[40:43]
	v_mfma_f32_16x16x32_bf16 v[24:27], v[152:155], v[194:197], v[24:27]
	v_mfma_f32_16x16x32_bf16 v[24:27], v[156:159], v[198:201], v[24:27]
	v_mfma_f32_16x16x32_bf16 v[8:11], v[152:155], v[202:205], v[8:11]
	v_mfma_f32_16x16x32_bf16 v[8:11], v[156:159], v[206:209], v[8:11]
	v_mfma_f32_16x16x32_bf16 v[0:3], v[152:155], v[210:213], v[0:3]
	v_mfma_f32_16x16x32_bf16 v[0:3], v[156:159], v[214:217], v[0:3]
	s_barrier
; #define PG8_STAGE(bufoff, gbase, voff) do { _Pragma("unroll") for (int _i = 0; _i < 2; ++_i) \
;         __builtin_amdgcn_global_load_lds((const unsigned*)((const char*)(gbase) + (voff)[_i]), (PG8_LAS unsigned*)(lds + (bufoff) + ldsw + _i * 8192), 16, 0, 0); } while (0)
; #define PG8_LDA(dst, b, h) do { _Pragma("unroll") for (int m = 0; m < 4; ++m) _Pragma("unroll") for (int k = 0; k < 2; ++k) dst[m][k] = *(const PG8_LAS bf16x8*)(lds + PG8_SA(b, h) + aoff + m * 2048 + k * 1024); } while (0)
; #define PG8_LDB(dst, b, h) do { _Pragma("unroll") for (int n = 0; n < 2; ++n) _Pragma("unroll") for (int k = 0; k < 2; ++k) dst[n][k] = *(const PG8_LAS bf16x8*)(lds + PG8_SB(b, h) + boff + n * 2048 + k * 1024); } while (0)
; #define PG8_MMA(ai, bj, At, Bt) do { __builtin_amdgcn_s_setprio(1); _Pragma("unroll") for (int m = 0; m < 4; ++m) _Pragma("unroll") for (int n = 0; n < 2; ++n) _Pragma("unroll") for (int k = 0; k < 2; ++k) \
;         acc[ai][bj][m][n] = __builtin_amdgcn_mfma_f32_16x16x32_bf16(Bt[n][k], At[m][k], acc[ai][bj][m][n], 0, 0, 0); __builtin_amdgcn_s_setprio(0); } while (0)
; #define PG8_WAIT_V(n) asm volatile("s_waitcnt vmcnt(" #n ")" ::: "memory")
; #define PG8_WAIT_L(n) asm volatile("s_waitcnt lgkmcnt(" #n ")" ::: "memory")
; #define PG8_BAR __builtin_amdgcn_s_barrier()
; #define PG8_SCHED __builtin_amdgcn_sched_barrier(0)
;     ...
;             PG8_LDB(B0, 1, 0); PG8_LDB(B1, 1, 1); PG8_SCHED; PG8_LDA(At, 1, 0); PG8_STAGE(PG8_SA(0, 1), a2 + hstep, voffA);
;             PG8_WAIT_V(8); PG8_WAIT_L(0); PG8_BAR; PG8_MMA(0, 0, At, B0); PG8_MMA(0, 1, At, B1); PG8_BAR; PG8_SCHED;
;             PG8_LDA(At, 1, 1); PG8_STAGE(PG8_SB(1, 0), b3, voffB); PG8_STAGE(PG8_SB(1, 1), b3 + hstep, voffB); PG8_STAGE(PG8_SA(1, 0), a3, voffA);
;             PG8_WAIT_V(8); PG8_WAIT_L(0); PG8_BAR; PG8_MMA(1, 0, At, B0); PG8_MMA(1, 1, At, B1); PG8_BAR; PG8_SCHED;
	s_setprio 0
	s_add_i32 s12, 0, 0x18000
	s_add_i32 s13, 0, 0x1c000
	v_add_u32_e32 v140, s12, v233
	v_add_u32_e32 v156, s13, v233
	ds_read_b128 v[128:131], v140
	ds_read_b128 v[132:135], v140 offset:1024
	ds_read_b128 v[136:139], v140 offset:2048
	ds_read_b128 v[140:143], v140 offset:3072
	ds_read_b128 v[144:147], v156
	ds_read_b128 v[148:151], v156 offset:1024
	ds_read_b128 v[152:155], v156 offset:2048
	ds_read_b128 v[156:159], v156 offset:3072
	s_add_u32 s42, s82, 0x160000
	s_addc_u32 s43, s83, 0
	s_mov_b32 m0, s18
	ds_read_b128 v[160:163], v236 offset:32768
	ds_read_b128 v[164:167], v236 offset:33792
	ds_read_b128 v[194:197], v236 offset:34816
	ds_read_b128 v[198:201], v236 offset:35840
	ds_read_b128 v[202:205], v236 offset:36864
	ds_read_b128 v[206:209], v236 offset:37888
	ds_read_b128 v[210:213], v236 offset:38912
	ds_read_b128 v[214:217], v236 offset:39936
	global_load_lds_dwordx4 v182, s[42:43]
	s_mov_b32 m0, s19
	s_nop 0
	global_load_lds_dwordx4 v186, s[42:43]
	s_waitcnt vmcnt(8)
	s_waitcnt lgkmcnt(0)
	s_setprio 1
	s_barrier
	v_mfma_f32_16x16x32_bf16 v[124:127], v[128:131], v[160:163], v[124:127]
	v_mfma_f32_16x16x32_bf16 v[124:127], v[132:135], v[164:167], v[124:127]
	v_mfma_f32_16x16x32_bf16 v[108:111], v[128:131], v[194:197], v[108:111]
	v_mfma_f32_16x16x32_bf16 v[108:111], v[132:135], v[198:201], v[108:111]
	v_mfma_f32_16x16x32_bf16 v[100:103], v[128:131], v[202:205], v[100:103]
	v_mfma_f32_16x16x32_bf16 v[100:103], v[132:135], v[206:209], v[100:103]
	v_mfma_f32_16x16x32_bf16 v[84:87], v[128:131], v[210:213], v[84:87]
	v_mfma_f32_16x16x32_bf16 v[84:87], v[132:135], v[214:217], v[84:87]
	v_mfma_f32_16x16x32_bf16 v[120:123], v[136:139], v[160:163], v[120:123]
	v_mfma_f32_16x16x32_bf16 v[120:123], v[140:143], v[164:167], v[120:123]
	v_mfma_f32_16x16x32_bf16 v[104:107], v[136:139], v[194:197], v[104:107]
	v_mfma_f32_16x16x32_bf16 v[104:107], v[140:143], v[198:201], v[104:107]
	v_mfma_f32_16x16x32_bf16 v[92:95], v[136:139], v[202:205], v[92:95]
	v_mfma_f32_16x16x32_bf16 v[92:95], v[140:143], v[206:209], v[92:95]
	v_mfma_f32_16x16x32_bf16 v[76:79], v[136:139], v[210:213], v[76:79]
	v_mfma_f32_16x16x32_bf16 v[76:79], v[140:143], v[214:217], v[76:79]
	v_mfma_f32_16x16x32_bf16 v[116:119], v[144:147], v[160:163], v[116:119]
	v_mfma_f32_16x16x32_bf16 v[116:119], v[148:151], v[164:167], v[116:119]
	v_mfma_f32_16x16x32_bf16 v[96:99], v[144:147], v[194:197], v[96:99]
	v_mfma_f32_16x16x32_bf16 v[96:99], v[148:151], v[198:201], v[96:99]
	v_mfma_f32_16x16x32_bf16 v[80:83], v[144:147], v[202:205], v[80:83]
	v_mfma_f32_16x16x32_bf16 v[80:83], v[148:151], v[206:209], v[80:83]
	v_mfma_f32_16x16x32_bf16 v[68:71], v[144:147], v[210:213], v[68:71]
	v_mfma_f32_16x16x32_bf16 v[68:71], v[148:151], v[214:217], v[68:71]
	v_mfma_f32_16x16x32_bf16 v[112:115], v[152:155], v[160:163], v[112:115]
	v_mfma_f32_16x16x32_bf16 v[112:115], v[156:159], v[164:167], v[112:115]
	v_mfma_f32_16x16x32_bf16 v[88:91], v[152:155], v[194:197], v[88:91]
	v_mfma_f32_16x16x32_bf16 v[88:91], v[156:159], v[198:201], v[88:91]
	v_mfma_f32_16x16x32_bf16 v[72:75], v[152:155], v[202:205], v[72:75]
	v_mfma_f32_16x16x32_bf16 v[72:75], v[156:159], v[206:209], v[72:75]
	v_mfma_f32_16x16x32_bf16 v[64:67], v[152:155], v[210:213], v[64:67]
	v_mfma_f32_16x16x32_bf16 v[64:67], v[156:159], v[214:217], v[64:67]
	s_barrier
	s_setprio 0
	s_add_i32 s12, s12, s8
	s_mov_b32 m0, s12
	ds_read_b128 v[160:163], v236 offset:49152
	ds_read_b128 v[164:167], v236 offset:50176
	ds_read_b128 v[194:197], v236 offset:51200
	ds_read_b128 v[198:201], v236 offset:52224
	ds_read_b128 v[202:205], v236 offset:53248
	ds_read_b128 v[206:209], v236 offset:54272
	ds_read_b128 v[210:213], v236 offset:55296
	ds_read_b128 v[214:217], v236 offset:56320
	s_add_u32 s100, s80, s38
	s_addc_u32 s101, s81, s39
	global_load_lds_dwordx4 v184, s[100:101]
	s_add_i32 m0, s12, 0x2000
	s_add_u32 s42, s80, 0x15ff80
	s_addc_u32 s43, s81, 0
	s_add_i32 s12, s13, s8
	global_load_lds_dwordx4 v188, s[100:101]
	s_mov_b32 m0, s12
	s_nop 0
	global_load_lds_dwordx4 v184, s[42:43]
	s_add_i32 m0, s12, 0x2000
	s_nop 0
	global_load_lds_dwordx4 v188, s[42:43]
	s_mov_b32 m0, s20
	s_nop 0
	s_add_u32 s100, s82, s38
	s_addc_u32 s101, s83, s39
	global_load_lds_dwordx4 v182, s[100:101]
	s_mov_b32 m0, s21
	s_nop 0
	global_load_lds_dwordx4 v186, s[100:101]
	s_waitcnt vmcnt(8)
	s_waitcnt lgkmcnt(0)
	s_setprio 1
	s_barrier
	v_mfma_f32_16x16x32_bf16 v[60:63], v[128:131], v[160:163], v[60:63]
	v_mfma_f32_16x16x32_bf16 v[60:63], v[132:135], v[164:167], v[60:63]
	v_mfma_f32_16x16x32_bf16 v[52:55], v[128:131], v[194:197], v[52:55]
	v_mfma_f32_16x16x32_bf16 v[52:55], v[132:135], v[198:201], v[52:55]
	v_mfma_f32_16x16x32_bf16 v[36:39], v[128:131], v[202:205], v[36:39]
	v_mfma_f32_16x16x32_bf16 v[36:39], v[132:135], v[206:209], v[36:39]
	v_mfma_f32_16x16x32_bf16 v[20:23], v[128:131], v[210:213], v[20:23]
	v_mfma_f32_16x16x32_bf16 v[20:23], v[132:135], v[214:217], v[20:23]
	v_mfma_f32_16x16x32_bf16 v[56:59], v[136:139], v[160:163], v[56:59]
	v_mfma_f32_16x16x32_bf16 v[56:59], v[140:143], v[164:167], v[56:59]
	v_mfma_f32_16x16x32_bf16 v[44:47], v[136:139], v[194:197], v[44:47]
	v_mfma_f32_16x16x32_bf16 v[44:47], v[140:143], v[198:201], v[44:47]
	v_mfma_f32_16x16x32_bf16 v[28:31], v[136:139], v[202:205], v[28:31]
	v_mfma_f32_16x16x32_bf16 v[28:31], v[140:143], v[206:209], v[28:31]
	v_mfma_f32_16x16x32_bf16 v[12:15], v[136:139], v[210:213], v[12:15]
	v_mfma_f32_16x16x32_bf16 v[12:15], v[140:143], v[214:217], v[12:15]
	v_mfma_f32_16x16x32_bf16 v[48:51], v[144:147], v[160:163], v[48:51]
	v_mfma_f32_16x16x32_bf16 v[48:51], v[148:151], v[164:167], v[48:51]
	v_mfma_f32_16x16x32_bf16 v[32:35], v[144:147], v[194:197], v[32:35]
	v_mfma_f32_16x16x32_bf16 v[32:35], v[148:151], v[198:201], v[32:35]
	v_mfma_f32_16x16x32_bf16 v[16:19], v[144:147], v[202:205], v[16:19]
	v_mfma_f32_16x16x32_bf16 v[16:19], v[148:151], v[206:209], v[16:19]
	v_mfma_f32_16x16x32_bf16 v[4:7], v[144:147], v[210:213], v[4:7]
	v_mfma_f32_16x16x32_bf16 v[4:7], v[148:151], v[214:217], v[4:7]
	v_mfma_f32_16x16x32_bf16 v[40:43], v[152:155], v[160:163], v[40:43]
	v_mfma_f32_16x16x32_bf16 v[40:43], v[156:159], v[164:167], v[40:43]
	v_mfma_f32_16x16x32_bf16 v[24:27], v[152:155], v[194:197], v[24:27]
	v_mfma_f32_16x16x32_bf16 v[24:27], v[156:159], v[198:201], v[24:27]
	v_mfma_f32_16x16x32_bf16 v[8:11], v[152:155], v[202:205], v[8:11]
	v_mfma_f32_16x16x32_bf16 v[8:11], v[156:159], v[206:209], v[8:11]
	v_mfma_f32_16x16x32_bf16 v[0:3], v[152:155], v[210:213], v[0:3]
	v_mfma_f32_16x16x32_bf16 v[0:3], v[156:159], v[214:217], v[0:3]
	s_barrier
	s_setprio 0
	s_add_i32 s3, s3, 2
	s_add_u32 s2, s2, 0xffffff00
	s_addc_u32 s30, s30, -1
	s_cmpk_gt_u32 s3, 0x55
	s_mov_b64 s[76:77], s[78:79]
	s_cbranch_scc0 .LBB0_343
	v_mov_b64_e32 v[234:235], 0x7f
	v_mov_b64_e32 v[174:175], 0x80
	v_mov_b64_e32 v[226:227], 0xb00
	s_and_b64 vcc, exec, s[72:73]
	s_cbranch_vccz .LBB0_346
	s_barrier

; #define PG8_STAGE(bufoff, gbase, voff) do { _Pragma("unroll") for (int _i = 0; _i < 2; ++_i) \
;         __builtin_amdgcn_global_load_lds((const unsigned*)((const char*)(gbase) + (voff)[_i]), (PG8_LAS unsigned*)(lds + (bufoff) + ldsw + _i * 8192), 16, 0, 0); } while (0)
; #define PG8_LDA(dst, b, h) do { _Pragma("unroll") for (int m = 0; m < 4; ++m) _Pragma("unroll") for (int k = 0; k < 2; ++k) dst[m][k] = *(const PG8_LAS bf16x8*)(lds + PG8_SA(b, h) + aoff + m * 2048 + k * 1024); } while (0)
; #define PG8_LDB(dst, b, h) do { _Pragma("unroll") for (int n = 0; n < 2; ++n) _Pragma("unroll") for (int k = 0; k < 2; ++k) dst[n][k] = *(const PG8_LAS bf16x8*)(lds + PG8_SB(b, h) + boff + n * 2048 + k * 1024); } while (0)
; #define PG8_MMA(ai, bj, At, Bt) do { __builtin_amdgcn_s_setprio(1); _Pragma("unroll") for (int m = 0; m < 4; ++m) _Pragma("unroll") for (int n = 0; n < 2; ++n) _Pragma("unroll") for (int k = 0; k < 2; ++k) \
;         acc[ai][bj][m][n] = __builtin_amdgcn_mfma_f32_16x16x32_bf16(Bt[n][k], At[m][k], acc[ai][bj][m][n], 0, 0, 0); __builtin_amdgcn_s_setprio(0); } while (0)
; #define PG8_WAIT_V(n) asm volatile("s_waitcnt vmcnt(" #n ")" ::: "memory")
; #define PG8_WAIT_L(n) asm volatile("s_waitcnt lgkmcnt(" #n ")" ::: "memory")
; #define PG8_BAR __builtin_amdgcn_s_barrier()
; #define PG8_SCHED __builtin_amdgcn_sched_barrier(0)
;     ...
;             const bool last = (t == nt - 2);
;             const char* a1 = PG8_KADV(cA, (size_t)(t + 1) * kstep);
;             const char* a2 = last ? nA : PG8_KADV(cA, (size_t)(t + 2) * kstep); const char* b2 = last ? nB : PG8_KADV(cB, (size_t)(t + 2) * kstep);
;             const char* a3 = PG8_KADV(a2, kstep); const char* b3 = PG8_KADV(b2, kstep);
;             if (last && has_next) S.a_ready(nxt);
;             if constexpr (SP2) {
;             PG8_LDB(B0, 0, 0); PG8_LDB(B1, 0, 1); PG8_SCHED; PG8_LDA(At, 0, 0); PG8_STAGE(PG8_SA(1, 1), a1 + hstep, voffA);
;             PG8_WAIT_V(8); PG8_WAIT_L(0); PG8_BAR; PG8_MMA(0, 0, At, B0); PG8_MMA(0, 1, At, B1); PG8_BAR; PG8_SCHED;
;             PG8_LDA(At, 0, 1); PG8_STAGE(PG8_SB(0, 0), b2, voffB); PG8_STAGE(PG8_SB(0, 1), b2 + hstep, voffB); PG8_STAGE(PG8_SA(0, 0), a2, voffA);
;             PG8_WAIT_V(8); PG8_WAIT_L(0); PG8_BAR; PG8_MMA(1, 0, At, B0); PG8_MMA(1, 1, At, B1); PG8_BAR; PG8_SCHED;
.LBB0_490:
	s_add_u32 s3, s86, 0xfff80080
	s_addc_u32 s12, s87, -1
	s_add_i32 s13, 0, 0x10000
	s_cmp_eq_u32 s2, 28
	s_cselect_b32 s91, s23, s12
	s_cselect_b32 s90, s25, s3
	s_cselect_b32 s89, s28, s40
	s_cselect_b32 s88, s30, s33
	s_add_i32 s3, 0, 0x14000
	v_add_u32_e32 v156, s13, v141
	v_add_u32_e32 v168, s3, v141
	ds_read_b128 v[144:147], v156
	ds_read_b128 v[148:151], v156 offset:1024
	ds_read_b128 v[152:155], v156 offset:2048
	ds_read_b128 v[156:159], v156 offset:3072
	ds_read_b128 v[160:163], v168
	ds_read_b128 v[164:167], v168 offset:1024
	ds_read_b128 v[170:173], v168 offset:2048
	ds_read_b128 v[178:181], v168 offset:3072
	s_add_i32 m0, s9, 0xc000
	ds_read_b128 v[182:185], v143
	ds_read_b128 v[186:189], v143 offset:1024
	ds_read_b128 v[190:193], v143 offset:2048
	ds_read_b128 v[194:197], v143 offset:3072
	ds_read_b128 v[198:201], v143 offset:4096
	ds_read_b128 v[202:205], v143 offset:5120
	ds_read_b128 v[206:209], v143 offset:6144
	ds_read_b128 v[210:213], v143 offset:7168
	global_load_lds_dwordx4 v136, s[86:87]
	s_add_i32 m0, s9, 0xe000
	s_nop 0
	global_load_lds_dwordx4 v138, s[86:87]
	s_waitcnt vmcnt(8)
	s_waitcnt lgkmcnt(0)
	s_setprio 1
	s_barrier
	v_mfma_f32_16x16x32_bf16 v[124:127], v[144:147], v[182:185], v[124:127]
	v_mfma_f32_16x16x32_bf16 v[124:127], v[148:151], v[186:189], v[124:127]
	v_mfma_f32_16x16x32_bf16 v[116:119], v[144:147], v[190:193], v[116:119]
	v_mfma_f32_16x16x32_bf16 v[116:119], v[148:151], v[194:197], v[116:119]
	v_mfma_f32_16x16x32_bf16 v[100:103], v[144:147], v[198:201], v[100:103]
	v_mfma_f32_16x16x32_bf16 v[100:103], v[148:151], v[202:205], v[100:103]
	v_mfma_f32_16x16x32_bf16 v[84:87], v[144:147], v[206:209], v[84:87]
	v_mfma_f32_16x16x32_bf16 v[84:87], v[148:151], v[210:213], v[84:87]
	v_mfma_f32_16x16x32_bf16 v[120:123], v[152:155], v[182:185], v[120:123]
	v_mfma_f32_16x16x32_bf16 v[120:123], v[156:159], v[186:189], v[120:123]
	v_mfma_f32_16x16x32_bf16 v[112:115], v[152:155], v[190:193], v[112:115]
	v_mfma_f32_16x16x32_bf16 v[112:115], v[156:159], v[194:197], v[112:115]
	v_mfma_f32_16x16x32_bf16 v[96:99], v[152:155], v[198:201], v[96:99]
	v_mfma_f32_16x16x32_bf16 v[96:99], v[156:159], v[202:205], v[96:99]
	v_mfma_f32_16x16x32_bf16 v[80:83], v[152:155], v[206:209], v[80:83]
	v_mfma_f32_16x16x32_bf16 v[80:83], v[156:159], v[210:213], v[80:83]
	v_mfma_f32_16x16x32_bf16 v[108:111], v[160:163], v[182:185], v[108:111]
	v_mfma_f32_16x16x32_bf16 v[108:111], v[164:167], v[186:189], v[108:111]
	v_mfma_f32_16x16x32_bf16 v[92:95], v[160:163], v[190:193], v[92:95]
	v_mfma_f32_16x16x32_bf16 v[92:95], v[164:167], v[194:197], v[92:95]
	v_mfma_f32_16x16x32_bf16 v[76:79], v[160:163], v[198:201], v[76:79]
	v_mfma_f32_16x16x32_bf16 v[76:79], v[164:167], v[202:205], v[76:79]
	v_mfma_f32_16x16x32_bf16 v[68:71], v[160:163], v[206:209], v[68:71]
	v_mfma_f32_16x16x32_bf16 v[68:71], v[164:167], v[210:213], v[68:71]
	v_mfma_f32_16x16x32_bf16 v[104:107], v[170:173], v[182:185], v[104:107]
	v_mfma_f32_16x16x32_bf16 v[104:107], v[178:181], v[186:189], v[104:107]
	v_mfma_f32_16x16x32_bf16 v[88:91], v[170:173], v[190:193], v[88:91]
	v_mfma_f32_16x16x32_bf16 v[88:91], v[178:181], v[194:197], v[88:91]
	v_mfma_f32_16x16x32_bf16 v[72:75], v[170:173], v[198:201], v[72:75]
	v_mfma_f32_16x16x32_bf16 v[72:75], v[178:181], v[202:205], v[72:75]
	v_mfma_f32_16x16x32_bf16 v[64:67], v[170:173], v[206:209], v[64:67]
	v_mfma_f32_16x16x32_bf16 v[64:67], v[178:181], v[210:213], v[64:67]
	s_barrier
	s_setprio 0
	s_add_i32 s12, s13, s8
	s_mov_b32 m0, s12
	ds_read_b128 v[182:185], v143 offset:16384
	ds_read_b128 v[186:189], v143 offset:17408
	ds_read_b128 v[190:193], v143 offset:18432
	ds_read_b128 v[194:197], v143 offset:19456
	ds_read_b128 v[198:201], v143 offset:20480
	ds_read_b128 v[202:205], v143 offset:21504
	ds_read_b128 v[206:209], v143 offset:22528
	ds_read_b128 v[210:213], v143 offset:23552
	global_load_lds_dwordx4 v130, s[88:89]
	s_add_i32 m0, s12, 0x2000
	s_add_u32 s42, s88, 0x80000
	s_addc_u32 s43, s89, 0
	s_add_i32 s3, s3, s8
	global_load_lds_dwordx4 v134, s[88:89]
	s_mov_b32 m0, s3
	s_nop 0
	global_load_lds_dwordx4 v130, s[42:43]
	s_add_i32 m0, s3, 0x2000
	s_nop 0
	global_load_lds_dwordx4 v134, s[42:43]
	s_mov_b32 m0, s9
	s_nop 0
	global_load_lds_dwordx4 v128, s[90:91]
	s_mov_b32 m0, s10
	s_nop 0
	global_load_lds_dwordx4 v132, s[90:91]
	s_waitcnt vmcnt(8)
	s_waitcnt lgkmcnt(0)
	s_setprio 1
	s_barrier
	v_mfma_f32_16x16x32_bf16 v[60:63], v[144:147], v[182:185], v[60:63]
	v_mfma_f32_16x16x32_bf16 v[60:63], v[148:151], v[186:189], v[60:63]
	v_mfma_f32_16x16x32_bf16 v[52:55], v[144:147], v[190:193], v[52:55]
	v_mfma_f32_16x16x32_bf16 v[52:55], v[148:151], v[194:197], v[52:55]
	v_mfma_f32_16x16x32_bf16 v[36:39], v[144:147], v[198:201], v[36:39]
	v_mfma_f32_16x16x32_bf16 v[36:39], v[148:151], v[202:205], v[36:39]
	v_mfma_f32_16x16x32_bf16 v[20:23], v[144:147], v[206:209], v[20:23]
	v_mfma_f32_16x16x32_bf16 v[20:23], v[148:151], v[210:213], v[20:23]
	v_mfma_f32_16x16x32_bf16 v[56:59], v[152:155], v[182:185], v[56:59]
	v_mfma_f32_16x16x32_bf16 v[56:59], v[156:159], v[186:189], v[56:59]
	v_mfma_f32_16x16x32_bf16 v[48:51], v[152:155], v[190:193], v[48:51]
	v_mfma_f32_16x16x32_bf16 v[48:51], v[156:159], v[194:197], v[48:51]
	v_mfma_f32_16x16x32_bf16 v[32:35], v[152:155], v[198:201], v[32:35]
	v_mfma_f32_16x16x32_bf16 v[32:35], v[156:159], v[202:205], v[32:35]
	v_mfma_f32_16x16x32_bf16 v[16:19], v[152:155], v[206:209], v[16:19]
	v_mfma_f32_16x16x32_bf16 v[16:19], v[156:159], v[210:213], v[16:19]
	v_mfma_f32_16x16x32_bf16 v[44:47], v[160:163], v[182:185], v[44:47]
	v_mfma_f32_16x16x32_bf16 v[44:47], v[164:167], v[186:189], v[44:47]
	v_mfma_f32_16x16x32_bf16 v[28:31], v[160:163], v[190:193], v[28:31]
	v_mfma_f32_16x16x32_bf16 v[28:31], v[164:167], v[194:197], v[28:31]
	v_mfma_f32_16x16x32_bf16 v[12:15], v[160:163], v[198:201], v[12:15]
	v_mfma_f32_16x16x32_bf16 v[12:15], v[164:167], v[202:205], v[12:15]
	v_mfma_f32_16x16x32_bf16 v[4:7], v[160:163], v[206:209], v[4:7]
	v_mfma_f32_16x16x32_bf16 v[4:7], v[164:167], v[210:213], v[4:7]
	v_mfma_f32_16x16x32_bf16 v[40:43], v[170:173], v[182:185], v[40:43]
	v_mfma_f32_16x16x32_bf16 v[40:43], v[178:181], v[186:189], v[40:43]
	v_mfma_f32_16x16x32_bf16 v[24:27], v[170:173], v[190:193], v[24:27]
	v_mfma_f32_16x16x32_bf16 v[24:27], v[178:181], v[194:197], v[24:27]
	v_mfma_f32_16x16x32_bf16 v[8:11], v[170:173], v[198:201], v[8:11]
	v_mfma_f32_16x16x32_bf16 v[8:11], v[178:181], v[202:205], v[8:11]
	v_mfma_f32_16x16x32_bf16 v[0:3], v[170:173], v[206:209], v[0:3]
	v_mfma_f32_16x16x32_bf16 v[0:3], v[178:181], v[210:213], v[0:3]
	s_barrier
; #define PG8_STAGE(bufoff, gbase, voff) do { _Pragma("unroll") for (int _i = 0; _i < 2; ++_i) \
;         __builtin_amdgcn_global_load_lds((const unsigned*)((const char*)(gbase) + (voff)[_i]), (PG8_LAS unsigned*)(lds + (bufoff) + ldsw + _i * 8192), 16, 0, 0); } while (0)
; #define PG8_LDA(dst, b, h) do { _Pragma("unroll") for (int m = 0; m < 4; ++m) _Pragma("unroll") for (int k = 0; k < 2; ++k) dst[m][k] = *(const PG8_LAS bf16x8*)(lds + PG8_SA(b, h) + aoff + m * 2048 + k * 1024); } while (0)
; #define PG8_LDB(dst, b, h) do { _Pragma("unroll") for (int n = 0; n < 2; ++n) _Pragma("unroll") for (int k = 0; k < 2; ++k) dst[n][k] = *(const PG8_LAS bf16x8*)(lds + PG8_SB(b, h) + boff + n * 2048 + k * 1024); } while (0)
; #define PG8_MMA(ai, bj, At, Bt) do { __builtin_amdgcn_s_setprio(1); _Pragma("unroll") for (int m = 0; m < 4; ++m) _Pragma("unroll") for (int n = 0; n < 2; ++n) _Pragma("unroll") for (int k = 0; k < 2; ++k) \
;         acc[ai][bj][m][n] = __builtin_amdgcn_mfma_f32_16x16x32_bf16(Bt[n][k], At[m][k], acc[ai][bj][m][n], 0, 0, 0); __builtin_amdgcn_s_setprio(0); } while (0)
; #define PG8_WAIT_V(n) asm volatile("s_waitcnt vmcnt(" #n ")" ::: "memory")
; #define PG8_WAIT_L(n) asm volatile("s_waitcnt lgkmcnt(" #n ")" ::: "memory")
; #define PG8_BAR __builtin_amdgcn_s_barrier()
; #define PG8_SCHED __builtin_amdgcn_sched_barrier(0)
;     ...
;             PG8_LDB(B0, 1, 0); PG8_LDB(B1, 1, 1); PG8_SCHED; PG8_LDA(At, 1, 0); PG8_STAGE(PG8_SA(0, 1), a2 + hstep, voffA);
;             PG8_WAIT_V(8); PG8_WAIT_L(0); PG8_BAR; PG8_MMA(0, 0, At, B0); PG8_MMA(0, 1, At, B1); PG8_BAR; PG8_SCHED;
;             PG8_LDA(At, 1, 1); PG8_STAGE(PG8_SB(1, 0), b3, voffB); PG8_STAGE(PG8_SB(1, 1), b3 + hstep, voffB); PG8_STAGE(PG8_SA(1, 0), a3, voffA);
;             PG8_WAIT_V(8); PG8_WAIT_L(0); PG8_BAR; PG8_MMA(1, 0, At, B0); PG8_MMA(1, 1, At, B1); PG8_BAR; PG8_SCHED;
	s_setprio 0
	s_add_i32 s3, 0, 0x18000
	s_add_i32 s12, 0, 0x1c000
	v_add_u32_e32 v156, s3, v141
	v_add_u32_e32 v168, s12, v141
	ds_read_b128 v[144:147], v156
	ds_read_b128 v[148:151], v156 offset:1024
	ds_read_b128 v[152:155], v156 offset:2048
	ds_read_b128 v[156:159], v156 offset:3072
	ds_read_b128 v[160:163], v168
	ds_read_b128 v[164:167], v168 offset:1024
	ds_read_b128 v[170:173], v168 offset:2048
	ds_read_b128 v[178:181], v168 offset:3072
	s_add_u32 s42, s90, 0x80000
	s_addc_u32 s43, s91, 0
	s_mov_b32 m0, s18
	ds_read_b128 v[182:185], v143 offset:32768
	ds_read_b128 v[186:189], v143 offset:33792
	ds_read_b128 v[190:193], v143 offset:34816
	ds_read_b128 v[194:197], v143 offset:35840
	ds_read_b128 v[198:201], v143 offset:36864
	ds_read_b128 v[202:205], v143 offset:37888
	ds_read_b128 v[206:209], v143 offset:38912
	ds_read_b128 v[210:213], v143 offset:39936
	global_load_lds_dwordx4 v128, s[42:43]
	s_mov_b32 m0, s19
	s_nop 0
	global_load_lds_dwordx4 v132, s[42:43]
	s_waitcnt vmcnt(8)
	s_waitcnt lgkmcnt(0)
	s_setprio 1
	s_barrier
	v_mfma_f32_16x16x32_bf16 v[124:127], v[144:147], v[182:185], v[124:127]
	v_mfma_f32_16x16x32_bf16 v[124:127], v[148:151], v[186:189], v[124:127]
	v_mfma_f32_16x16x32_bf16 v[116:119], v[144:147], v[190:193], v[116:119]
	v_mfma_f32_16x16x32_bf16 v[116:119], v[148:151], v[194:197], v[116:119]
	v_mfma_f32_16x16x32_bf16 v[100:103], v[144:147], v[198:201], v[100:103]
	v_mfma_f32_16x16x32_bf16 v[100:103], v[148:151], v[202:205], v[100:103]
	v_mfma_f32_16x16x32_bf16 v[84:87], v[144:147], v[206:209], v[84:87]
	v_mfma_f32_16x16x32_bf16 v[84:87], v[148:151], v[210:213], v[84:87]
	v_mfma_f32_16x16x32_bf16 v[120:123], v[152:155], v[182:185], v[120:123]
	v_mfma_f32_16x16x32_bf16 v[120:123], v[156:159], v[186:189], v[120:123]
	v_mfma_f32_16x16x32_bf16 v[112:115], v[152:155], v[190:193], v[112:115]
	v_mfma_f32_16x16x32_bf16 v[112:115], v[156:159], v[194:197], v[112:115]
	v_mfma_f32_16x16x32_bf16 v[96:99], v[152:155], v[198:201], v[96:99]
	v_mfma_f32_16x16x32_bf16 v[96:99], v[156:159], v[202:205], v[96:99]
	v_mfma_f32_16x16x32_bf16 v[80:83], v[152:155], v[206:209], v[80:83]
	v_mfma_f32_16x16x32_bf16 v[80:83], v[156:159], v[210:213], v[80:83]
	v_mfma_f32_16x16x32_bf16 v[108:111], v[160:163], v[182:185], v[108:111]
	v_mfma_f32_16x16x32_bf16 v[108:111], v[164:167], v[186:189], v[108:111]
	v_mfma_f32_16x16x32_bf16 v[92:95], v[160:163], v[190:193], v[92:95]
	v_mfma_f32_16x16x32_bf16 v[92:95], v[164:167], v[194:197], v[92:95]
	v_mfma_f32_16x16x32_bf16 v[76:79], v[160:163], v[198:201], v[76:79]
	v_mfma_f32_16x16x32_bf16 v[76:79], v[164:167], v[202:205], v[76:79]
	v_mfma_f32_16x16x32_bf16 v[68:71], v[160:163], v[206:209], v[68:71]
	v_mfma_f32_16x16x32_bf16 v[68:71], v[164:167], v[210:213], v[68:71]
	v_mfma_f32_16x16x32_bf16 v[104:107], v[170:173], v[182:185], v[104:107]
	v_mfma_f32_16x16x32_bf16 v[104:107], v[178:181], v[186:189], v[104:107]
	v_mfma_f32_16x16x32_bf16 v[88:91], v[170:173], v[190:193], v[88:91]
	v_mfma_f32_16x16x32_bf16 v[88:91], v[178:181], v[194:197], v[88:91]
	v_mfma_f32_16x16x32_bf16 v[72:75], v[170:173], v[198:201], v[72:75]
	v_mfma_f32_16x16x32_bf16 v[72:75], v[178:181], v[202:205], v[72:75]
	v_mfma_f32_16x16x32_bf16 v[64:67], v[170:173], v[206:209], v[64:67]
	v_mfma_f32_16x16x32_bf16 v[64:67], v[178:181], v[210:213], v[64:67]
	s_barrier
	s_setprio 0
	s_add_i32 s3, s3, s8
	s_mov_b32 m0, s3
	ds_read_b128 v[182:185], v143 offset:49152
	ds_read_b128 v[186:189], v143 offset:50176
	ds_read_b128 v[190:193], v143 offset:51200
	ds_read_b128 v[194:197], v143 offset:52224
	ds_read_b128 v[198:201], v143 offset:53248
	ds_read_b128 v[202:205], v143 offset:54272
	ds_read_b128 v[206:209], v143 offset:55296
	ds_read_b128 v[210:213], v143 offset:56320
	s_add_u32 s100, s88, s16
	s_addc_u32 s101, s89, s17
	global_load_lds_dwordx4 v130, s[100:101]
	s_add_i32 m0, s3, 0x2000
	s_add_u32 s42, s88, 0x80080
	s_addc_u32 s43, s89, 0
	s_add_i32 s3, s12, s8
	global_load_lds_dwordx4 v134, s[100:101]
	s_mov_b32 m0, s3
	s_nop 0
	global_load_lds_dwordx4 v130, s[42:43]
	s_add_i32 m0, s3, 0x2000
	s_nop 0
	global_load_lds_dwordx4 v134, s[42:43]
	s_mov_b32 m0, s20
	s_nop 0
	s_add_u32 s100, s90, s16
	s_addc_u32 s101, s91, s17
	global_load_lds_dwordx4 v128, s[100:101]
	s_mov_b32 m0, s21
	s_nop 0
	global_load_lds_dwordx4 v132, s[100:101]
	s_waitcnt vmcnt(8)
	s_waitcnt lgkmcnt(0)
	s_setprio 1
	s_barrier
	v_mfma_f32_16x16x32_bf16 v[60:63], v[144:147], v[182:185], v[60:63]
	v_mfma_f32_16x16x32_bf16 v[60:63], v[148:151], v[186:189], v[60:63]
	v_mfma_f32_16x16x32_bf16 v[52:55], v[144:147], v[190:193], v[52:55]
	v_mfma_f32_16x16x32_bf16 v[52:55], v[148:151], v[194:197], v[52:55]
	v_mfma_f32_16x16x32_bf16 v[36:39], v[144:147], v[198:201], v[36:39]
	v_mfma_f32_16x16x32_bf16 v[36:39], v[148:151], v[202:205], v[36:39]
	v_mfma_f32_16x16x32_bf16 v[20:23], v[144:147], v[206:209], v[20:23]
	v_mfma_f32_16x16x32_bf16 v[20:23], v[148:151], v[210:213], v[20:23]
	v_mfma_f32_16x16x32_bf16 v[56:59], v[152:155], v[182:185], v[56:59]
	v_mfma_f32_16x16x32_bf16 v[56:59], v[156:159], v[186:189], v[56:59]
	v_mfma_f32_16x16x32_bf16 v[48:51], v[152:155], v[190:193], v[48:51]
	v_mfma_f32_16x16x32_bf16 v[48:51], v[156:159], v[194:197], v[48:51]
	v_mfma_f32_16x16x32_bf16 v[32:35], v[152:155], v[198:201], v[32:35]
	v_mfma_f32_16x16x32_bf16 v[32:35], v[156:159], v[202:205], v[32:35]
	v_mfma_f32_16x16x32_bf16 v[16:19], v[152:155], v[206:209], v[16:19]
	v_mfma_f32_16x16x32_bf16 v[16:19], v[156:159], v[210:213], v[16:19]
	v_mfma_f32_16x16x32_bf16 v[44:47], v[160:163], v[182:185], v[44:47]
	v_mfma_f32_16x16x32_bf16 v[44:47], v[164:167], v[186:189], v[44:47]
	v_mfma_f32_16x16x32_bf16 v[28:31], v[160:163], v[190:193], v[28:31]
	v_mfma_f32_16x16x32_bf16 v[28:31], v[164:167], v[194:197], v[28:31]
	v_mfma_f32_16x16x32_bf16 v[12:15], v[160:163], v[198:201], v[12:15]
	v_mfma_f32_16x16x32_bf16 v[12:15], v[164:167], v[202:205], v[12:15]
	v_mfma_f32_16x16x32_bf16 v[4:7], v[160:163], v[206:209], v[4:7]
	v_mfma_f32_16x16x32_bf16 v[4:7], v[164:167], v[210:213], v[4:7]
	v_mfma_f32_16x16x32_bf16 v[40:43], v[170:173], v[182:185], v[40:43]
	v_mfma_f32_16x16x32_bf16 v[40:43], v[178:181], v[186:189], v[40:43]
	v_mfma_f32_16x16x32_bf16 v[24:27], v[170:173], v[190:193], v[24:27]
	v_mfma_f32_16x16x32_bf16 v[24:27], v[178:181], v[194:197], v[24:27]
	v_mfma_f32_16x16x32_bf16 v[8:11], v[170:173], v[198:201], v[8:11]
	v_mfma_f32_16x16x32_bf16 v[8:11], v[178:181], v[202:205], v[8:11]
	v_mfma_f32_16x16x32_bf16 v[0:3], v[170:173], v[206:209], v[0:3]
	v_mfma_f32_16x16x32_bf16 v[0:3], v[178:181], v[210:213], v[0:3]
	s_barrier
	s_setprio 0
	s_add_i32 s2, s2, 2
	s_add_u32 s86, s86, 0x100
	s_addc_u32 s87, s87, 0
	s_add_u32 s33, s33, 0x100
	s_addc_u32 s40, s40, 0
	s_cmp_gt_u32 s2, 29
	s_cbranch_scc0 .LBB0_490
	s_and_b64 vcc, exec, s[74:75]
	s_cbranch_vccz .LBB0_493
	s_barrier

; #define PG8_STAGE(bufoff, gbase, voff) do { _Pragma("unroll") for (int _i = 0; _i < 2; ++_i) \
;         __builtin_amdgcn_global_load_lds((const unsigned*)((const char*)(gbase) + (voff)[_i]), (PG8_LAS unsigned*)(lds + (bufoff) + ldsw + _i * 8192), 16, 0, 0); } while (0)
; #define PG8_LDA(dst, b, h) do { _Pragma("unroll") for (int m = 0; m < 4; ++m) _Pragma("unroll") for (int k = 0; k < 2; ++k) dst[m][k] = *(const PG8_LAS bf16x8*)(lds + PG8_SA(b, h) + aoff + m * 2048 + k * 1024); } while (0)
; #define PG8_LDB(dst, b, h) do { _Pragma("unroll") for (int n = 0; n < 2; ++n) _Pragma("unroll") for (int k = 0; k < 2; ++k) dst[n][k] = *(const PG8_LAS bf16x8*)(lds + PG8_SB(b, h) + boff + n * 2048 + k * 1024); } while (0)
; #define PG8_MMA(ai, bj, At, Bt) do { __builtin_amdgcn_s_setprio(1); _Pragma("unroll") for (int m = 0; m < 4; ++m) _Pragma("unroll") for (int n = 0; n < 2; ++n) _Pragma("unroll") for (int k = 0; k < 2; ++k) \
;         acc[ai][bj][m][n] = __builtin_amdgcn_mfma_f32_16x16x32_bf16(Bt[n][k], At[m][k], acc[ai][bj][m][n], 0, 0, 0); __builtin_amdgcn_s_setprio(0); } while (0)
; #define PG8_WAIT_V(n) asm volatile("s_waitcnt vmcnt(" #n ")" ::: "memory")
; #define PG8_WAIT_L(n) asm volatile("s_waitcnt lgkmcnt(" #n ")" ::: "memory")
; #define PG8_BAR __builtin_amdgcn_s_barrier()
; #define PG8_SCHED __builtin_amdgcn_sched_barrier(0)
;     ...
;             const bool last = (t == nt - 2);
;             const char* a1 = PG8_KADV(cA, (size_t)(t + 1) * kstep);
;             const char* a2 = last ? nA : PG8_KADV(cA, (size_t)(t + 2) * kstep); const char* b2 = last ? nB : PG8_KADV(cB, (size_t)(t + 2) * kstep);
;             const char* a3 = PG8_KADV(a2, kstep); const char* b3 = PG8_KADV(b2, kstep);
;             if (last && has_next) S.a_ready(nxt);
;             if constexpr (SP2) {
;             PG8_LDB(B0, 0, 0); PG8_LDB(B1, 0, 1); PG8_SCHED; PG8_LDA(At, 0, 0); PG8_STAGE(PG8_SA(1, 1), a1 + hstep, voffA);
;             PG8_WAIT_V(8); PG8_WAIT_L(0); PG8_BAR; PG8_MMA(0, 0, At, B0); PG8_MMA(0, 1, At, B1); PG8_BAR; PG8_SCHED;
;             PG8_LDA(At, 0, 1); PG8_STAGE(PG8_SB(0, 0), b2, voffB); PG8_STAGE(PG8_SB(0, 1), b2 + hstep, voffB); PG8_STAGE(PG8_SA(0, 0), a2, voffA);
;             PG8_WAIT_V(8); PG8_WAIT_L(0); PG8_BAR; PG8_MMA(1, 0, At, B0); PG8_MMA(1, 1, At, B1); PG8_BAR; PG8_SCHED;
.LBB0_514:
	s_add_u32 s3, s86, 0xfff80080
	s_addc_u32 s12, s87, -1
	s_add_i32 s13, 0, 0x10000
	s_cmp_eq_u32 s2, 28
	s_cselect_b32 s91, s28, s12
	s_cselect_b32 s90, s30, s3
	s_cselect_b32 s89, s33, s43
	s_cselect_b32 s88, s40, s42
	s_add_i32 s3, 0, 0x14000
	v_add_u32_e32 v156, s13, v141
	v_add_u32_e32 v168, s3, v141
	ds_read_b128 v[144:147], v156
	ds_read_b128 v[148:151], v156 offset:1024
	ds_read_b128 v[152:155], v156 offset:2048
	ds_read_b128 v[156:159], v156 offset:3072
	ds_read_b128 v[160:163], v168
	ds_read_b128 v[164:167], v168 offset:1024
	ds_read_b128 v[170:173], v168 offset:2048
	ds_read_b128 v[178:181], v168 offset:3072
	s_add_i32 m0, s18, 0xc000
	ds_read_b128 v[182:185], v143
	ds_read_b128 v[186:189], v143 offset:1024
	ds_read_b128 v[190:193], v143 offset:2048
	ds_read_b128 v[194:197], v143 offset:3072
	ds_read_b128 v[198:201], v143 offset:4096
	ds_read_b128 v[202:205], v143 offset:5120
	ds_read_b128 v[206:209], v143 offset:6144
	ds_read_b128 v[210:213], v143 offset:7168
	global_load_lds_dwordx4 v136, s[86:87]
	s_add_i32 m0, s18, 0xe000
	s_nop 0
	global_load_lds_dwordx4 v138, s[86:87]
	s_waitcnt vmcnt(8)
	s_waitcnt lgkmcnt(0)
	s_setprio 1
	s_barrier
	v_mfma_f32_16x16x32_bf16 v[124:127], v[144:147], v[182:185], v[124:127]
	v_mfma_f32_16x16x32_bf16 v[124:127], v[148:151], v[186:189], v[124:127]
	v_mfma_f32_16x16x32_bf16 v[116:119], v[144:147], v[190:193], v[116:119]
	v_mfma_f32_16x16x32_bf16 v[116:119], v[148:151], v[194:197], v[116:119]
	v_mfma_f32_16x16x32_bf16 v[100:103], v[144:147], v[198:201], v[100:103]
	v_mfma_f32_16x16x32_bf16 v[100:103], v[148:151], v[202:205], v[100:103]
	v_mfma_f32_16x16x32_bf16 v[84:87], v[144:147], v[206:209], v[84:87]
	v_mfma_f32_16x16x32_bf16 v[84:87], v[148:151], v[210:213], v[84:87]
	v_mfma_f32_16x16x32_bf16 v[120:123], v[152:155], v[182:185], v[120:123]
	v_mfma_f32_16x16x32_bf16 v[120:123], v[156:159], v[186:189], v[120:123]
	v_mfma_f32_16x16x32_bf16 v[112:115], v[152:155], v[190:193], v[112:115]
	v_mfma_f32_16x16x32_bf16 v[112:115], v[156:159], v[194:197], v[112:115]
	v_mfma_f32_16x16x32_bf16 v[96:99], v[152:155], v[198:201], v[96:99]
	v_mfma_f32_16x16x32_bf16 v[96:99], v[156:159], v[202:205], v[96:99]
	v_mfma_f32_16x16x32_bf16 v[80:83], v[152:155], v[206:209], v[80:83]
	v_mfma_f32_16x16x32_bf16 v[80:83], v[156:159], v[210:213], v[80:83]
	v_mfma_f32_16x16x32_bf16 v[108:111], v[160:163], v[182:185], v[108:111]
	v_mfma_f32_16x16x32_bf16 v[108:111], v[164:167], v[186:189], v[108:111]
	v_mfma_f32_16x16x32_bf16 v[92:95], v[160:163], v[190:193], v[92:95]
	v_mfma_f32_16x16x32_bf16 v[92:95], v[164:167], v[194:197], v[92:95]
	v_mfma_f32_16x16x32_bf16 v[76:79], v[160:163], v[198:201], v[76:79]
	v_mfma_f32_16x16x32_bf16 v[76:79], v[164:167], v[202:205], v[76:79]
	v_mfma_f32_16x16x32_bf16 v[68:71], v[160:163], v[206:209], v[68:71]
	v_mfma_f32_16x16x32_bf16 v[68:71], v[164:167], v[210:213], v[68:71]
	v_mfma_f32_16x16x32_bf16 v[104:107], v[170:173], v[182:185], v[104:107]
	v_mfma_f32_16x16x32_bf16 v[104:107], v[178:181], v[186:189], v[104:107]
	v_mfma_f32_16x16x32_bf16 v[88:91], v[170:173], v[190:193], v[88:91]
	v_mfma_f32_16x16x32_bf16 v[88:91], v[178:181], v[194:197], v[88:91]
	v_mfma_f32_16x16x32_bf16 v[72:75], v[170:173], v[198:201], v[72:75]
	v_mfma_f32_16x16x32_bf16 v[72:75], v[178:181], v[202:205], v[72:75]
	v_mfma_f32_16x16x32_bf16 v[64:67], v[170:173], v[206:209], v[64:67]
	v_mfma_f32_16x16x32_bf16 v[64:67], v[178:181], v[210:213], v[64:67]
	s_barrier
	s_setprio 0
	s_add_i32 s12, s13, s10
	s_mov_b32 m0, s12
	ds_read_b128 v[182:185], v143 offset:16384
	ds_read_b128 v[186:189], v143 offset:17408
	ds_read_b128 v[190:193], v143 offset:18432
	ds_read_b128 v[194:197], v143 offset:19456
	ds_read_b128 v[198:201], v143 offset:20480
	ds_read_b128 v[202:205], v143 offset:21504
	ds_read_b128 v[206:209], v143 offset:22528
	ds_read_b128 v[210:213], v143 offset:23552
	global_load_lds_dwordx4 v130, s[88:89]
	s_add_i32 m0, s12, 0x2000
	s_add_u32 vcc_lo, s88, 0x80000
	v_lshl_add_u64 v[216:217], s[88:89], 0, v[134:135]
	s_addc_u32 vcc_hi, s89, 0
	s_add_i32 s3, s3, s10
	global_load_lds_dwordx4 v134, s[88:89]
	s_mov_b32 m0, s3
	v_lshl_add_u64 v[220:221], s[90:91], 0, v[132:133]
	global_load_lds_dwordx4 v130, vcc
	s_add_i32 m0, s3, 0x2000
	s_nop 0
	global_load_lds_dwordx4 v134, vcc
	v_lshl_add_u64 v[218:219], s[90:91], 0, v[128:129]
	s_mov_b32 m0, s18
	s_nop 0
	global_load_lds_dwordx4 v128, s[90:91]
	s_mov_b32 m0, s19
	s_nop 0
	global_load_lds_dwordx4 v132, s[90:91]
	s_waitcnt vmcnt(8)
	s_waitcnt lgkmcnt(0)
	s_setprio 1
	s_barrier
	v_mfma_f32_16x16x32_bf16 v[60:63], v[144:147], v[182:185], v[60:63]
	v_mfma_f32_16x16x32_bf16 v[60:63], v[148:151], v[186:189], v[60:63]
	v_mfma_f32_16x16x32_bf16 v[52:55], v[144:147], v[190:193], v[52:55]
	v_mfma_f32_16x16x32_bf16 v[52:55], v[148:151], v[194:197], v[52:55]
	v_mfma_f32_16x16x32_bf16 v[36:39], v[144:147], v[198:201], v[36:39]
	v_mfma_f32_16x16x32_bf16 v[36:39], v[148:151], v[202:205], v[36:39]
	v_mfma_f32_16x16x32_bf16 v[20:23], v[144:147], v[206:209], v[20:23]
	v_mfma_f32_16x16x32_bf16 v[20:23], v[148:151], v[210:213], v[20:23]
	v_mfma_f32_16x16x32_bf16 v[56:59], v[152:155], v[182:185], v[56:59]
	v_mfma_f32_16x16x32_bf16 v[56:59], v[156:159], v[186:189], v[56:59]
	v_mfma_f32_16x16x32_bf16 v[48:51], v[152:155], v[190:193], v[48:51]
	v_mfma_f32_16x16x32_bf16 v[48:51], v[156:159], v[194:197], v[48:51]
	v_mfma_f32_16x16x32_bf16 v[32:35], v[152:155], v[198:201], v[32:35]
	v_mfma_f32_16x16x32_bf16 v[32:35], v[156:159], v[202:205], v[32:35]
	v_mfma_f32_16x16x32_bf16 v[16:19], v[152:155], v[206:209], v[16:19]
	v_mfma_f32_16x16x32_bf16 v[16:19], v[156:159], v[210:213], v[16:19]
	v_mfma_f32_16x16x32_bf16 v[44:47], v[160:163], v[182:185], v[44:47]
	v_mfma_f32_16x16x32_bf16 v[44:47], v[164:167], v[186:189], v[44:47]
	v_mfma_f32_16x16x32_bf16 v[28:31], v[160:163], v[190:193], v[28:31]
	v_mfma_f32_16x16x32_bf16 v[28:31], v[164:167], v[194:197], v[28:31]
	v_mfma_f32_16x16x32_bf16 v[12:15], v[160:163], v[198:201], v[12:15]
	v_mfma_f32_16x16x32_bf16 v[12:15], v[164:167], v[202:205], v[12:15]
	v_mfma_f32_16x16x32_bf16 v[4:7], v[160:163], v[206:209], v[4:7]
	v_mfma_f32_16x16x32_bf16 v[4:7], v[164:167], v[210:213], v[4:7]
	v_mfma_f32_16x16x32_bf16 v[40:43], v[170:173], v[182:185], v[40:43]
	v_mfma_f32_16x16x32_bf16 v[40:43], v[178:181], v[186:189], v[40:43]
	v_mfma_f32_16x16x32_bf16 v[24:27], v[170:173], v[190:193], v[24:27]
	v_mfma_f32_16x16x32_bf16 v[24:27], v[178:181], v[194:197], v[24:27]
	v_mfma_f32_16x16x32_bf16 v[8:11], v[170:173], v[198:201], v[8:11]
	v_mfma_f32_16x16x32_bf16 v[8:11], v[178:181], v[202:205], v[8:11]
	v_mfma_f32_16x16x32_bf16 v[0:3], v[170:173], v[206:209], v[0:3]
	v_mfma_f32_16x16x32_bf16 v[0:3], v[178:181], v[210:213], v[0:3]
	s_barrier
; #define PG8_STAGE(bufoff, gbase, voff) do { _Pragma("unroll") for (int _i = 0; _i < 2; ++_i) \
;         __builtin_amdgcn_global_load_lds((const unsigned*)((const char*)(gbase) + (voff)[_i]), (PG8_LAS unsigned*)(lds + (bufoff) + ldsw + _i * 8192), 16, 0, 0); } while (0)
; #define PG8_LDA(dst, b, h) do { _Pragma("unroll") for (int m = 0; m < 4; ++m) _Pragma("unroll") for (int k = 0; k < 2; ++k) dst[m][k] = *(const PG8_LAS bf16x8*)(lds + PG8_SA(b, h) + aoff + m * 2048 + k * 1024); } while (0)
; #define PG8_LDB(dst, b, h) do { _Pragma("unroll") for (int n = 0; n < 2; ++n) _Pragma("unroll") for (int k = 0; k < 2; ++k) dst[n][k] = *(const PG8_LAS bf16x8*)(lds + PG8_SB(b, h) + boff + n * 2048 + k * 1024); } while (0)
; #define PG8_MMA(ai, bj, At, Bt) do { __builtin_amdgcn_s_setprio(1); _Pragma("unroll") for (int m = 0; m < 4; ++m) _Pragma("unroll") for (int n = 0; n < 2; ++n) _Pragma("unroll") for (int k = 0; k < 2; ++k) \
;         acc[ai][bj][m][n] = __builtin_amdgcn_mfma_f32_16x16x32_bf16(Bt[n][k], At[m][k], acc[ai][bj][m][n], 0, 0, 0); __builtin_amdgcn_s_setprio(0); } while (0)
; #define PG8_WAIT_V(n) asm volatile("s_waitcnt vmcnt(" #n ")" ::: "memory")
; #define PG8_WAIT_L(n) asm volatile("s_waitcnt lgkmcnt(" #n ")" ::: "memory")
; #define PG8_BAR __builtin_amdgcn_s_barrier()
; #define PG8_SCHED __builtin_amdgcn_sched_barrier(0)
;     ...
;             PG8_LDB(B0, 1, 0); PG8_LDB(B1, 1, 1); PG8_SCHED; PG8_LDA(At, 1, 0); PG8_STAGE(PG8_SA(0, 1), a2 + hstep, voffA);
;             PG8_WAIT_V(8); PG8_WAIT_L(0); PG8_BAR; PG8_MMA(0, 0, At, B0); PG8_MMA(0, 1, At, B1); PG8_BAR; PG8_SCHED;
;             PG8_LDA(At, 1, 1); PG8_STAGE(PG8_SB(1, 0), b3, voffB); PG8_STAGE(PG8_SB(1, 1), b3 + hstep, voffB); PG8_STAGE(PG8_SA(1, 0), a3, voffA);
;             PG8_WAIT_V(8); PG8_WAIT_L(0); PG8_BAR; PG8_MMA(1, 0, At, B0); PG8_MMA(1, 1, At, B1); PG8_BAR; PG8_SCHED;
	s_setprio 0
	s_add_i32 s3, 0, 0x18000
	s_add_i32 s12, 0, 0x1c000
	v_add_u32_e32 v156, s3, v141
	v_add_u32_e32 v168, s12, v141
	ds_read_b128 v[144:147], v156
	ds_read_b128 v[148:151], v156 offset:1024
	ds_read_b128 v[152:155], v156 offset:2048
	ds_read_b128 v[156:159], v156 offset:3072
	ds_read_b128 v[160:163], v168
	ds_read_b128 v[164:167], v168 offset:1024
	ds_read_b128 v[170:173], v168 offset:2048
	ds_read_b128 v[178:181], v168 offset:3072
	s_add_u32 s90, s90, 0x80000
	s_addc_u32 s91, s91, 0
	s_mov_b32 m0, s20
	ds_read_b128 v[182:185], v143 offset:32768
	ds_read_b128 v[186:189], v143 offset:33792
	ds_read_b128 v[190:193], v143 offset:34816
	ds_read_b128 v[194:197], v143 offset:35840
	ds_read_b128 v[198:201], v143 offset:36864
	ds_read_b128 v[202:205], v143 offset:37888
	ds_read_b128 v[206:209], v143 offset:38912
	ds_read_b128 v[210:213], v143 offset:39936
	global_load_lds_dwordx4 v128, s[90:91]
	s_mov_b32 m0, s21
	s_nop 0
	global_load_lds_dwordx4 v132, s[90:91]
	s_waitcnt vmcnt(8)
	s_waitcnt lgkmcnt(0)
	s_setprio 1
	s_barrier
	v_mfma_f32_16x16x32_bf16 v[124:127], v[144:147], v[182:185], v[124:127]
	v_mfma_f32_16x16x32_bf16 v[124:127], v[148:151], v[186:189], v[124:127]
	v_mfma_f32_16x16x32_bf16 v[116:119], v[144:147], v[190:193], v[116:119]
	v_mfma_f32_16x16x32_bf16 v[116:119], v[148:151], v[194:197], v[116:119]
	v_mfma_f32_16x16x32_bf16 v[100:103], v[144:147], v[198:201], v[100:103]
	v_mfma_f32_16x16x32_bf16 v[100:103], v[148:151], v[202:205], v[100:103]
	v_mfma_f32_16x16x32_bf16 v[84:87], v[144:147], v[206:209], v[84:87]
	v_mfma_f32_16x16x32_bf16 v[84:87], v[148:151], v[210:213], v[84:87]
	v_mfma_f32_16x16x32_bf16 v[120:123], v[152:155], v[182:185], v[120:123]
	v_mfma_f32_16x16x32_bf16 v[120:123], v[156:159], v[186:189], v[120:123]
	v_mfma_f32_16x16x32_bf16 v[112:115], v[152:155], v[190:193], v[112:115]
	v_mfma_f32_16x16x32_bf16 v[112:115], v[156:159], v[194:197], v[112:115]
	v_mfma_f32_16x16x32_bf16 v[96:99], v[152:155], v[198:201], v[96:99]
	v_mfma_f32_16x16x32_bf16 v[96:99], v[156:159], v[202:205], v[96:99]
	v_mfma_f32_16x16x32_bf16 v[80:83], v[152:155], v[206:209], v[80:83]
	v_mfma_f32_16x16x32_bf16 v[80:83], v[156:159], v[210:213], v[80:83]
	v_mfma_f32_16x16x32_bf16 v[108:111], v[160:163], v[182:185], v[108:111]
	v_mfma_f32_16x16x32_bf16 v[108:111], v[164:167], v[186:189], v[108:111]
	v_mfma_f32_16x16x32_bf16 v[92:95], v[160:163], v[190:193], v[92:95]
	v_mfma_f32_16x16x32_bf16 v[92:95], v[164:167], v[194:197], v[92:95]
	v_mfma_f32_16x16x32_bf16 v[76:79], v[160:163], v[198:201], v[76:79]
	v_mfma_f32_16x16x32_bf16 v[76:79], v[164:167], v[202:205], v[76:79]
	v_mfma_f32_16x16x32_bf16 v[68:71], v[160:163], v[206:209], v[68:71]
	v_mfma_f32_16x16x32_bf16 v[68:71], v[164:167], v[210:213], v[68:71]
	v_mfma_f32_16x16x32_bf16 v[104:107], v[170:173], v[182:185], v[104:107]
	v_mfma_f32_16x16x32_bf16 v[104:107], v[178:181], v[186:189], v[104:107]
	v_mfma_f32_16x16x32_bf16 v[88:91], v[170:173], v[190:193], v[88:91]
	v_mfma_f32_16x16x32_bf16 v[88:91], v[178:181], v[194:197], v[88:91]
	v_mfma_f32_16x16x32_bf16 v[72:75], v[170:173], v[198:201], v[72:75]
	v_mfma_f32_16x16x32_bf16 v[72:75], v[178:181], v[202:205], v[72:75]
	v_mfma_f32_16x16x32_bf16 v[64:67], v[170:173], v[206:209], v[64:67]
	v_mfma_f32_16x16x32_bf16 v[64:67], v[178:181], v[210:213], v[64:67]
	s_barrier
	s_setprio 0
	s_add_i32 s3, s3, s10
	s_mov_b32 m0, s3
	ds_read_b128 v[182:185], v143 offset:49152
	ds_read_b128 v[186:189], v143 offset:50176
	ds_read_b128 v[190:193], v143 offset:51200
	ds_read_b128 v[194:197], v143 offset:52224
	ds_read_b128 v[198:201], v143 offset:53248
	ds_read_b128 v[202:205], v143 offset:54272
	ds_read_b128 v[206:209], v143 offset:55296
	ds_read_b128 v[210:213], v143 offset:56320
	s_add_u32 s100, s88, s16
	s_addc_u32 s101, s89, s17
	global_load_lds_dwordx4 v130, s[100:101]
	s_add_i32 m0, s3, 0x2000
	s_add_u32 s88, s88, 0x80080
	v_lshl_add_u64 v[214:215], v[216:217], 0, s[16:17]
	s_addc_u32 s89, s89, 0
	s_add_i32 s3, s12, s10
	global_load_lds_dwordx4 v[214:215], off
	s_mov_b32 m0, s3
	s_nop 0
	global_load_lds_dwordx4 v130, s[88:89]
	s_add_i32 m0, s3, 0x2000
	s_nop 0
	global_load_lds_dwordx4 v134, s[88:89]
	v_lshl_add_u64 v[214:215], v[218:219], 0, s[16:17]
	s_mov_b32 m0, s22
	s_nop 0
	global_load_lds_dwordx4 v[214:215], off
	v_lshl_add_u64 v[214:215], v[220:221], 0, s[16:17]
	s_mov_b32 m0, s23
	s_nop 0
	global_load_lds_dwordx4 v[214:215], off
	s_waitcnt vmcnt(8)
	s_waitcnt lgkmcnt(0)
	s_setprio 1
	s_barrier
	v_mfma_f32_16x16x32_bf16 v[60:63], v[144:147], v[182:185], v[60:63]
	v_mfma_f32_16x16x32_bf16 v[60:63], v[148:151], v[186:189], v[60:63]
	v_mfma_f32_16x16x32_bf16 v[52:55], v[144:147], v[190:193], v[52:55]
	v_mfma_f32_16x16x32_bf16 v[52:55], v[148:151], v[194:197], v[52:55]
	v_mfma_f32_16x16x32_bf16 v[36:39], v[144:147], v[198:201], v[36:39]
	v_mfma_f32_16x16x32_bf16 v[36:39], v[148:151], v[202:205], v[36:39]
	v_mfma_f32_16x16x32_bf16 v[20:23], v[144:147], v[206:209], v[20:23]
	v_mfma_f32_16x16x32_bf16 v[20:23], v[148:151], v[210:213], v[20:23]
	v_mfma_f32_16x16x32_bf16 v[56:59], v[152:155], v[182:185], v[56:59]
	v_mfma_f32_16x16x32_bf16 v[56:59], v[156:159], v[186:189], v[56:59]
	v_mfma_f32_16x16x32_bf16 v[48:51], v[152:155], v[190:193], v[48:51]
	v_mfma_f32_16x16x32_bf16 v[48:51], v[156:159], v[194:197], v[48:51]
	v_mfma_f32_16x16x32_bf16 v[32:35], v[152:155], v[198:201], v[32:35]
	v_mfma_f32_16x16x32_bf16 v[32:35], v[156:159], v[202:205], v[32:35]
	v_mfma_f32_16x16x32_bf16 v[16:19], v[152:155], v[206:209], v[16:19]
	v_mfma_f32_16x16x32_bf16 v[16:19], v[156:159], v[210:213], v[16:19]
	v_mfma_f32_16x16x32_bf16 v[44:47], v[160:163], v[182:185], v[44:47]
	v_mfma_f32_16x16x32_bf16 v[44:47], v[164:167], v[186:189], v[44:47]
	v_mfma_f32_16x16x32_bf16 v[28:31], v[160:163], v[190:193], v[28:31]
	v_mfma_f32_16x16x32_bf16 v[28:31], v[164:167], v[194:197], v[28:31]
	v_mfma_f32_16x16x32_bf16 v[12:15], v[160:163], v[198:201], v[12:15]
	v_mfma_f32_16x16x32_bf16 v[12:15], v[164:167], v[202:205], v[12:15]
	v_mfma_f32_16x16x32_bf16 v[4:7], v[160:163], v[206:209], v[4:7]
	v_mfma_f32_16x16x32_bf16 v[4:7], v[164:167], v[210:213], v[4:7]
	v_mfma_f32_16x16x32_bf16 v[40:43], v[170:173], v[182:185], v[40:43]
	v_mfma_f32_16x16x32_bf16 v[40:43], v[178:181], v[186:189], v[40:43]
	v_mfma_f32_16x16x32_bf16 v[24:27], v[170:173], v[190:193], v[24:27]
	v_mfma_f32_16x16x32_bf16 v[24:27], v[178:181], v[194:197], v[24:27]
	v_mfma_f32_16x16x32_bf16 v[8:11], v[170:173], v[198:201], v[8:11]
	v_mfma_f32_16x16x32_bf16 v[8:11], v[178:181], v[202:205], v[8:11]
	v_mfma_f32_16x16x32_bf16 v[0:3], v[170:173], v[206:209], v[0:3]
	v_mfma_f32_16x16x32_bf16 v[0:3], v[178:181], v[210:213], v[0:3]
	s_barrier
	s_setprio 0
	s_add_i32 s2, s2, 2
	s_add_u32 s86, s86, 0x100
	s_addc_u32 s87, s87, 0
	s_add_u32 s42, s42, 0x100
	s_addc_u32 s43, s43, 0
	s_cmp_gt_u32 s2, 29
	s_cbranch_scc0 .LBB0_514
	s_and_b64 vcc, exec, s[74:75]
	s_cbranch_vccz .LBB0_517
	s_barrier

; #define PG8_STAGE(bufoff, gbase, voff) do { _Pragma("unroll") for (int _i = 0; _i < 2; ++_i) \
;         __builtin_amdgcn_global_load_lds((const unsigned*)((const char*)(gbase) + (voff)[_i]), (PG8_LAS unsigned*)(lds + (bufoff) + ldsw + _i * 8192), 16, 0, 0); } while (0)
; #define PG8_LDA(dst, b, h) do { _Pragma("unroll") for (int m = 0; m < 4; ++m) _Pragma("unroll") for (int k = 0; k < 2; ++k) dst[m][k] = *(const PG8_LAS bf16x8*)(lds + PG8_SA(b, h) + aoff + m * 2048 + k * 1024); } while (0)
; #define PG8_LDB(dst, b, h) do { _Pragma("unroll") for (int n = 0; n < 2; ++n) _Pragma("unroll") for (int k = 0; k < 2; ++k) dst[n][k] = *(const PG8_LAS bf16x8*)(lds + PG8_SB(b, h) + boff + n * 2048 + k * 1024); } while (0)
; #define PG8_MMA(ai, bj, At, Bt) do { __builtin_amdgcn_s_setprio(1); _Pragma("unroll") for (int m = 0; m < 4; ++m) _Pragma("unroll") for (int n = 0; n < 2; ++n) _Pragma("unroll") for (int k = 0; k < 2; ++k) \
;         acc[ai][bj][m][n] = __builtin_amdgcn_mfma_f32_16x16x32_bf16(Bt[n][k], At[m][k], acc[ai][bj][m][n], 0, 0, 0); __builtin_amdgcn_s_setprio(0); } while (0)
; #define PG8_WAIT_V(n) asm volatile("s_waitcnt vmcnt(" #n ")" ::: "memory")
; #define PG8_WAIT_L(n) asm volatile("s_waitcnt lgkmcnt(" #n ")" ::: "memory")
; #define PG8_BAR __builtin_amdgcn_s_barrier()
; #define PG8_SCHED __builtin_amdgcn_sched_barrier(0)
;     ...
;             const bool last = (t == nt - 2);
;             const char* a1 = PG8_KADV(cA, (size_t)(t + 1) * kstep);
;             const char* a2 = last ? nA : PG8_KADV(cA, (size_t)(t + 2) * kstep); const char* b2 = last ? nB : PG8_KADV(cB, (size_t)(t + 2) * kstep);
;             const char* a3 = PG8_KADV(a2, kstep); const char* b3 = PG8_KADV(b2, kstep);
;             if (last && has_next) S.a_ready(nxt);
;             if constexpr (SP2) {
;             PG8_LDB(B0, 0, 0); PG8_LDB(B1, 0, 1); PG8_SCHED; PG8_LDA(At, 0, 0); PG8_STAGE(PG8_SA(1, 1), a1 + hstep, voffA);
;             PG8_WAIT_V(8); PG8_WAIT_L(0); PG8_BAR; PG8_MMA(0, 0, At, B0); PG8_MMA(0, 1, At, B1); PG8_BAR; PG8_SCHED;
;             PG8_LDA(At, 0, 1); PG8_STAGE(PG8_SB(0, 0), b2, voffB); PG8_STAGE(PG8_SB(0, 1), b2 + hstep, voffB); PG8_STAGE(PG8_SA(0, 0), a2, voffA);
;             PG8_WAIT_V(8); PG8_WAIT_L(0); PG8_BAR; PG8_MMA(1, 0, At, B0); PG8_MMA(1, 1, At, B1); PG8_BAR; PG8_SCHED;
.LBB0_541:
	s_add_u32 s3, s88, 0xfff80080
	s_addc_u32 s12, s89, -1
	s_add_i32 s13, 0, 0x10000
	s_cmp_eq_u32 s2, 28
	s_cselect_b32 s93, s15, s12
	s_cselect_b32 s92, s30, s3
	v_add_u32_e32 v140, s13, v142
	s_cselect_b32 s91, s33, s43
	s_cselect_b32 s90, s40, s42
	s_add_i32 s3, 0, 0x14000
	ds_read_b128 v[146:149], v140
	ds_read_b128 v[150:153], v140 offset:1024
	ds_read_b128 v[154:157], v140 offset:2048
	ds_read_b128 v[158:161], v140 offset:3072
	v_add_u32_e32 v140, s3, v142
	ds_read_b128 v[162:165], v140
	ds_read_b128 v[170:173], v140 offset:1024
	ds_read_b128 v[178:181], v140 offset:2048
	ds_read_b128 v[182:185], v140 offset:3072
	s_add_i32 m0, s21, 0xc000
	ds_read_b128 v[186:189], v145
	ds_read_b128 v[190:193], v145 offset:1024
	ds_read_b128 v[194:197], v145 offset:2048
	ds_read_b128 v[198:201], v145 offset:3072
	ds_read_b128 v[202:205], v145 offset:4096
	ds_read_b128 v[206:209], v145 offset:5120
	ds_read_b128 v[210:213], v145 offset:6144
	ds_read_b128 v[214:217], v145 offset:7168
	global_load_lds_dwordx4 v136, s[88:89]
	s_add_i32 m0, s21, 0xe000
	s_nop 0
	global_load_lds_dwordx4 v138, s[88:89]
	s_waitcnt vmcnt(8)
	s_waitcnt lgkmcnt(0)
	s_setprio 1
	s_barrier
	v_mfma_f32_16x16x32_bf16 v[124:127], v[146:149], v[186:189], v[124:127]
	v_mfma_f32_16x16x32_bf16 v[124:127], v[150:153], v[190:193], v[124:127]
	v_mfma_f32_16x16x32_bf16 v[116:119], v[146:149], v[194:197], v[116:119]
	v_mfma_f32_16x16x32_bf16 v[116:119], v[150:153], v[198:201], v[116:119]
	v_mfma_f32_16x16x32_bf16 v[100:103], v[146:149], v[202:205], v[100:103]
	v_mfma_f32_16x16x32_bf16 v[100:103], v[150:153], v[206:209], v[100:103]
	v_mfma_f32_16x16x32_bf16 v[84:87], v[146:149], v[210:213], v[84:87]
	v_mfma_f32_16x16x32_bf16 v[84:87], v[150:153], v[214:217], v[84:87]
	v_mfma_f32_16x16x32_bf16 v[120:123], v[154:157], v[186:189], v[120:123]
	v_mfma_f32_16x16x32_bf16 v[120:123], v[158:161], v[190:193], v[120:123]
	v_mfma_f32_16x16x32_bf16 v[112:115], v[154:157], v[194:197], v[112:115]
	v_mfma_f32_16x16x32_bf16 v[112:115], v[158:161], v[198:201], v[112:115]
	v_mfma_f32_16x16x32_bf16 v[96:99], v[154:157], v[202:205], v[96:99]
	v_mfma_f32_16x16x32_bf16 v[96:99], v[158:161], v[206:209], v[96:99]
	v_mfma_f32_16x16x32_bf16 v[80:83], v[154:157], v[210:213], v[80:83]
	v_mfma_f32_16x16x32_bf16 v[80:83], v[158:161], v[214:217], v[80:83]
	v_mfma_f32_16x16x32_bf16 v[108:111], v[162:165], v[186:189], v[108:111]
	v_mfma_f32_16x16x32_bf16 v[108:111], v[170:173], v[190:193], v[108:111]
	v_mfma_f32_16x16x32_bf16 v[92:95], v[162:165], v[194:197], v[92:95]
	v_mfma_f32_16x16x32_bf16 v[92:95], v[170:173], v[198:201], v[92:95]
	v_mfma_f32_16x16x32_bf16 v[76:79], v[162:165], v[202:205], v[76:79]
	v_mfma_f32_16x16x32_bf16 v[76:79], v[170:173], v[206:209], v[76:79]
	v_mfma_f32_16x16x32_bf16 v[68:71], v[162:165], v[210:213], v[68:71]
	v_mfma_f32_16x16x32_bf16 v[68:71], v[170:173], v[214:217], v[68:71]
	v_mfma_f32_16x16x32_bf16 v[104:107], v[178:181], v[186:189], v[104:107]
	v_mfma_f32_16x16x32_bf16 v[104:107], v[182:185], v[190:193], v[104:107]
	v_mfma_f32_16x16x32_bf16 v[88:91], v[178:181], v[194:197], v[88:91]
	v_mfma_f32_16x16x32_bf16 v[88:91], v[182:185], v[198:201], v[88:91]
	v_mfma_f32_16x16x32_bf16 v[72:75], v[178:181], v[202:205], v[72:75]
	v_mfma_f32_16x16x32_bf16 v[72:75], v[182:185], v[206:209], v[72:75]
	v_mfma_f32_16x16x32_bf16 v[64:67], v[178:181], v[210:213], v[64:67]
	v_mfma_f32_16x16x32_bf16 v[64:67], v[182:185], v[214:217], v[64:67]
	s_barrier
	s_setprio 0
	s_add_i32 s12, s13, s20
	s_mov_b32 m0, s12
	ds_read_b128 v[186:189], v145 offset:16384
	ds_read_b128 v[190:193], v145 offset:17408
	ds_read_b128 v[194:197], v145 offset:18432
	ds_read_b128 v[198:201], v145 offset:19456
	ds_read_b128 v[202:205], v145 offset:20480
	ds_read_b128 v[206:209], v145 offset:21504
	ds_read_b128 v[210:213], v145 offset:22528
	ds_read_b128 v[214:217], v145 offset:23552
	global_load_lds_dwordx4 v132, s[90:91]
	s_add_i32 m0, s12, 0x2000
	s_add_u32 vcc_lo, s90, 0x80000
	v_lshl_add_u64 v[218:219], s[90:91], 0, v[128:129]
	s_addc_u32 vcc_hi, s91, 0
	s_add_i32 s3, s3, s20
	global_load_lds_dwordx4 v128, s[90:91]
	s_mov_b32 m0, s3
	v_lshl_add_u64 v[222:223], s[92:93], 0, v[130:131]
	global_load_lds_dwordx4 v132, vcc
	s_add_i32 m0, s3, 0x2000
	s_nop 0
	global_load_lds_dwordx4 v128, vcc
	v_lshl_add_u64 v[220:221], s[92:93], 0, v[134:135]
	s_mov_b32 m0, s21
	s_nop 0
	global_load_lds_dwordx4 v134, s[92:93]
	s_mov_b32 m0, s22
	s_nop 0
	global_load_lds_dwordx4 v130, s[92:93]
	s_waitcnt vmcnt(8)
	s_waitcnt lgkmcnt(0)
	s_setprio 1
	s_barrier
	v_mfma_f32_16x16x32_bf16 v[60:63], v[146:149], v[186:189], v[60:63]
	v_mfma_f32_16x16x32_bf16 v[60:63], v[150:153], v[190:193], v[60:63]
	v_mfma_f32_16x16x32_bf16 v[52:55], v[146:149], v[194:197], v[52:55]
	v_mfma_f32_16x16x32_bf16 v[52:55], v[150:153], v[198:201], v[52:55]
	v_mfma_f32_16x16x32_bf16 v[36:39], v[146:149], v[202:205], v[36:39]
	v_mfma_f32_16x16x32_bf16 v[36:39], v[150:153], v[206:209], v[36:39]
	v_mfma_f32_16x16x32_bf16 v[20:23], v[146:149], v[210:213], v[20:23]
	v_mfma_f32_16x16x32_bf16 v[20:23], v[150:153], v[214:217], v[20:23]
	v_mfma_f32_16x16x32_bf16 v[56:59], v[154:157], v[186:189], v[56:59]
	v_mfma_f32_16x16x32_bf16 v[56:59], v[158:161], v[190:193], v[56:59]
	v_mfma_f32_16x16x32_bf16 v[48:51], v[154:157], v[194:197], v[48:51]
	v_mfma_f32_16x16x32_bf16 v[48:51], v[158:161], v[198:201], v[48:51]
	v_mfma_f32_16x16x32_bf16 v[32:35], v[154:157], v[202:205], v[32:35]
	v_mfma_f32_16x16x32_bf16 v[32:35], v[158:161], v[206:209], v[32:35]
	v_mfma_f32_16x16x32_bf16 v[16:19], v[154:157], v[210:213], v[16:19]
	v_mfma_f32_16x16x32_bf16 v[16:19], v[158:161], v[214:217], v[16:19]
	v_mfma_f32_16x16x32_bf16 v[44:47], v[162:165], v[186:189], v[44:47]
	v_mfma_f32_16x16x32_bf16 v[44:47], v[170:173], v[190:193], v[44:47]
	v_mfma_f32_16x16x32_bf16 v[28:31], v[162:165], v[194:197], v[28:31]
	v_mfma_f32_16x16x32_bf16 v[28:31], v[170:173], v[198:201], v[28:31]
	v_mfma_f32_16x16x32_bf16 v[12:15], v[162:165], v[202:205], v[12:15]
	v_mfma_f32_16x16x32_bf16 v[12:15], v[170:173], v[206:209], v[12:15]
	v_mfma_f32_16x16x32_bf16 v[4:7], v[162:165], v[210:213], v[4:7]
	v_mfma_f32_16x16x32_bf16 v[4:7], v[170:173], v[214:217], v[4:7]
	v_mfma_f32_16x16x32_bf16 v[40:43], v[178:181], v[186:189], v[40:43]
	v_mfma_f32_16x16x32_bf16 v[40:43], v[182:185], v[190:193], v[40:43]
	v_mfma_f32_16x16x32_bf16 v[24:27], v[178:181], v[194:197], v[24:27]
	v_mfma_f32_16x16x32_bf16 v[24:27], v[182:185], v[198:201], v[24:27]
	v_mfma_f32_16x16x32_bf16 v[8:11], v[178:181], v[202:205], v[8:11]
	v_mfma_f32_16x16x32_bf16 v[8:11], v[182:185], v[206:209], v[8:11]
	v_mfma_f32_16x16x32_bf16 v[0:3], v[178:181], v[210:213], v[0:3]
	v_mfma_f32_16x16x32_bf16 v[0:3], v[182:185], v[214:217], v[0:3]
	s_barrier
; #define PG8_STAGE(bufoff, gbase, voff) do { _Pragma("unroll") for (int _i = 0; _i < 2; ++_i) \
;         __builtin_amdgcn_global_load_lds((const unsigned*)((const char*)(gbase) + (voff)[_i]), (PG8_LAS unsigned*)(lds + (bufoff) + ldsw + _i * 8192), 16, 0, 0); } while (0)
; #define PG8_LDA(dst, b, h) do { _Pragma("unroll") for (int m = 0; m < 4; ++m) _Pragma("unroll") for (int k = 0; k < 2; ++k) dst[m][k] = *(const PG8_LAS bf16x8*)(lds + PG8_SA(b, h) + aoff + m * 2048 + k * 1024); } while (0)
; #define PG8_LDB(dst, b, h) do { _Pragma("unroll") for (int n = 0; n < 2; ++n) _Pragma("unroll") for (int k = 0; k < 2; ++k) dst[n][k] = *(const PG8_LAS bf16x8*)(lds + PG8_SB(b, h) + boff + n * 2048 + k * 1024); } while (0)
; #define PG8_MMA(ai, bj, At, Bt) do { __builtin_amdgcn_s_setprio(1); _Pragma("unroll") for (int m = 0; m < 4; ++m) _Pragma("unroll") for (int n = 0; n < 2; ++n) _Pragma("unroll") for (int k = 0; k < 2; ++k) \
;         acc[ai][bj][m][n] = __builtin_amdgcn_mfma_f32_16x16x32_bf16(Bt[n][k], At[m][k], acc[ai][bj][m][n], 0, 0, 0); __builtin_amdgcn_s_setprio(0); } while (0)
; #define PG8_WAIT_V(n) asm volatile("s_waitcnt vmcnt(" #n ")" ::: "memory")
; #define PG8_WAIT_L(n) asm volatile("s_waitcnt lgkmcnt(" #n ")" ::: "memory")
; #define PG8_BAR __builtin_amdgcn_s_barrier()
; #define PG8_SCHED __builtin_amdgcn_sched_barrier(0)
;     ...
;             PG8_LDB(B0, 1, 0); PG8_LDB(B1, 1, 1); PG8_SCHED; PG8_LDA(At, 1, 0); PG8_STAGE(PG8_SA(0, 1), a2 + hstep, voffA);
;             PG8_WAIT_V(8); PG8_WAIT_L(0); PG8_BAR; PG8_MMA(0, 0, At, B0); PG8_MMA(0, 1, At, B1); PG8_BAR; PG8_SCHED;
;             PG8_LDA(At, 1, 1); PG8_STAGE(PG8_SB(1, 0), b3, voffB); PG8_STAGE(PG8_SB(1, 1), b3 + hstep, voffB); PG8_STAGE(PG8_SA(1, 0), a3, voffA);
;             PG8_WAIT_V(8); PG8_WAIT_L(0); PG8_BAR; PG8_MMA(1, 0, At, B0); PG8_MMA(1, 1, At, B1); PG8_BAR; PG8_SCHED;
	s_setprio 0
	s_add_i32 s3, 0, 0x18000
	v_add_u32_e32 v140, s3, v142
	s_add_i32 s12, 0, 0x1c000
	ds_read_b128 v[146:149], v140
	ds_read_b128 v[150:153], v140 offset:1024
	ds_read_b128 v[154:157], v140 offset:2048
	ds_read_b128 v[158:161], v140 offset:3072
	v_add_u32_e32 v140, s12, v142
	ds_read_b128 v[162:165], v140
	ds_read_b128 v[170:173], v140 offset:1024
	ds_read_b128 v[178:181], v140 offset:2048
	ds_read_b128 v[182:185], v140 offset:3072
	s_add_u32 s92, s92, 0x80000
	s_addc_u32 s93, s93, 0
	s_mov_b32 m0, s23
	ds_read_b128 v[186:189], v145 offset:32768
	ds_read_b128 v[190:193], v145 offset:33792
	ds_read_b128 v[194:197], v145 offset:34816
	ds_read_b128 v[198:201], v145 offset:35840
	ds_read_b128 v[202:205], v145 offset:36864
	ds_read_b128 v[206:209], v145 offset:37888
	ds_read_b128 v[210:213], v145 offset:38912
	ds_read_b128 v[214:217], v145 offset:39936
	global_load_lds_dwordx4 v134, s[92:93]
	s_mov_b32 m0, s57
	s_nop 0
	global_load_lds_dwordx4 v130, s[92:93]
	s_waitcnt vmcnt(8)
	s_waitcnt lgkmcnt(0)
	s_setprio 1
	s_barrier
	v_mfma_f32_16x16x32_bf16 v[124:127], v[146:149], v[186:189], v[124:127]
	v_mfma_f32_16x16x32_bf16 v[124:127], v[150:153], v[190:193], v[124:127]
	v_mfma_f32_16x16x32_bf16 v[116:119], v[146:149], v[194:197], v[116:119]
	v_mfma_f32_16x16x32_bf16 v[116:119], v[150:153], v[198:201], v[116:119]
	v_mfma_f32_16x16x32_bf16 v[100:103], v[146:149], v[202:205], v[100:103]
	v_mfma_f32_16x16x32_bf16 v[100:103], v[150:153], v[206:209], v[100:103]
	v_mfma_f32_16x16x32_bf16 v[84:87], v[146:149], v[210:213], v[84:87]
	v_mfma_f32_16x16x32_bf16 v[84:87], v[150:153], v[214:217], v[84:87]
	v_mfma_f32_16x16x32_bf16 v[120:123], v[154:157], v[186:189], v[120:123]
	v_mfma_f32_16x16x32_bf16 v[120:123], v[158:161], v[190:193], v[120:123]
	v_mfma_f32_16x16x32_bf16 v[112:115], v[154:157], v[194:197], v[112:115]
	v_mfma_f32_16x16x32_bf16 v[112:115], v[158:161], v[198:201], v[112:115]
	v_mfma_f32_16x16x32_bf16 v[96:99], v[154:157], v[202:205], v[96:99]
	v_mfma_f32_16x16x32_bf16 v[96:99], v[158:161], v[206:209], v[96:99]
	v_mfma_f32_16x16x32_bf16 v[80:83], v[154:157], v[210:213], v[80:83]
	v_mfma_f32_16x16x32_bf16 v[80:83], v[158:161], v[214:217], v[80:83]
	v_mfma_f32_16x16x32_bf16 v[108:111], v[162:165], v[186:189], v[108:111]
	v_mfma_f32_16x16x32_bf16 v[108:111], v[170:173], v[190:193], v[108:111]
	v_mfma_f32_16x16x32_bf16 v[92:95], v[162:165], v[194:197], v[92:95]
	v_mfma_f32_16x16x32_bf16 v[92:95], v[170:173], v[198:201], v[92:95]
	v_mfma_f32_16x16x32_bf16 v[76:79], v[162:165], v[202:205], v[76:79]
	v_mfma_f32_16x16x32_bf16 v[76:79], v[170:173], v[206:209], v[76:79]
	v_mfma_f32_16x16x32_bf16 v[68:71], v[162:165], v[210:213], v[68:71]
	v_mfma_f32_16x16x32_bf16 v[68:71], v[170:173], v[214:217], v[68:71]
	v_mfma_f32_16x16x32_bf16 v[104:107], v[178:181], v[186:189], v[104:107]
	v_mfma_f32_16x16x32_bf16 v[104:107], v[182:185], v[190:193], v[104:107]
	v_mfma_f32_16x16x32_bf16 v[88:91], v[178:181], v[194:197], v[88:91]
	v_mfma_f32_16x16x32_bf16 v[88:91], v[182:185], v[198:201], v[88:91]
	v_mfma_f32_16x16x32_bf16 v[72:75], v[178:181], v[202:205], v[72:75]
	v_mfma_f32_16x16x32_bf16 v[72:75], v[182:185], v[206:209], v[72:75]
	v_mfma_f32_16x16x32_bf16 v[64:67], v[178:181], v[210:213], v[64:67]
	v_mfma_f32_16x16x32_bf16 v[64:67], v[182:185], v[214:217], v[64:67]
	s_barrier
	s_setprio 0
	s_add_i32 s3, s3, s20
	s_mov_b32 m0, s3
	ds_read_b128 v[186:189], v145 offset:49152
	ds_read_b128 v[190:193], v145 offset:50176
	ds_read_b128 v[194:197], v145 offset:51200
	ds_read_b128 v[198:201], v145 offset:52224
	ds_read_b128 v[202:205], v145 offset:53248
	ds_read_b128 v[206:209], v145 offset:54272
	ds_read_b128 v[210:213], v145 offset:55296
	ds_read_b128 v[214:217], v145 offset:56320
	s_add_u32 s100, s90, s16
	s_addc_u32 s101, s91, s17
	global_load_lds_dwordx4 v132, s[100:101]
	s_add_i32 m0, s3, 0x2000
	s_add_u32 s90, s90, 0x80080
	v_lshl_add_u64 v[166:167], v[218:219], 0, s[16:17]
	s_addc_u32 s91, s91, 0
	s_add_i32 s3, s12, s20
	global_load_lds_dwordx4 v[166:167], off
	s_mov_b32 m0, s3
	s_nop 0
	global_load_lds_dwordx4 v132, s[90:91]
	s_add_i32 m0, s3, 0x2000
	s_nop 0
	global_load_lds_dwordx4 v128, s[90:91]
	v_lshl_add_u64 v[166:167], v[220:221], 0, s[16:17]
	s_mov_b32 m0, s59
	s_nop 0
	global_load_lds_dwordx4 v[166:167], off
	v_lshl_add_u64 v[166:167], v[222:223], 0, s[16:17]
	s_mov_b32 m0, s8
	s_nop 0
	global_load_lds_dwordx4 v[166:167], off
	s_waitcnt vmcnt(8)
	s_waitcnt lgkmcnt(0)
	s_setprio 1
	s_barrier
	v_mfma_f32_16x16x32_bf16 v[60:63], v[146:149], v[186:189], v[60:63]
	v_mfma_f32_16x16x32_bf16 v[60:63], v[150:153], v[190:193], v[60:63]
	v_mfma_f32_16x16x32_bf16 v[52:55], v[146:149], v[194:197], v[52:55]
	v_mfma_f32_16x16x32_bf16 v[52:55], v[150:153], v[198:201], v[52:55]
	v_mfma_f32_16x16x32_bf16 v[36:39], v[146:149], v[202:205], v[36:39]
	v_mfma_f32_16x16x32_bf16 v[36:39], v[150:153], v[206:209], v[36:39]
	v_mfma_f32_16x16x32_bf16 v[20:23], v[146:149], v[210:213], v[20:23]
	v_mfma_f32_16x16x32_bf16 v[20:23], v[150:153], v[214:217], v[20:23]
	v_mfma_f32_16x16x32_bf16 v[56:59], v[154:157], v[186:189], v[56:59]
	v_mfma_f32_16x16x32_bf16 v[56:59], v[158:161], v[190:193], v[56:59]
	v_mfma_f32_16x16x32_bf16 v[48:51], v[154:157], v[194:197], v[48:51]
	v_mfma_f32_16x16x32_bf16 v[48:51], v[158:161], v[198:201], v[48:51]
	v_mfma_f32_16x16x32_bf16 v[32:35], v[154:157], v[202:205], v[32:35]
	v_mfma_f32_16x16x32_bf16 v[32:35], v[158:161], v[206:209], v[32:35]
	v_mfma_f32_16x16x32_bf16 v[16:19], v[154:157], v[210:213], v[16:19]
	v_mfma_f32_16x16x32_bf16 v[16:19], v[158:161], v[214:217], v[16:19]
	v_mfma_f32_16x16x32_bf16 v[44:47], v[162:165], v[186:189], v[44:47]
	v_mfma_f32_16x16x32_bf16 v[44:47], v[170:173], v[190:193], v[44:47]
	v_mfma_f32_16x16x32_bf16 v[28:31], v[162:165], v[194:197], v[28:31]
	v_mfma_f32_16x16x32_bf16 v[28:31], v[170:173], v[198:201], v[28:31]
	v_mfma_f32_16x16x32_bf16 v[12:15], v[162:165], v[202:205], v[12:15]
	v_mfma_f32_16x16x32_bf16 v[12:15], v[170:173], v[206:209], v[12:15]
	v_mfma_f32_16x16x32_bf16 v[4:7], v[162:165], v[210:213], v[4:7]
	v_mfma_f32_16x16x32_bf16 v[4:7], v[170:173], v[214:217], v[4:7]
	v_mfma_f32_16x16x32_bf16 v[40:43], v[178:181], v[186:189], v[40:43]
	v_mfma_f32_16x16x32_bf16 v[40:43], v[182:185], v[190:193], v[40:43]
	v_mfma_f32_16x16x32_bf16 v[24:27], v[178:181], v[194:197], v[24:27]
	v_mfma_f32_16x16x32_bf16 v[24:27], v[182:185], v[198:201], v[24:27]
	v_mfma_f32_16x16x32_bf16 v[8:11], v[178:181], v[202:205], v[8:11]
	v_mfma_f32_16x16x32_bf16 v[8:11], v[182:185], v[206:209], v[8:11]
	v_mfma_f32_16x16x32_bf16 v[0:3], v[178:181], v[210:213], v[0:3]
	v_mfma_f32_16x16x32_bf16 v[0:3], v[182:185], v[214:217], v[0:3]
	s_barrier
	s_setprio 0
	s_add_i32 s2, s2, 2
	s_add_u32 s88, s88, 0x100
	s_addc_u32 s89, s89, 0
	s_add_u32 s42, s42, 0x100
	s_addc_u32 s43, s43, 0
	s_cmp_gt_u32 s2, 29
	s_cbranch_scc0 .LBB0_541
	s_and_b64 vcc, exec, s[76:77]
	s_cbranch_vccz .LBB0_544
	s_barrier

; #define PG8_STAGE(bufoff, gbase, voff) do { _Pragma("unroll") for (int _i = 0; _i < 2; ++_i) \
;         __builtin_amdgcn_global_load_lds((const unsigned*)((const char*)(gbase) + (voff)[_i]), (PG8_LAS unsigned*)(lds + (bufoff) + ldsw + _i * 8192), 16, 0, 0); } while (0)
; #define PG8_LDA(dst, b, h) do { _Pragma("unroll") for (int m = 0; m < 4; ++m) _Pragma("unroll") for (int k = 0; k < 2; ++k) dst[m][k] = *(const PG8_LAS bf16x8*)(lds + PG8_SA(b, h) + aoff + m * 2048 + k * 1024); } while (0)
; #define PG8_LDB(dst, b, h) do { _Pragma("unroll") for (int n = 0; n < 2; ++n) _Pragma("unroll") for (int k = 0; k < 2; ++k) dst[n][k] = *(const PG8_LAS bf16x8*)(lds + PG8_SB(b, h) + boff + n * 2048 + k * 1024); } while (0)
; #define PG8_MMA(ai, bj, At, Bt) do { __builtin_amdgcn_s_setprio(1); _Pragma("unroll") for (int m = 0; m < 4; ++m) _Pragma("unroll") for (int n = 0; n < 2; ++n) _Pragma("unroll") for (int k = 0; k < 2; ++k) \
;         acc[ai][bj][m][n] = __builtin_amdgcn_mfma_f32_16x16x32_bf16(Bt[n][k], At[m][k], acc[ai][bj][m][n], 0, 0, 0); __builtin_amdgcn_s_setprio(0); } while (0)
; #define PG8_WAIT_V(n) asm volatile("s_waitcnt vmcnt(" #n ")" ::: "memory")
; #define PG8_WAIT_L(n) asm volatile("s_waitcnt lgkmcnt(" #n ")" ::: "memory")
; #define PG8_BAR __builtin_amdgcn_s_barrier()
; #define PG8_SCHED __builtin_amdgcn_sched_barrier(0)
;     ...
;             const bool last = (t == nt - 2);
;             const char* a1 = PG8_KADV(cA, (size_t)(t + 1) * kstep);
;             const char* a2 = last ? nA : PG8_KADV(cA, (size_t)(t + 2) * kstep); const char* b2 = last ? nB : PG8_KADV(cB, (size_t)(t + 2) * kstep);
;             const char* a3 = PG8_KADV(a2, kstep); const char* b3 = PG8_KADV(b2, kstep);
;             if (last && has_next) S.a_ready(nxt);
;             if constexpr (SP2) {
;             PG8_LDB(B0, 0, 0); PG8_LDB(B1, 0, 1); PG8_SCHED; PG8_LDA(At, 0, 0); PG8_STAGE(PG8_SA(1, 1), a1 + hstep, voffA);
;             PG8_WAIT_V(8); PG8_WAIT_L(0); PG8_BAR; PG8_MMA(0, 0, At, B0); PG8_MMA(0, 1, At, B1); PG8_BAR; PG8_SCHED;
;             PG8_LDA(At, 0, 1); PG8_STAGE(PG8_SB(0, 0), b2, voffB); PG8_STAGE(PG8_SB(0, 1), b2 + hstep, voffB); PG8_STAGE(PG8_SA(0, 0), a2, voffA);
;             PG8_WAIT_V(8); PG8_WAIT_L(0); PG8_BAR; PG8_MMA(1, 0, At, B0); PG8_MMA(1, 1, At, B1); PG8_BAR; PG8_SCHED;
.LBB0_626:
	s_add_u32 s12, s86, 0xfffc0080
	s_addc_u32 s13, s87, -1
	s_add_i32 s96, 0, 0x10000
	s_cmp_eq_u32 s3, 12
	s_cselect_b32 s91, s75, s13
	s_cselect_b32 s90, s81, s12
	v_add_u32_e32 v143, s96, v140
	s_cselect_b32 s89, s79, s2
	s_cselect_b32 s88, vcc_lo, vcc_hi
	s_add_i32 s31, 0, 0x14000
	ds_read_b128 v[144:147], v143
	ds_read_b128 v[148:151], v143 offset:1024
	ds_read_b128 v[152:155], v143 offset:2048
	ds_read_b128 v[156:159], v143 offset:3072
	v_add_u32_e32 v143, s31, v140
	ds_read_b128 v[160:163], v143
	ds_read_b128 v[164:167], v143 offset:1024
	ds_read_b128 v[170:173], v143 offset:2048
	ds_read_b128 v[178:181], v143 offset:3072
	s_add_i32 m0, s97, 0xc000
	ds_read_b128 v[182:185], v142
	ds_read_b128 v[186:189], v142 offset:1024
	ds_read_b128 v[190:193], v142 offset:2048
	ds_read_b128 v[194:197], v142 offset:3072
	ds_read_b128 v[198:201], v142 offset:4096
	ds_read_b128 v[202:205], v142 offset:5120
	ds_read_b128 v[206:209], v142 offset:6144
	ds_read_b128 v[210:213], v142 offset:7168
	global_load_lds_dwordx4 v136, s[86:87]
	s_add_i32 m0, s97, 0xe000
	s_nop 0
	global_load_lds_dwordx4 v138, s[86:87]
	s_waitcnt vmcnt(8)
	s_waitcnt lgkmcnt(0)
	s_setprio 1
	s_barrier
	v_mfma_f32_16x16x32_bf16 v[124:127], v[144:147], v[182:185], v[124:127]
	v_mfma_f32_16x16x32_bf16 v[124:127], v[148:151], v[186:189], v[124:127]
	v_mfma_f32_16x16x32_bf16 v[116:119], v[144:147], v[190:193], v[116:119]
	v_mfma_f32_16x16x32_bf16 v[116:119], v[148:151], v[194:197], v[116:119]
	v_mfma_f32_16x16x32_bf16 v[100:103], v[144:147], v[198:201], v[100:103]
	v_mfma_f32_16x16x32_bf16 v[100:103], v[148:151], v[202:205], v[100:103]
	v_mfma_f32_16x16x32_bf16 v[84:87], v[144:147], v[206:209], v[84:87]
	v_mfma_f32_16x16x32_bf16 v[84:87], v[148:151], v[210:213], v[84:87]
	v_mfma_f32_16x16x32_bf16 v[120:123], v[152:155], v[182:185], v[120:123]
	v_mfma_f32_16x16x32_bf16 v[120:123], v[156:159], v[186:189], v[120:123]
	v_mfma_f32_16x16x32_bf16 v[112:115], v[152:155], v[190:193], v[112:115]
	v_mfma_f32_16x16x32_bf16 v[112:115], v[156:159], v[194:197], v[112:115]
	v_mfma_f32_16x16x32_bf16 v[96:99], v[152:155], v[198:201], v[96:99]
	v_mfma_f32_16x16x32_bf16 v[96:99], v[156:159], v[202:205], v[96:99]
	v_mfma_f32_16x16x32_bf16 v[80:83], v[152:155], v[206:209], v[80:83]
	v_mfma_f32_16x16x32_bf16 v[80:83], v[156:159], v[210:213], v[80:83]
	v_mfma_f32_16x16x32_bf16 v[108:111], v[160:163], v[182:185], v[108:111]
	v_mfma_f32_16x16x32_bf16 v[108:111], v[164:167], v[186:189], v[108:111]
	v_mfma_f32_16x16x32_bf16 v[92:95], v[160:163], v[190:193], v[92:95]
	v_mfma_f32_16x16x32_bf16 v[92:95], v[164:167], v[194:197], v[92:95]
	v_mfma_f32_16x16x32_bf16 v[76:79], v[160:163], v[198:201], v[76:79]
	v_mfma_f32_16x16x32_bf16 v[76:79], v[164:167], v[202:205], v[76:79]
	v_mfma_f32_16x16x32_bf16 v[68:71], v[160:163], v[206:209], v[68:71]
	v_mfma_f32_16x16x32_bf16 v[68:71], v[164:167], v[210:213], v[68:71]
	v_mfma_f32_16x16x32_bf16 v[104:107], v[170:173], v[182:185], v[104:107]
	v_mfma_f32_16x16x32_bf16 v[104:107], v[178:181], v[186:189], v[104:107]
	v_mfma_f32_16x16x32_bf16 v[88:91], v[170:173], v[190:193], v[88:91]
	v_mfma_f32_16x16x32_bf16 v[88:91], v[178:181], v[194:197], v[88:91]
	v_mfma_f32_16x16x32_bf16 v[72:75], v[170:173], v[198:201], v[72:75]
	v_mfma_f32_16x16x32_bf16 v[72:75], v[178:181], v[202:205], v[72:75]
	v_mfma_f32_16x16x32_bf16 v[64:67], v[170:173], v[206:209], v[64:67]
	v_mfma_f32_16x16x32_bf16 v[64:67], v[178:181], v[210:213], v[64:67]
	s_barrier
	s_setprio 0
	s_add_i32 s12, s96, s93
	s_mov_b32 m0, s12
	ds_read_b128 v[182:185], v142 offset:16384
	ds_read_b128 v[186:189], v142 offset:17408
	ds_read_b128 v[190:193], v142 offset:18432
	ds_read_b128 v[194:197], v142 offset:19456
	ds_read_b128 v[198:201], v142 offset:20480
	ds_read_b128 v[202:205], v142 offset:21504
	ds_read_b128 v[206:209], v142 offset:22528
	ds_read_b128 v[210:213], v142 offset:23552
	global_load_lds_dwordx4 v130, s[88:89]
	s_add_i32 m0, s12, 0x2000
	s_add_u32 s12, s88, 0x40000
	s_addc_u32 s13, s89, 0
	s_add_i32 s31, s31, s93
	global_load_lds_dwordx4 v134, s[88:89]
	s_mov_b32 m0, s31
	s_nop 0
	global_load_lds_dwordx4 v130, s[12:13]
	s_add_i32 m0, s31, 0x2000
	s_nop 0
	global_load_lds_dwordx4 v134, s[12:13]
	s_mov_b32 m0, s97
	s_nop 0
	global_load_lds_dwordx4 v128, s[90:91]
	s_mov_b32 m0, s40
	s_nop 0
	global_load_lds_dwordx4 v132, s[90:91]
	s_waitcnt vmcnt(8)
	s_waitcnt lgkmcnt(0)
	s_setprio 1
	s_barrier
	v_mfma_f32_16x16x32_bf16 v[60:63], v[144:147], v[182:185], v[60:63]
	v_mfma_f32_16x16x32_bf16 v[60:63], v[148:151], v[186:189], v[60:63]
	v_mfma_f32_16x16x32_bf16 v[52:55], v[144:147], v[190:193], v[52:55]
	v_mfma_f32_16x16x32_bf16 v[52:55], v[148:151], v[194:197], v[52:55]
	v_mfma_f32_16x16x32_bf16 v[36:39], v[144:147], v[198:201], v[36:39]
	v_mfma_f32_16x16x32_bf16 v[36:39], v[148:151], v[202:205], v[36:39]
	v_mfma_f32_16x16x32_bf16 v[20:23], v[144:147], v[206:209], v[20:23]
	v_mfma_f32_16x16x32_bf16 v[20:23], v[148:151], v[210:213], v[20:23]
	v_mfma_f32_16x16x32_bf16 v[56:59], v[152:155], v[182:185], v[56:59]
	v_mfma_f32_16x16x32_bf16 v[56:59], v[156:159], v[186:189], v[56:59]
	v_mfma_f32_16x16x32_bf16 v[48:51], v[152:155], v[190:193], v[48:51]
	v_mfma_f32_16x16x32_bf16 v[48:51], v[156:159], v[194:197], v[48:51]
	v_mfma_f32_16x16x32_bf16 v[32:35], v[152:155], v[198:201], v[32:35]
	v_mfma_f32_16x16x32_bf16 v[32:35], v[156:159], v[202:205], v[32:35]
	v_mfma_f32_16x16x32_bf16 v[16:19], v[152:155], v[206:209], v[16:19]
	v_mfma_f32_16x16x32_bf16 v[16:19], v[156:159], v[210:213], v[16:19]
	v_mfma_f32_16x16x32_bf16 v[44:47], v[160:163], v[182:185], v[44:47]
	v_mfma_f32_16x16x32_bf16 v[44:47], v[164:167], v[186:189], v[44:47]
	v_mfma_f32_16x16x32_bf16 v[28:31], v[160:163], v[190:193], v[28:31]
	v_mfma_f32_16x16x32_bf16 v[28:31], v[164:167], v[194:197], v[28:31]
	v_mfma_f32_16x16x32_bf16 v[12:15], v[160:163], v[198:201], v[12:15]
	v_mfma_f32_16x16x32_bf16 v[12:15], v[164:167], v[202:205], v[12:15]
	v_mfma_f32_16x16x32_bf16 v[4:7], v[160:163], v[206:209], v[4:7]
	v_mfma_f32_16x16x32_bf16 v[4:7], v[164:167], v[210:213], v[4:7]
	v_mfma_f32_16x16x32_bf16 v[40:43], v[170:173], v[182:185], v[40:43]
	v_mfma_f32_16x16x32_bf16 v[40:43], v[178:181], v[186:189], v[40:43]
	v_mfma_f32_16x16x32_bf16 v[24:27], v[170:173], v[190:193], v[24:27]
	v_mfma_f32_16x16x32_bf16 v[24:27], v[178:181], v[194:197], v[24:27]
	v_mfma_f32_16x16x32_bf16 v[8:11], v[170:173], v[198:201], v[8:11]
	v_mfma_f32_16x16x32_bf16 v[8:11], v[178:181], v[202:205], v[8:11]
	v_mfma_f32_16x16x32_bf16 v[0:3], v[170:173], v[206:209], v[0:3]
	v_mfma_f32_16x16x32_bf16 v[0:3], v[178:181], v[210:213], v[0:3]
	s_barrier
; #define PG8_STAGE(bufoff, gbase, voff) do { _Pragma("unroll") for (int _i = 0; _i < 2; ++_i) \
;         __builtin_amdgcn_global_load_lds((const unsigned*)((const char*)(gbase) + (voff)[_i]), (PG8_LAS unsigned*)(lds + (bufoff) + ldsw + _i * 8192), 16, 0, 0); } while (0)
; #define PG8_LDA(dst, b, h) do { _Pragma("unroll") for (int m = 0; m < 4; ++m) _Pragma("unroll") for (int k = 0; k < 2; ++k) dst[m][k] = *(const PG8_LAS bf16x8*)(lds + PG8_SA(b, h) + aoff + m * 2048 + k * 1024); } while (0)
; #define PG8_LDB(dst, b, h) do { _Pragma("unroll") for (int n = 0; n < 2; ++n) _Pragma("unroll") for (int k = 0; k < 2; ++k) dst[n][k] = *(const PG8_LAS bf16x8*)(lds + PG8_SB(b, h) + boff + n * 2048 + k * 1024); } while (0)
; #define PG8_MMA(ai, bj, At, Bt) do { __builtin_amdgcn_s_setprio(1); _Pragma("unroll") for (int m = 0; m < 4; ++m) _Pragma("unroll") for (int n = 0; n < 2; ++n) _Pragma("unroll") for (int k = 0; k < 2; ++k) \
;         acc[ai][bj][m][n] = __builtin_amdgcn_mfma_f32_16x16x32_bf16(Bt[n][k], At[m][k], acc[ai][bj][m][n], 0, 0, 0); __builtin_amdgcn_s_setprio(0); } while (0)
; #define PG8_WAIT_V(n) asm volatile("s_waitcnt vmcnt(" #n ")" ::: "memory")
; #define PG8_WAIT_L(n) asm volatile("s_waitcnt lgkmcnt(" #n ")" ::: "memory")
; #define PG8_BAR __builtin_amdgcn_s_barrier()
; #define PG8_SCHED __builtin_amdgcn_sched_barrier(0)
;     ...
;             PG8_LDB(B0, 1, 0); PG8_LDB(B1, 1, 1); PG8_SCHED; PG8_LDA(At, 1, 0); PG8_STAGE(PG8_SA(0, 1), a2 + hstep, voffA);
;             PG8_WAIT_V(8); PG8_WAIT_L(0); PG8_BAR; PG8_MMA(0, 0, At, B0); PG8_MMA(0, 1, At, B1); PG8_BAR; PG8_SCHED;
;             PG8_LDA(At, 1, 1); PG8_STAGE(PG8_SB(1, 0), b3, voffB); PG8_STAGE(PG8_SB(1, 1), b3 + hstep, voffB); PG8_STAGE(PG8_SA(1, 0), a3, voffA);
;             PG8_WAIT_V(8); PG8_WAIT_L(0); PG8_BAR; PG8_MMA(1, 0, At, B0); PG8_MMA(1, 1, At, B1); PG8_BAR; PG8_SCHED;
	s_setprio 0
	s_add_i32 s31, 0, 0x18000
	v_add_u32_e32 v143, s31, v140
	s_add_i32 s96, 0, 0x1c000
	ds_read_b128 v[144:147], v143
	ds_read_b128 v[148:151], v143 offset:1024
	ds_read_b128 v[152:155], v143 offset:2048
	ds_read_b128 v[156:159], v143 offset:3072
	v_add_u32_e32 v143, s96, v140
	ds_read_b128 v[160:163], v143
	ds_read_b128 v[164:167], v143 offset:1024
	ds_read_b128 v[170:173], v143 offset:2048
	ds_read_b128 v[178:181], v143 offset:3072
	s_add_u32 s12, s90, 0x40000
	s_addc_u32 s13, s91, 0
	s_mov_b32 m0, s33
	ds_read_b128 v[182:185], v142 offset:32768
	ds_read_b128 v[186:189], v142 offset:33792
	ds_read_b128 v[190:193], v142 offset:34816
	ds_read_b128 v[194:197], v142 offset:35840
	ds_read_b128 v[198:201], v142 offset:36864
	ds_read_b128 v[202:205], v142 offset:37888
	ds_read_b128 v[206:209], v142 offset:38912
	ds_read_b128 v[210:213], v142 offset:39936
	global_load_lds_dwordx4 v128, s[12:13]
	s_mov_b32 m0, s30
	s_nop 0
	global_load_lds_dwordx4 v132, s[12:13]
	s_waitcnt vmcnt(8)
	s_waitcnt lgkmcnt(0)
	s_setprio 1
	s_barrier
	v_mfma_f32_16x16x32_bf16 v[124:127], v[144:147], v[182:185], v[124:127]
	v_mfma_f32_16x16x32_bf16 v[124:127], v[148:151], v[186:189], v[124:127]
	v_mfma_f32_16x16x32_bf16 v[116:119], v[144:147], v[190:193], v[116:119]
	v_mfma_f32_16x16x32_bf16 v[116:119], v[148:151], v[194:197], v[116:119]
	v_mfma_f32_16x16x32_bf16 v[100:103], v[144:147], v[198:201], v[100:103]
	v_mfma_f32_16x16x32_bf16 v[100:103], v[148:151], v[202:205], v[100:103]
	v_mfma_f32_16x16x32_bf16 v[84:87], v[144:147], v[206:209], v[84:87]
	v_mfma_f32_16x16x32_bf16 v[84:87], v[148:151], v[210:213], v[84:87]
	v_mfma_f32_16x16x32_bf16 v[120:123], v[152:155], v[182:185], v[120:123]
	v_mfma_f32_16x16x32_bf16 v[120:123], v[156:159], v[186:189], v[120:123]
	v_mfma_f32_16x16x32_bf16 v[112:115], v[152:155], v[190:193], v[112:115]
	v_mfma_f32_16x16x32_bf16 v[112:115], v[156:159], v[194:197], v[112:115]
	v_mfma_f32_16x16x32_bf16 v[96:99], v[152:155], v[198:201], v[96:99]
	v_mfma_f32_16x16x32_bf16 v[96:99], v[156:159], v[202:205], v[96:99]
	v_mfma_f32_16x16x32_bf16 v[80:83], v[152:155], v[206:209], v[80:83]
	v_mfma_f32_16x16x32_bf16 v[80:83], v[156:159], v[210:213], v[80:83]
	v_mfma_f32_16x16x32_bf16 v[108:111], v[160:163], v[182:185], v[108:111]
	v_mfma_f32_16x16x32_bf16 v[108:111], v[164:167], v[186:189], v[108:111]
	v_mfma_f32_16x16x32_bf16 v[92:95], v[160:163], v[190:193], v[92:95]
	v_mfma_f32_16x16x32_bf16 v[92:95], v[164:167], v[194:197], v[92:95]
	v_mfma_f32_16x16x32_bf16 v[76:79], v[160:163], v[198:201], v[76:79]
	v_mfma_f32_16x16x32_bf16 v[76:79], v[164:167], v[202:205], v[76:79]
	v_mfma_f32_16x16x32_bf16 v[68:71], v[160:163], v[206:209], v[68:71]
	v_mfma_f32_16x16x32_bf16 v[68:71], v[164:167], v[210:213], v[68:71]
	v_mfma_f32_16x16x32_bf16 v[104:107], v[170:173], v[182:185], v[104:107]
	v_mfma_f32_16x16x32_bf16 v[104:107], v[178:181], v[186:189], v[104:107]
	v_mfma_f32_16x16x32_bf16 v[88:91], v[170:173], v[190:193], v[88:91]
	v_mfma_f32_16x16x32_bf16 v[88:91], v[178:181], v[194:197], v[88:91]
	v_mfma_f32_16x16x32_bf16 v[72:75], v[170:173], v[198:201], v[72:75]
	v_mfma_f32_16x16x32_bf16 v[72:75], v[178:181], v[202:205], v[72:75]
	v_mfma_f32_16x16x32_bf16 v[64:67], v[170:173], v[206:209], v[64:67]
	v_mfma_f32_16x16x32_bf16 v[64:67], v[178:181], v[210:213], v[64:67]
	s_barrier
	s_setprio 0
	s_add_i32 s12, s31, s93
	s_mov_b32 m0, s12
	ds_read_b128 v[182:185], v142 offset:49152
	ds_read_b128 v[186:189], v142 offset:50176
	ds_read_b128 v[190:193], v142 offset:51200
	ds_read_b128 v[194:197], v142 offset:52224
	ds_read_b128 v[198:201], v142 offset:53248
	ds_read_b128 v[202:205], v142 offset:54272
	ds_read_b128 v[206:209], v142 offset:55296
	ds_read_b128 v[210:213], v142 offset:56320
	s_add_u32 s100, s88, s16
	s_addc_u32 s101, s89, s17
	global_load_lds_dwordx4 v130, s[100:101]
	s_add_i32 m0, s12, 0x2000
	s_add_u32 s12, s88, 0x40080
	s_addc_u32 s13, s89, 0
	s_add_i32 s31, s96, s93
	global_load_lds_dwordx4 v134, s[100:101]
	s_mov_b32 m0, s31
	s_nop 0
	global_load_lds_dwordx4 v130, s[12:13]
	s_add_i32 m0, s31, 0x2000
	s_nop 0
	global_load_lds_dwordx4 v134, s[12:13]
	s_mov_b32 m0, s14
	s_nop 0
	s_add_u32 s100, s90, s16
	s_addc_u32 s101, s91, s17
	global_load_lds_dwordx4 v128, s[100:101]
	s_mov_b32 m0, s15
	s_nop 0
	global_load_lds_dwordx4 v132, s[100:101]
	s_waitcnt vmcnt(8)
	s_waitcnt lgkmcnt(0)
	s_setprio 1
	s_barrier
	v_mfma_f32_16x16x32_bf16 v[60:63], v[144:147], v[182:185], v[60:63]
	v_mfma_f32_16x16x32_bf16 v[60:63], v[148:151], v[186:189], v[60:63]
	v_mfma_f32_16x16x32_bf16 v[52:55], v[144:147], v[190:193], v[52:55]
	v_mfma_f32_16x16x32_bf16 v[52:55], v[148:151], v[194:197], v[52:55]
	v_mfma_f32_16x16x32_bf16 v[36:39], v[144:147], v[198:201], v[36:39]
	v_mfma_f32_16x16x32_bf16 v[36:39], v[148:151], v[202:205], v[36:39]
	v_mfma_f32_16x16x32_bf16 v[20:23], v[144:147], v[206:209], v[20:23]
	v_mfma_f32_16x16x32_bf16 v[20:23], v[148:151], v[210:213], v[20:23]
	v_mfma_f32_16x16x32_bf16 v[56:59], v[152:155], v[182:185], v[56:59]
	v_mfma_f32_16x16x32_bf16 v[56:59], v[156:159], v[186:189], v[56:59]
	v_mfma_f32_16x16x32_bf16 v[48:51], v[152:155], v[190:193], v[48:51]
	v_mfma_f32_16x16x32_bf16 v[48:51], v[156:159], v[194:197], v[48:51]
	v_mfma_f32_16x16x32_bf16 v[32:35], v[152:155], v[198:201], v[32:35]
	v_mfma_f32_16x16x32_bf16 v[32:35], v[156:159], v[202:205], v[32:35]
	v_mfma_f32_16x16x32_bf16 v[16:19], v[152:155], v[206:209], v[16:19]
	v_mfma_f32_16x16x32_bf16 v[16:19], v[156:159], v[210:213], v[16:19]
	v_mfma_f32_16x16x32_bf16 v[44:47], v[160:163], v[182:185], v[44:47]
	v_mfma_f32_16x16x32_bf16 v[44:47], v[164:167], v[186:189], v[44:47]
	v_mfma_f32_16x16x32_bf16 v[28:31], v[160:163], v[190:193], v[28:31]
	v_mfma_f32_16x16x32_bf16 v[28:31], v[164:167], v[194:197], v[28:31]
	v_mfma_f32_16x16x32_bf16 v[12:15], v[160:163], v[198:201], v[12:15]
	v_mfma_f32_16x16x32_bf16 v[12:15], v[164:167], v[202:205], v[12:15]
	v_mfma_f32_16x16x32_bf16 v[4:7], v[160:163], v[206:209], v[4:7]
	v_mfma_f32_16x16x32_bf16 v[4:7], v[164:167], v[210:213], v[4:7]
	v_mfma_f32_16x16x32_bf16 v[40:43], v[170:173], v[182:185], v[40:43]
	v_mfma_f32_16x16x32_bf16 v[40:43], v[178:181], v[186:189], v[40:43]
	v_mfma_f32_16x16x32_bf16 v[24:27], v[170:173], v[190:193], v[24:27]
	v_mfma_f32_16x16x32_bf16 v[24:27], v[178:181], v[194:197], v[24:27]
	v_mfma_f32_16x16x32_bf16 v[8:11], v[170:173], v[198:201], v[8:11]
	v_mfma_f32_16x16x32_bf16 v[8:11], v[178:181], v[202:205], v[8:11]
	v_mfma_f32_16x16x32_bf16 v[0:3], v[170:173], v[206:209], v[0:3]
	v_mfma_f32_16x16x32_bf16 v[0:3], v[178:181], v[210:213], v[0:3]
	s_barrier
	s_setprio 0
	s_add_i32 s3, s3, 2
	s_add_u32 s86, s86, 0x100
	s_addc_u32 s87, s87, 0
	s_add_u32 vcc_hi, vcc_hi, 0x100
	s_addc_u32 s2, s2, 0
	s_cmp_gt_u32 s3, 13
	s_cbranch_scc0 .LBB0_626
	s_and_b64 vcc, exec, s[72:73]
	s_cbranch_vccz .LBB0_629
	s_barrier

; #define PG8_STAGE(bufoff, gbase, voff) do { _Pragma("unroll") for (int _i = 0; _i < 2; ++_i) \
;         __builtin_amdgcn_global_load_lds((const unsigned*)((const char*)(gbase) + (voff)[_i]), (PG8_LAS unsigned*)(lds + (bufoff) + ldsw + _i * 8192), 16, 0, 0); } while (0)
; #define PG8_LDA(dst, b, h) do { _Pragma("unroll") for (int m = 0; m < 4; ++m) _Pragma("unroll") for (int k = 0; k < 2; ++k) dst[m][k] = *(const PG8_LAS bf16x8*)(lds + PG8_SA(b, h) + aoff + m * 2048 + k * 1024); } while (0)
; #define PG8_LDB(dst, b, h) do { _Pragma("unroll") for (int n = 0; n < 2; ++n) _Pragma("unroll") for (int k = 0; k < 2; ++k) dst[n][k] = *(const PG8_LAS bf16x8*)(lds + PG8_SB(b, h) + boff + n * 2048 + k * 1024); } while (0)
; #define PG8_MMA(ai, bj, At, Bt) do { __builtin_amdgcn_s_setprio(1); _Pragma("unroll") for (int m = 0; m < 4; ++m) _Pragma("unroll") for (int n = 0; n < 2; ++n) _Pragma("unroll") for (int k = 0; k < 2; ++k) \
;         acc[ai][bj][m][n] = __builtin_amdgcn_mfma_f32_16x16x32_bf16(Bt[n][k], At[m][k], acc[ai][bj][m][n], 0, 0, 0); __builtin_amdgcn_s_setprio(0); } while (0)
; #define PG8_WAIT_V(n) asm volatile("s_waitcnt vmcnt(" #n ")" ::: "memory")
; #define PG8_WAIT_L(n) asm volatile("s_waitcnt lgkmcnt(" #n ")" ::: "memory")
; #define PG8_BAR __builtin_amdgcn_s_barrier()
; #define PG8_SCHED __builtin_amdgcn_sched_barrier(0)
;     ...
;             const bool last = (t == nt - 2);
;             const char* a1 = PG8_KADV(cA, (size_t)(t + 1) * kstep);
;             const char* a2 = last ? nA : PG8_KADV(cA, (size_t)(t + 2) * kstep); const char* b2 = last ? nB : PG8_KADV(cB, (size_t)(t + 2) * kstep);
;             const char* a3 = PG8_KADV(a2, kstep); const char* b3 = PG8_KADV(b2, kstep);
;             if (last && has_next) S.a_ready(nxt);
;             if constexpr (SP2) {
;             PG8_LDB(B0, 0, 0); PG8_LDB(B1, 0, 1); PG8_SCHED; PG8_LDA(At, 0, 0); PG8_STAGE(PG8_SA(1, 1), a1 + hstep, voffA);
;             PG8_WAIT_V(8); PG8_WAIT_L(0); PG8_BAR; PG8_MMA(0, 0, At, B0); PG8_MMA(0, 1, At, B1); PG8_BAR; PG8_SCHED;
;             PG8_LDA(At, 0, 1); PG8_STAGE(PG8_SB(0, 0), b2, voffB); PG8_STAGE(PG8_SB(0, 1), b2 + hstep, voffB); PG8_STAGE(PG8_SA(0, 0), a2, voffA);
;             PG8_WAIT_V(8); PG8_WAIT_L(0); PG8_BAR; PG8_MMA(1, 0, At, B0); PG8_MMA(1, 1, At, B1); PG8_BAR; PG8_SCHED;
.LBB0_856:
	s_add_u32 s12, s82, 0xfff80080
	s_addc_u32 s13, s83, -1
	s_add_i32 s31, 0, 0x10000
	s_cmp_eq_u32 s3, 28
	s_cselect_b32 s87, s15, s13
	s_cselect_b32 s86, s23, s12
	s_cselect_b32 s85, s25, s2
	s_cselect_b32 s84, s28, s30
	s_add_i32 s33, 0, 0x14000
	v_add_u32_e32 v140, s31, v166
	v_add_u32_e32 v164, s33, v166
	ds_read_b128 v[128:131], v140
	ds_read_b128 v[132:135], v140 offset:1024
	ds_read_b128 v[136:139], v140 offset:2048
	ds_read_b128 v[140:143], v140 offset:3072
	ds_read_b128 v[144:147], v164
	ds_read_b128 v[148:151], v164 offset:1024
	ds_read_b128 v[170:173], v164 offset:2048
	ds_read_b128 v[178:181], v164 offset:3072
	s_add_i32 m0, s9, 0xc000
	ds_read_b128 v[184:187], v183
	ds_read_b128 v[188:191], v183 offset:1024
	ds_read_b128 v[192:195], v183 offset:2048
	ds_read_b128 v[196:199], v183 offset:3072
	ds_read_b128 v[200:203], v183 offset:4096
	ds_read_b128 v[204:207], v183 offset:5120
	ds_read_b128 v[208:211], v183 offset:6144
	ds_read_b128 v[212:215], v183 offset:7168
	global_load_lds_dwordx4 v160, s[82:83]
	s_add_i32 m0, s9, 0xe000
	s_nop 0
	global_load_lds_dwordx4 v162, s[82:83]
	s_waitcnt vmcnt(8)
	s_waitcnt lgkmcnt(0)
	s_setprio 1
	s_barrier
	v_mfma_f32_16x16x32_bf16 v[124:127], v[128:131], v[184:187], v[124:127]
	v_mfma_f32_16x16x32_bf16 v[124:127], v[132:135], v[188:191], v[124:127]
	v_mfma_f32_16x16x32_bf16 v[112:115], v[128:131], v[192:195], v[112:115]
	v_mfma_f32_16x16x32_bf16 v[112:115], v[132:135], v[196:199], v[112:115]
	v_mfma_f32_16x16x32_bf16 v[92:95], v[128:131], v[200:203], v[92:95]
	v_mfma_f32_16x16x32_bf16 v[92:95], v[132:135], v[204:207], v[92:95]
	v_mfma_f32_16x16x32_bf16 v[80:83], v[128:131], v[208:211], v[80:83]
	v_mfma_f32_16x16x32_bf16 v[80:83], v[132:135], v[212:215], v[80:83]
	v_mfma_f32_16x16x32_bf16 v[120:123], v[136:139], v[184:187], v[120:123]
	v_mfma_f32_16x16x32_bf16 v[120:123], v[140:143], v[188:191], v[120:123]
	v_mfma_f32_16x16x32_bf16 v[104:107], v[136:139], v[192:195], v[104:107]
	v_mfma_f32_16x16x32_bf16 v[104:107], v[140:143], v[196:199], v[104:107]
	v_mfma_f32_16x16x32_bf16 v[88:91], v[136:139], v[200:203], v[88:91]
	v_mfma_f32_16x16x32_bf16 v[88:91], v[140:143], v[204:207], v[88:91]
	v_mfma_f32_16x16x32_bf16 v[72:75], v[136:139], v[208:211], v[72:75]
	v_mfma_f32_16x16x32_bf16 v[72:75], v[140:143], v[212:215], v[72:75]
	v_mfma_f32_16x16x32_bf16 v[116:119], v[144:147], v[184:187], v[116:119]
	v_mfma_f32_16x16x32_bf16 v[116:119], v[148:151], v[188:191], v[116:119]
	v_mfma_f32_16x16x32_bf16 v[100:103], v[144:147], v[192:195], v[100:103]
	v_mfma_f32_16x16x32_bf16 v[100:103], v[148:151], v[196:199], v[100:103]
	v_mfma_f32_16x16x32_bf16 v[84:87], v[144:147], v[200:203], v[84:87]
	v_mfma_f32_16x16x32_bf16 v[84:87], v[148:151], v[204:207], v[84:87]
	v_mfma_f32_16x16x32_bf16 v[68:71], v[144:147], v[208:211], v[68:71]
	v_mfma_f32_16x16x32_bf16 v[68:71], v[148:151], v[212:215], v[68:71]
	v_mfma_f32_16x16x32_bf16 v[108:111], v[170:173], v[184:187], v[108:111]
	v_mfma_f32_16x16x32_bf16 v[108:111], v[178:181], v[188:191], v[108:111]
	v_mfma_f32_16x16x32_bf16 v[96:99], v[170:173], v[192:195], v[96:99]
	v_mfma_f32_16x16x32_bf16 v[96:99], v[178:181], v[196:199], v[96:99]
	v_mfma_f32_16x16x32_bf16 v[76:79], v[170:173], v[200:203], v[76:79]
	v_mfma_f32_16x16x32_bf16 v[76:79], v[178:181], v[204:207], v[76:79]
	v_mfma_f32_16x16x32_bf16 v[64:67], v[170:173], v[208:211], v[64:67]
	v_mfma_f32_16x16x32_bf16 v[64:67], v[178:181], v[212:215], v[64:67]
	s_barrier
	s_setprio 0
	s_add_i32 s12, s31, s8
	s_mov_b32 m0, s12
	ds_read_b128 v[184:187], v183 offset:16384
	ds_read_b128 v[188:191], v183 offset:17408
	ds_read_b128 v[192:195], v183 offset:18432
	ds_read_b128 v[196:199], v183 offset:19456
	ds_read_b128 v[200:203], v183 offset:20480
	ds_read_b128 v[204:207], v183 offset:21504
	ds_read_b128 v[208:211], v183 offset:22528
	ds_read_b128 v[212:215], v183 offset:23552
	global_load_lds_dwordx4 v154, s[84:85]
	s_add_i32 m0, s12, 0x2000
	s_add_u32 s12, s84, 0x80000
	s_addc_u32 s13, s85, 0
	s_add_i32 s31, s33, s8
	global_load_lds_dwordx4 v158, s[84:85]
	s_mov_b32 m0, s31
	s_nop 0
	global_load_lds_dwordx4 v154, s[12:13]
	s_add_i32 m0, s31, 0x2000
	s_nop 0
	global_load_lds_dwordx4 v158, s[12:13]
	s_mov_b32 m0, s9
	s_nop 0
	global_load_lds_dwordx4 v152, s[86:87]
	s_mov_b32 m0, s10
	s_nop 0
	global_load_lds_dwordx4 v156, s[86:87]
	s_waitcnt vmcnt(8)
	s_waitcnt lgkmcnt(0)
	s_setprio 1
	s_barrier
	v_mfma_f32_16x16x32_bf16 v[60:63], v[128:131], v[184:187], v[60:63]
	v_mfma_f32_16x16x32_bf16 v[60:63], v[132:135], v[188:191], v[60:63]
	v_mfma_f32_16x16x32_bf16 v[48:51], v[128:131], v[192:195], v[48:51]
	v_mfma_f32_16x16x32_bf16 v[48:51], v[132:135], v[196:199], v[48:51]
	v_mfma_f32_16x16x32_bf16 v[28:31], v[128:131], v[200:203], v[28:31]
	v_mfma_f32_16x16x32_bf16 v[28:31], v[132:135], v[204:207], v[28:31]
	v_mfma_f32_16x16x32_bf16 v[16:19], v[128:131], v[208:211], v[16:19]
	v_mfma_f32_16x16x32_bf16 v[16:19], v[132:135], v[212:215], v[16:19]
	v_mfma_f32_16x16x32_bf16 v[56:59], v[136:139], v[184:187], v[56:59]
	v_mfma_f32_16x16x32_bf16 v[56:59], v[140:143], v[188:191], v[56:59]
	v_mfma_f32_16x16x32_bf16 v[40:43], v[136:139], v[192:195], v[40:43]
	v_mfma_f32_16x16x32_bf16 v[40:43], v[140:143], v[196:199], v[40:43]
	v_mfma_f32_16x16x32_bf16 v[24:27], v[136:139], v[200:203], v[24:27]
	v_mfma_f32_16x16x32_bf16 v[24:27], v[140:143], v[204:207], v[24:27]
	v_mfma_f32_16x16x32_bf16 v[8:11], v[136:139], v[208:211], v[8:11]
	v_mfma_f32_16x16x32_bf16 v[8:11], v[140:143], v[212:215], v[8:11]
	v_mfma_f32_16x16x32_bf16 v[52:55], v[144:147], v[184:187], v[52:55]
	v_mfma_f32_16x16x32_bf16 v[52:55], v[148:151], v[188:191], v[52:55]
	v_mfma_f32_16x16x32_bf16 v[36:39], v[144:147], v[192:195], v[36:39]
	v_mfma_f32_16x16x32_bf16 v[36:39], v[148:151], v[196:199], v[36:39]
	v_mfma_f32_16x16x32_bf16 v[20:23], v[144:147], v[200:203], v[20:23]
	v_mfma_f32_16x16x32_bf16 v[20:23], v[148:151], v[204:207], v[20:23]
	v_mfma_f32_16x16x32_bf16 v[4:7], v[144:147], v[208:211], v[4:7]
	v_mfma_f32_16x16x32_bf16 v[4:7], v[148:151], v[212:215], v[4:7]
	v_mfma_f32_16x16x32_bf16 v[44:47], v[170:173], v[184:187], v[44:47]
	v_mfma_f32_16x16x32_bf16 v[44:47], v[178:181], v[188:191], v[44:47]
	v_mfma_f32_16x16x32_bf16 v[32:35], v[170:173], v[192:195], v[32:35]
	v_mfma_f32_16x16x32_bf16 v[32:35], v[178:181], v[196:199], v[32:35]
	v_mfma_f32_16x16x32_bf16 v[12:15], v[170:173], v[200:203], v[12:15]
	v_mfma_f32_16x16x32_bf16 v[12:15], v[178:181], v[204:207], v[12:15]
	v_mfma_f32_16x16x32_bf16 v[0:3], v[170:173], v[208:211], v[0:3]
	v_mfma_f32_16x16x32_bf16 v[0:3], v[178:181], v[212:215], v[0:3]
	s_barrier
; #define PG8_STAGE(bufoff, gbase, voff) do { _Pragma("unroll") for (int _i = 0; _i < 2; ++_i) \
;         __builtin_amdgcn_global_load_lds((const unsigned*)((const char*)(gbase) + (voff)[_i]), (PG8_LAS unsigned*)(lds + (bufoff) + ldsw + _i * 8192), 16, 0, 0); } while (0)
; #define PG8_LDA(dst, b, h) do { _Pragma("unroll") for (int m = 0; m < 4; ++m) _Pragma("unroll") for (int k = 0; k < 2; ++k) dst[m][k] = *(const PG8_LAS bf16x8*)(lds + PG8_SA(b, h) + aoff + m * 2048 + k * 1024); } while (0)
; #define PG8_LDB(dst, b, h) do { _Pragma("unroll") for (int n = 0; n < 2; ++n) _Pragma("unroll") for (int k = 0; k < 2; ++k) dst[n][k] = *(const PG8_LAS bf16x8*)(lds + PG8_SB(b, h) + boff + n * 2048 + k * 1024); } while (0)
; #define PG8_MMA(ai, bj, At, Bt) do { __builtin_amdgcn_s_setprio(1); _Pragma("unroll") for (int m = 0; m < 4; ++m) _Pragma("unroll") for (int n = 0; n < 2; ++n) _Pragma("unroll") for (int k = 0; k < 2; ++k) \
;         acc[ai][bj][m][n] = __builtin_amdgcn_mfma_f32_16x16x32_bf16(Bt[n][k], At[m][k], acc[ai][bj][m][n], 0, 0, 0); __builtin_amdgcn_s_setprio(0); } while (0)
; #define PG8_WAIT_V(n) asm volatile("s_waitcnt vmcnt(" #n ")" ::: "memory")
; #define PG8_WAIT_L(n) asm volatile("s_waitcnt lgkmcnt(" #n ")" ::: "memory")
; #define PG8_BAR __builtin_amdgcn_s_barrier()
; #define PG8_SCHED __builtin_amdgcn_sched_barrier(0)
;     ...
;             PG8_LDB(B0, 1, 0); PG8_LDB(B1, 1, 1); PG8_SCHED; PG8_LDA(At, 1, 0); PG8_STAGE(PG8_SA(0, 1), a2 + hstep, voffA);
;             PG8_WAIT_V(8); PG8_WAIT_L(0); PG8_BAR; PG8_MMA(0, 0, At, B0); PG8_MMA(0, 1, At, B1); PG8_BAR; PG8_SCHED;
;             PG8_LDA(At, 1, 1); PG8_STAGE(PG8_SB(1, 0), b3, voffB); PG8_STAGE(PG8_SB(1, 1), b3 + hstep, voffB); PG8_STAGE(PG8_SA(1, 0), a3, voffA);
;             PG8_WAIT_V(8); PG8_WAIT_L(0); PG8_BAR; PG8_MMA(1, 0, At, B0); PG8_MMA(1, 1, At, B1); PG8_BAR; PG8_SCHED;
	s_setprio 0
	s_add_i32 s31, 0, 0x18000
	s_add_i32 s33, 0, 0x1c000
	v_add_u32_e32 v140, s31, v166
	v_add_u32_e32 v168, s33, v166
	ds_read_b128 v[128:131], v140
	ds_read_b128 v[132:135], v140 offset:1024
	ds_read_b128 v[136:139], v140 offset:2048
	ds_read_b128 v[140:143], v140 offset:3072
	ds_read_b128 v[144:147], v168
	ds_read_b128 v[148:151], v168 offset:1024
	ds_read_b128 v[170:173], v168 offset:2048
	ds_read_b128 v[178:181], v168 offset:3072
	s_add_u32 s12, s86, 0x80000
	s_addc_u32 s13, s87, 0
	s_mov_b32 m0, s18
	ds_read_b128 v[184:187], v183 offset:32768
	ds_read_b128 v[188:191], v183 offset:33792
	ds_read_b128 v[192:195], v183 offset:34816
	ds_read_b128 v[196:199], v183 offset:35840
	ds_read_b128 v[200:203], v183 offset:36864
	ds_read_b128 v[204:207], v183 offset:37888
	ds_read_b128 v[208:211], v183 offset:38912
	ds_read_b128 v[212:215], v183 offset:39936
	global_load_lds_dwordx4 v152, s[12:13]
	s_mov_b32 m0, s19
	s_nop 0
	global_load_lds_dwordx4 v156, s[12:13]
	s_waitcnt vmcnt(8)
	s_waitcnt lgkmcnt(0)
	s_setprio 1
	s_barrier
	v_mfma_f32_16x16x32_bf16 v[124:127], v[128:131], v[184:187], v[124:127]
	v_mfma_f32_16x16x32_bf16 v[124:127], v[132:135], v[188:191], v[124:127]
	v_mfma_f32_16x16x32_bf16 v[112:115], v[128:131], v[192:195], v[112:115]
	v_mfma_f32_16x16x32_bf16 v[112:115], v[132:135], v[196:199], v[112:115]
	v_mfma_f32_16x16x32_bf16 v[92:95], v[128:131], v[200:203], v[92:95]
	v_mfma_f32_16x16x32_bf16 v[92:95], v[132:135], v[204:207], v[92:95]
	v_mfma_f32_16x16x32_bf16 v[80:83], v[128:131], v[208:211], v[80:83]
	v_mfma_f32_16x16x32_bf16 v[80:83], v[132:135], v[212:215], v[80:83]
	v_mfma_f32_16x16x32_bf16 v[120:123], v[136:139], v[184:187], v[120:123]
	v_mfma_f32_16x16x32_bf16 v[120:123], v[140:143], v[188:191], v[120:123]
	v_mfma_f32_16x16x32_bf16 v[104:107], v[136:139], v[192:195], v[104:107]
	v_mfma_f32_16x16x32_bf16 v[104:107], v[140:143], v[196:199], v[104:107]
	v_mfma_f32_16x16x32_bf16 v[88:91], v[136:139], v[200:203], v[88:91]
	v_mfma_f32_16x16x32_bf16 v[88:91], v[140:143], v[204:207], v[88:91]
	v_mfma_f32_16x16x32_bf16 v[72:75], v[136:139], v[208:211], v[72:75]
	v_mfma_f32_16x16x32_bf16 v[72:75], v[140:143], v[212:215], v[72:75]
	v_mfma_f32_16x16x32_bf16 v[116:119], v[144:147], v[184:187], v[116:119]
	v_mfma_f32_16x16x32_bf16 v[116:119], v[148:151], v[188:191], v[116:119]
	v_mfma_f32_16x16x32_bf16 v[100:103], v[144:147], v[192:195], v[100:103]
	v_mfma_f32_16x16x32_bf16 v[100:103], v[148:151], v[196:199], v[100:103]
	v_mfma_f32_16x16x32_bf16 v[84:87], v[144:147], v[200:203], v[84:87]
	v_mfma_f32_16x16x32_bf16 v[84:87], v[148:151], v[204:207], v[84:87]
	v_mfma_f32_16x16x32_bf16 v[68:71], v[144:147], v[208:211], v[68:71]
	v_mfma_f32_16x16x32_bf16 v[68:71], v[148:151], v[212:215], v[68:71]
	v_mfma_f32_16x16x32_bf16 v[108:111], v[170:173], v[184:187], v[108:111]
	v_mfma_f32_16x16x32_bf16 v[108:111], v[178:181], v[188:191], v[108:111]
	v_mfma_f32_16x16x32_bf16 v[96:99], v[170:173], v[192:195], v[96:99]
	v_mfma_f32_16x16x32_bf16 v[96:99], v[178:181], v[196:199], v[96:99]
	v_mfma_f32_16x16x32_bf16 v[76:79], v[170:173], v[200:203], v[76:79]
	v_mfma_f32_16x16x32_bf16 v[76:79], v[178:181], v[204:207], v[76:79]
	v_mfma_f32_16x16x32_bf16 v[64:67], v[170:173], v[208:211], v[64:67]
	v_mfma_f32_16x16x32_bf16 v[64:67], v[178:181], v[212:215], v[64:67]
	s_barrier
	s_setprio 0
	s_add_i32 s12, s31, s8
	s_mov_b32 m0, s12
	ds_read_b128 v[184:187], v183 offset:49152
	ds_read_b128 v[188:191], v183 offset:50176
	ds_read_b128 v[192:195], v183 offset:51200
	ds_read_b128 v[196:199], v183 offset:52224
	ds_read_b128 v[200:203], v183 offset:53248
	ds_read_b128 v[204:207], v183 offset:54272
	ds_read_b128 v[208:211], v183 offset:55296
	ds_read_b128 v[212:215], v183 offset:56320
	s_add_u32 s100, s84, s16
	s_addc_u32 s101, s85, s17
	global_load_lds_dwordx4 v154, s[100:101]
	s_add_i32 m0, s12, 0x2000
	s_add_u32 s12, s84, 0x80080
	s_addc_u32 s13, s85, 0
	s_add_i32 s31, s33, s8
	global_load_lds_dwordx4 v158, s[100:101]
	s_mov_b32 m0, s31
	s_nop 0
	global_load_lds_dwordx4 v154, s[12:13]
	s_add_i32 m0, s31, 0x2000
	s_nop 0
	global_load_lds_dwordx4 v158, s[12:13]
	s_mov_b32 m0, s20
	s_nop 0
	s_add_u32 s100, s86, s16
	s_addc_u32 s101, s87, s17
	global_load_lds_dwordx4 v152, s[100:101]
	s_mov_b32 m0, s21
	s_nop 0
	global_load_lds_dwordx4 v156, s[100:101]
	s_waitcnt vmcnt(8)
	s_waitcnt lgkmcnt(0)
	s_setprio 1
	s_barrier
	v_mfma_f32_16x16x32_bf16 v[60:63], v[128:131], v[184:187], v[60:63]
	v_mfma_f32_16x16x32_bf16 v[60:63], v[132:135], v[188:191], v[60:63]
	v_mfma_f32_16x16x32_bf16 v[48:51], v[128:131], v[192:195], v[48:51]
	v_mfma_f32_16x16x32_bf16 v[48:51], v[132:135], v[196:199], v[48:51]
	v_mfma_f32_16x16x32_bf16 v[28:31], v[128:131], v[200:203], v[28:31]
	v_mfma_f32_16x16x32_bf16 v[28:31], v[132:135], v[204:207], v[28:31]
	v_mfma_f32_16x16x32_bf16 v[16:19], v[128:131], v[208:211], v[16:19]
	v_mfma_f32_16x16x32_bf16 v[16:19], v[132:135], v[212:215], v[16:19]
	v_mfma_f32_16x16x32_bf16 v[56:59], v[136:139], v[184:187], v[56:59]
	v_mfma_f32_16x16x32_bf16 v[56:59], v[140:143], v[188:191], v[56:59]
	v_mfma_f32_16x16x32_bf16 v[40:43], v[136:139], v[192:195], v[40:43]
	v_mfma_f32_16x16x32_bf16 v[40:43], v[140:143], v[196:199], v[40:43]
	v_mfma_f32_16x16x32_bf16 v[24:27], v[136:139], v[200:203], v[24:27]
	v_mfma_f32_16x16x32_bf16 v[24:27], v[140:143], v[204:207], v[24:27]
	v_mfma_f32_16x16x32_bf16 v[8:11], v[136:139], v[208:211], v[8:11]
	v_mfma_f32_16x16x32_bf16 v[8:11], v[140:143], v[212:215], v[8:11]
	v_mfma_f32_16x16x32_bf16 v[52:55], v[144:147], v[184:187], v[52:55]
	v_mfma_f32_16x16x32_bf16 v[52:55], v[148:151], v[188:191], v[52:55]
	v_mfma_f32_16x16x32_bf16 v[36:39], v[144:147], v[192:195], v[36:39]
	v_mfma_f32_16x16x32_bf16 v[36:39], v[148:151], v[196:199], v[36:39]
	v_mfma_f32_16x16x32_bf16 v[20:23], v[144:147], v[200:203], v[20:23]
	v_mfma_f32_16x16x32_bf16 v[20:23], v[148:151], v[204:207], v[20:23]
	v_mfma_f32_16x16x32_bf16 v[4:7], v[144:147], v[208:211], v[4:7]
	v_mfma_f32_16x16x32_bf16 v[4:7], v[148:151], v[212:215], v[4:7]
	v_mfma_f32_16x16x32_bf16 v[44:47], v[170:173], v[184:187], v[44:47]
	v_mfma_f32_16x16x32_bf16 v[44:47], v[178:181], v[188:191], v[44:47]
	v_mfma_f32_16x16x32_bf16 v[32:35], v[170:173], v[192:195], v[32:35]
	v_mfma_f32_16x16x32_bf16 v[32:35], v[178:181], v[196:199], v[32:35]
	v_mfma_f32_16x16x32_bf16 v[12:15], v[170:173], v[200:203], v[12:15]
	v_mfma_f32_16x16x32_bf16 v[12:15], v[178:181], v[204:207], v[12:15]
	v_mfma_f32_16x16x32_bf16 v[0:3], v[170:173], v[208:211], v[0:3]
	v_mfma_f32_16x16x32_bf16 v[0:3], v[178:181], v[212:215], v[0:3]
	s_barrier
	s_setprio 0
	s_add_i32 s3, s3, 2
	s_add_u32 s82, s82, 0x100
	s_addc_u32 s83, s83, 0
	s_add_u32 s30, s30, 0x100
	s_addc_u32 s2, s2, 0
	s_cmp_gt_u32 s3, 29
	s_cbranch_scc0 .LBB0_856
	s_and_b64 vcc, exec, s[70:71]
	s_cbranch_vccz .LBB0_859
	s_barrier

; #define PG8_STAGE(bufoff, gbase, voff) do { _Pragma("unroll") for (int _i = 0; _i < 2; ++_i) \
;         __builtin_amdgcn_global_load_lds((const unsigned*)((const char*)(gbase) + (voff)[_i]), (PG8_LAS unsigned*)(lds + (bufoff) + ldsw + _i * 8192), 16, 0, 0); } while (0)
; #define PG8_LDA(dst, b, h) do { _Pragma("unroll") for (int m = 0; m < 4; ++m) _Pragma("unroll") for (int k = 0; k < 2; ++k) dst[m][k] = *(const PG8_LAS bf16x8*)(lds + PG8_SA(b, h) + aoff + m * 2048 + k * 1024); } while (0)
; #define PG8_LDB(dst, b, h) do { _Pragma("unroll") for (int n = 0; n < 2; ++n) _Pragma("unroll") for (int k = 0; k < 2; ++k) dst[n][k] = *(const PG8_LAS bf16x8*)(lds + PG8_SB(b, h) + boff + n * 2048 + k * 1024); } while (0)
; #define PG8_MMA(ai, bj, At, Bt) do { __builtin_amdgcn_s_setprio(1); _Pragma("unroll") for (int m = 0; m < 4; ++m) _Pragma("unroll") for (int n = 0; n < 2; ++n) _Pragma("unroll") for (int k = 0; k < 2; ++k) \
;         acc[ai][bj][m][n] = __builtin_amdgcn_mfma_f32_16x16x32_bf16(Bt[n][k], At[m][k], acc[ai][bj][m][n], 0, 0, 0); __builtin_amdgcn_s_setprio(0); } while (0)
; #define PG8_WAIT_V(n) asm volatile("s_waitcnt vmcnt(" #n ")" ::: "memory")
; #define PG8_WAIT_L(n) asm volatile("s_waitcnt lgkmcnt(" #n ")" ::: "memory")
; #define PG8_BAR __builtin_amdgcn_s_barrier()
; #define PG8_SCHED __builtin_amdgcn_sched_barrier(0)
;     ...
;             const bool last = (t == nt - 2);
;             const char* a1 = PG8_KADV(cA, (size_t)(t + 1) * kstep);
;             const char* a2 = last ? nA : PG8_KADV(cA, (size_t)(t + 2) * kstep); const char* b2 = last ? nB : PG8_KADV(cB, (size_t)(t + 2) * kstep);
;             const char* a3 = PG8_KADV(a2, kstep); const char* b3 = PG8_KADV(b2, kstep);
;             if (last && has_next) S.a_ready(nxt);
;             if constexpr (SP2) {
;             PG8_LDB(B0, 0, 0); PG8_LDB(B1, 0, 1); PG8_SCHED; PG8_LDA(At, 0, 0); PG8_STAGE(PG8_SA(1, 1), a1 + hstep, voffA);
;             PG8_WAIT_V(8); PG8_WAIT_L(0); PG8_BAR; PG8_MMA(0, 0, At, B0); PG8_MMA(0, 1, At, B1); PG8_BAR; PG8_SCHED;
;             PG8_LDA(At, 0, 1); PG8_STAGE(PG8_SB(0, 0), b2, voffB); PG8_STAGE(PG8_SB(0, 1), b2 + hstep, voffB); PG8_STAGE(PG8_SA(0, 0), a2, voffA);
;             PG8_WAIT_V(8); PG8_WAIT_L(0); PG8_BAR; PG8_MMA(1, 0, At, B0); PG8_MMA(1, 1, At, B1); PG8_BAR; PG8_SCHED;
.LBB0_983:
	s_add_u32 s12, s70, 0xfff80080
	s_addc_u32 s13, s71, -1
	s_add_i32 s31, 0, 0x10000
	s_cmp_eq_u32 s3, 28
	s_cselect_b32 s75, s15, s13
	s_cselect_b32 s74, s28, s12
	s_cselect_b32 s73, s30, s2
	s_cselect_b32 s72, s33, s40
	s_add_i32 s42, 0, 0x14000
	v_add_u32_e32 v156, s31, v141
	v_add_u32_e32 v168, s42, v141
	ds_read_b128 v[144:147], v156
	ds_read_b128 v[148:151], v156 offset:1024
	ds_read_b128 v[152:155], v156 offset:2048
	ds_read_b128 v[156:159], v156 offset:3072
	ds_read_b128 v[160:163], v168
	ds_read_b128 v[164:167], v168 offset:1024
	ds_read_b128 v[170:173], v168 offset:2048
	ds_read_b128 v[178:181], v168 offset:3072
	s_add_i32 m0, s18, 0xc000
	ds_read_b128 v[182:185], v143
	ds_read_b128 v[186:189], v143 offset:1024
	ds_read_b128 v[190:193], v143 offset:2048
	ds_read_b128 v[194:197], v143 offset:3072
	ds_read_b128 v[198:201], v143 offset:4096
	ds_read_b128 v[202:205], v143 offset:5120
	ds_read_b128 v[206:209], v143 offset:6144
	ds_read_b128 v[210:213], v143 offset:7168
	global_load_lds_dwordx4 v136, s[70:71]
	s_add_i32 m0, s18, 0xe000
	s_nop 0
	global_load_lds_dwordx4 v138, s[70:71]
	s_waitcnt vmcnt(8)
	s_waitcnt lgkmcnt(0)
	s_setprio 1
	s_barrier
	v_mfma_f32_16x16x32_bf16 v[124:127], v[144:147], v[182:185], v[124:127]
	v_mfma_f32_16x16x32_bf16 v[124:127], v[148:151], v[186:189], v[124:127]
	v_mfma_f32_16x16x32_bf16 v[108:111], v[144:147], v[190:193], v[108:111]
	v_mfma_f32_16x16x32_bf16 v[108:111], v[148:151], v[194:197], v[108:111]
	v_mfma_f32_16x16x32_bf16 v[92:95], v[144:147], v[198:201], v[92:95]
	v_mfma_f32_16x16x32_bf16 v[92:95], v[148:151], v[202:205], v[92:95]
	v_mfma_f32_16x16x32_bf16 v[76:79], v[144:147], v[206:209], v[76:79]
	v_mfma_f32_16x16x32_bf16 v[76:79], v[148:151], v[210:213], v[76:79]
	v_mfma_f32_16x16x32_bf16 v[120:123], v[152:155], v[182:185], v[120:123]
	v_mfma_f32_16x16x32_bf16 v[120:123], v[156:159], v[186:189], v[120:123]
	v_mfma_f32_16x16x32_bf16 v[104:107], v[152:155], v[190:193], v[104:107]
	v_mfma_f32_16x16x32_bf16 v[104:107], v[156:159], v[194:197], v[104:107]
	v_mfma_f32_16x16x32_bf16 v[88:91], v[152:155], v[198:201], v[88:91]
	v_mfma_f32_16x16x32_bf16 v[88:91], v[156:159], v[202:205], v[88:91]
	v_mfma_f32_16x16x32_bf16 v[72:75], v[152:155], v[206:209], v[72:75]
	v_mfma_f32_16x16x32_bf16 v[72:75], v[156:159], v[210:213], v[72:75]
	v_mfma_f32_16x16x32_bf16 v[116:119], v[160:163], v[182:185], v[116:119]
	v_mfma_f32_16x16x32_bf16 v[116:119], v[164:167], v[186:189], v[116:119]
	v_mfma_f32_16x16x32_bf16 v[100:103], v[160:163], v[190:193], v[100:103]
	v_mfma_f32_16x16x32_bf16 v[100:103], v[164:167], v[194:197], v[100:103]
	v_mfma_f32_16x16x32_bf16 v[84:87], v[160:163], v[198:201], v[84:87]
	v_mfma_f32_16x16x32_bf16 v[84:87], v[164:167], v[202:205], v[84:87]
	v_mfma_f32_16x16x32_bf16 v[68:71], v[160:163], v[206:209], v[68:71]
	v_mfma_f32_16x16x32_bf16 v[68:71], v[164:167], v[210:213], v[68:71]
	v_mfma_f32_16x16x32_bf16 v[112:115], v[170:173], v[182:185], v[112:115]
	v_mfma_f32_16x16x32_bf16 v[112:115], v[178:181], v[186:189], v[112:115]
	v_mfma_f32_16x16x32_bf16 v[96:99], v[170:173], v[190:193], v[96:99]
	v_mfma_f32_16x16x32_bf16 v[96:99], v[178:181], v[194:197], v[96:99]
	v_mfma_f32_16x16x32_bf16 v[80:83], v[170:173], v[198:201], v[80:83]
	v_mfma_f32_16x16x32_bf16 v[80:83], v[178:181], v[202:205], v[80:83]
	v_mfma_f32_16x16x32_bf16 v[64:67], v[170:173], v[206:209], v[64:67]
	v_mfma_f32_16x16x32_bf16 v[64:67], v[178:181], v[210:213], v[64:67]
	s_barrier
	s_setprio 0
	s_add_i32 s12, s31, s10
	s_mov_b32 m0, s12
	ds_read_b128 v[182:185], v143 offset:16384
	ds_read_b128 v[186:189], v143 offset:17408
	ds_read_b128 v[190:193], v143 offset:18432
	ds_read_b128 v[194:197], v143 offset:19456
	ds_read_b128 v[198:201], v143 offset:20480
	ds_read_b128 v[202:205], v143 offset:21504
	ds_read_b128 v[206:209], v143 offset:22528
	ds_read_b128 v[210:213], v143 offset:23552
	global_load_lds_dwordx4 v132, s[72:73]
	s_add_i32 m0, s12, 0x2000
	s_add_u32 s12, s72, 0x80000
	s_addc_u32 s13, s73, 0
	s_add_i32 s31, s42, s10
	global_load_lds_dwordx4 v128, s[72:73]
	s_mov_b32 m0, s31
	s_nop 0
	global_load_lds_dwordx4 v132, s[12:13]
	s_add_i32 m0, s31, 0x2000
	s_nop 0
	global_load_lds_dwordx4 v128, s[12:13]
	s_mov_b32 m0, s18
	s_nop 0
	global_load_lds_dwordx4 v134, s[74:75]
	s_mov_b32 m0, s19
	s_nop 0
	global_load_lds_dwordx4 v130, s[74:75]
	s_waitcnt vmcnt(8)
	s_waitcnt lgkmcnt(0)
	s_setprio 1
	s_barrier
	v_mfma_f32_16x16x32_bf16 v[60:63], v[144:147], v[182:185], v[60:63]
	v_mfma_f32_16x16x32_bf16 v[60:63], v[148:151], v[186:189], v[60:63]
	v_mfma_f32_16x16x32_bf16 v[44:47], v[144:147], v[190:193], v[44:47]
	v_mfma_f32_16x16x32_bf16 v[44:47], v[148:151], v[194:197], v[44:47]
	v_mfma_f32_16x16x32_bf16 v[28:31], v[144:147], v[198:201], v[28:31]
	v_mfma_f32_16x16x32_bf16 v[28:31], v[148:151], v[202:205], v[28:31]
	v_mfma_f32_16x16x32_bf16 v[12:15], v[144:147], v[206:209], v[12:15]
	v_mfma_f32_16x16x32_bf16 v[12:15], v[148:151], v[210:213], v[12:15]
	v_mfma_f32_16x16x32_bf16 v[56:59], v[152:155], v[182:185], v[56:59]
	v_mfma_f32_16x16x32_bf16 v[56:59], v[156:159], v[186:189], v[56:59]
	v_mfma_f32_16x16x32_bf16 v[40:43], v[152:155], v[190:193], v[40:43]
	v_mfma_f32_16x16x32_bf16 v[40:43], v[156:159], v[194:197], v[40:43]
	v_mfma_f32_16x16x32_bf16 v[24:27], v[152:155], v[198:201], v[24:27]
	v_mfma_f32_16x16x32_bf16 v[24:27], v[156:159], v[202:205], v[24:27]
	v_mfma_f32_16x16x32_bf16 v[8:11], v[152:155], v[206:209], v[8:11]
	v_mfma_f32_16x16x32_bf16 v[8:11], v[156:159], v[210:213], v[8:11]
	v_mfma_f32_16x16x32_bf16 v[52:55], v[160:163], v[182:185], v[52:55]
	v_mfma_f32_16x16x32_bf16 v[52:55], v[164:167], v[186:189], v[52:55]
	v_mfma_f32_16x16x32_bf16 v[36:39], v[160:163], v[190:193], v[36:39]
	v_mfma_f32_16x16x32_bf16 v[36:39], v[164:167], v[194:197], v[36:39]
	v_mfma_f32_16x16x32_bf16 v[20:23], v[160:163], v[198:201], v[20:23]
	v_mfma_f32_16x16x32_bf16 v[20:23], v[164:167], v[202:205], v[20:23]
	v_mfma_f32_16x16x32_bf16 v[4:7], v[160:163], v[206:209], v[4:7]
	v_mfma_f32_16x16x32_bf16 v[4:7], v[164:167], v[210:213], v[4:7]
	v_mfma_f32_16x16x32_bf16 v[48:51], v[170:173], v[182:185], v[48:51]
	v_mfma_f32_16x16x32_bf16 v[48:51], v[178:181], v[186:189], v[48:51]
	v_mfma_f32_16x16x32_bf16 v[32:35], v[170:173], v[190:193], v[32:35]
	v_mfma_f32_16x16x32_bf16 v[32:35], v[178:181], v[194:197], v[32:35]
	v_mfma_f32_16x16x32_bf16 v[16:19], v[170:173], v[198:201], v[16:19]
	v_mfma_f32_16x16x32_bf16 v[16:19], v[178:181], v[202:205], v[16:19]
	v_mfma_f32_16x16x32_bf16 v[0:3], v[170:173], v[206:209], v[0:3]
	v_mfma_f32_16x16x32_bf16 v[0:3], v[178:181], v[210:213], v[0:3]
	s_barrier
; #define PG8_STAGE(bufoff, gbase, voff) do { _Pragma("unroll") for (int _i = 0; _i < 2; ++_i) \
;         __builtin_amdgcn_global_load_lds((const unsigned*)((const char*)(gbase) + (voff)[_i]), (PG8_LAS unsigned*)(lds + (bufoff) + ldsw + _i * 8192), 16, 0, 0); } while (0)
; #define PG8_LDA(dst, b, h) do { _Pragma("unroll") for (int m = 0; m < 4; ++m) _Pragma("unroll") for (int k = 0; k < 2; ++k) dst[m][k] = *(const PG8_LAS bf16x8*)(lds + PG8_SA(b, h) + aoff + m * 2048 + k * 1024); } while (0)
; #define PG8_LDB(dst, b, h) do { _Pragma("unroll") for (int n = 0; n < 2; ++n) _Pragma("unroll") for (int k = 0; k < 2; ++k) dst[n][k] = *(const PG8_LAS bf16x8*)(lds + PG8_SB(b, h) + boff + n * 2048 + k * 1024); } while (0)
; #define PG8_MMA(ai, bj, At, Bt) do { __builtin_amdgcn_s_setprio(1); _Pragma("unroll") for (int m = 0; m < 4; ++m) _Pragma("unroll") for (int n = 0; n < 2; ++n) _Pragma("unroll") for (int k = 0; k < 2; ++k) \
;         acc[ai][bj][m][n] = __builtin_amdgcn_mfma_f32_16x16x32_bf16(Bt[n][k], At[m][k], acc[ai][bj][m][n], 0, 0, 0); __builtin_amdgcn_s_setprio(0); } while (0)
; #define PG8_WAIT_V(n) asm volatile("s_waitcnt vmcnt(" #n ")" ::: "memory")
; #define PG8_WAIT_L(n) asm volatile("s_waitcnt lgkmcnt(" #n ")" ::: "memory")
; #define PG8_BAR __builtin_amdgcn_s_barrier()
; #define PG8_SCHED __builtin_amdgcn_sched_barrier(0)
;     ...
;             PG8_LDB(B0, 1, 0); PG8_LDB(B1, 1, 1); PG8_SCHED; PG8_LDA(At, 1, 0); PG8_STAGE(PG8_SA(0, 1), a2 + hstep, voffA);
;             PG8_WAIT_V(8); PG8_WAIT_L(0); PG8_BAR; PG8_MMA(0, 0, At, B0); PG8_MMA(0, 1, At, B1); PG8_BAR; PG8_SCHED;
;             PG8_LDA(At, 1, 1); PG8_STAGE(PG8_SB(1, 0), b3, voffB); PG8_STAGE(PG8_SB(1, 1), b3 + hstep, voffB); PG8_STAGE(PG8_SA(1, 0), a3, voffA);
;             PG8_WAIT_V(8); PG8_WAIT_L(0); PG8_BAR; PG8_MMA(1, 0, At, B0); PG8_MMA(1, 1, At, B1); PG8_BAR; PG8_SCHED;
	s_setprio 0
	s_add_i32 s31, 0, 0x18000
	s_add_i32 s42, 0, 0x1c000
	v_add_u32_e32 v156, s31, v141
	v_add_u32_e32 v168, s42, v141
	ds_read_b128 v[144:147], v156
	ds_read_b128 v[148:151], v156 offset:1024
	ds_read_b128 v[152:155], v156 offset:2048
	ds_read_b128 v[156:159], v156 offset:3072
	ds_read_b128 v[160:163], v168
	ds_read_b128 v[164:167], v168 offset:1024
	ds_read_b128 v[170:173], v168 offset:2048
	ds_read_b128 v[178:181], v168 offset:3072
	s_add_u32 s12, s74, 0x80000
	s_addc_u32 s13, s75, 0
	s_mov_b32 m0, s20
	ds_read_b128 v[182:185], v143 offset:32768
	ds_read_b128 v[186:189], v143 offset:33792
	ds_read_b128 v[190:193], v143 offset:34816
	ds_read_b128 v[194:197], v143 offset:35840
	ds_read_b128 v[198:201], v143 offset:36864
	ds_read_b128 v[202:205], v143 offset:37888
	ds_read_b128 v[206:209], v143 offset:38912
	ds_read_b128 v[210:213], v143 offset:39936
	global_load_lds_dwordx4 v134, s[12:13]
	s_mov_b32 m0, s21
	s_nop 0
	global_load_lds_dwordx4 v130, s[12:13]
	s_waitcnt vmcnt(8)
	s_waitcnt lgkmcnt(0)
	s_setprio 1
	s_barrier
	v_mfma_f32_16x16x32_bf16 v[124:127], v[144:147], v[182:185], v[124:127]
	v_mfma_f32_16x16x32_bf16 v[124:127], v[148:151], v[186:189], v[124:127]
	v_mfma_f32_16x16x32_bf16 v[108:111], v[144:147], v[190:193], v[108:111]
	v_mfma_f32_16x16x32_bf16 v[108:111], v[148:151], v[194:197], v[108:111]
	v_mfma_f32_16x16x32_bf16 v[92:95], v[144:147], v[198:201], v[92:95]
	v_mfma_f32_16x16x32_bf16 v[92:95], v[148:151], v[202:205], v[92:95]
	v_mfma_f32_16x16x32_bf16 v[76:79], v[144:147], v[206:209], v[76:79]
	v_mfma_f32_16x16x32_bf16 v[76:79], v[148:151], v[210:213], v[76:79]
	v_mfma_f32_16x16x32_bf16 v[120:123], v[152:155], v[182:185], v[120:123]
	v_mfma_f32_16x16x32_bf16 v[120:123], v[156:159], v[186:189], v[120:123]
	v_mfma_f32_16x16x32_bf16 v[104:107], v[152:155], v[190:193], v[104:107]
	v_mfma_f32_16x16x32_bf16 v[104:107], v[156:159], v[194:197], v[104:107]
	v_mfma_f32_16x16x32_bf16 v[88:91], v[152:155], v[198:201], v[88:91]
	v_mfma_f32_16x16x32_bf16 v[88:91], v[156:159], v[202:205], v[88:91]
	v_mfma_f32_16x16x32_bf16 v[72:75], v[152:155], v[206:209], v[72:75]
	v_mfma_f32_16x16x32_bf16 v[72:75], v[156:159], v[210:213], v[72:75]
	v_mfma_f32_16x16x32_bf16 v[116:119], v[160:163], v[182:185], v[116:119]
	v_mfma_f32_16x16x32_bf16 v[116:119], v[164:167], v[186:189], v[116:119]
	v_mfma_f32_16x16x32_bf16 v[100:103], v[160:163], v[190:193], v[100:103]
	v_mfma_f32_16x16x32_bf16 v[100:103], v[164:167], v[194:197], v[100:103]
	v_mfma_f32_16x16x32_bf16 v[84:87], v[160:163], v[198:201], v[84:87]
	v_mfma_f32_16x16x32_bf16 v[84:87], v[164:167], v[202:205], v[84:87]
	v_mfma_f32_16x16x32_bf16 v[68:71], v[160:163], v[206:209], v[68:71]
	v_mfma_f32_16x16x32_bf16 v[68:71], v[164:167], v[210:213], v[68:71]
	v_mfma_f32_16x16x32_bf16 v[112:115], v[170:173], v[182:185], v[112:115]
	v_mfma_f32_16x16x32_bf16 v[112:115], v[178:181], v[186:189], v[112:115]
	v_mfma_f32_16x16x32_bf16 v[96:99], v[170:173], v[190:193], v[96:99]
	v_mfma_f32_16x16x32_bf16 v[96:99], v[178:181], v[194:197], v[96:99]
	v_mfma_f32_16x16x32_bf16 v[80:83], v[170:173], v[198:201], v[80:83]
	v_mfma_f32_16x16x32_bf16 v[80:83], v[178:181], v[202:205], v[80:83]
	v_mfma_f32_16x16x32_bf16 v[64:67], v[170:173], v[206:209], v[64:67]
	v_mfma_f32_16x16x32_bf16 v[64:67], v[178:181], v[210:213], v[64:67]
	s_barrier
	s_setprio 0
	s_add_i32 s12, s31, s10
	s_mov_b32 m0, s12
	ds_read_b128 v[182:185], v143 offset:49152
	ds_read_b128 v[186:189], v143 offset:50176
	ds_read_b128 v[190:193], v143 offset:51200
	ds_read_b128 v[194:197], v143 offset:52224
	ds_read_b128 v[198:201], v143 offset:53248
	ds_read_b128 v[202:205], v143 offset:54272
	ds_read_b128 v[206:209], v143 offset:55296
	ds_read_b128 v[210:213], v143 offset:56320
	s_add_u32 s100, s72, s16
	s_addc_u32 s101, s73, s17
	global_load_lds_dwordx4 v132, s[100:101]
	s_add_i32 m0, s12, 0x2000
	s_add_u32 s12, s72, 0x80080
	s_addc_u32 s13, s73, 0
	s_add_i32 s31, s42, s10
	global_load_lds_dwordx4 v128, s[100:101]
	s_mov_b32 m0, s31
	s_nop 0
	global_load_lds_dwordx4 v132, s[12:13]
	s_add_i32 m0, s31, 0x2000
	s_nop 0
	global_load_lds_dwordx4 v128, s[12:13]
	s_mov_b32 m0, s22
	s_nop 0
	s_add_u32 s100, s74, s16
	s_addc_u32 s101, s75, s17
	global_load_lds_dwordx4 v134, s[100:101]
	s_mov_b32 m0, s23
	s_nop 0
	global_load_lds_dwordx4 v130, s[100:101]
	s_waitcnt vmcnt(8)
	s_waitcnt lgkmcnt(0)
	s_setprio 1
	s_barrier
	v_mfma_f32_16x16x32_bf16 v[60:63], v[144:147], v[182:185], v[60:63]
	v_mfma_f32_16x16x32_bf16 v[60:63], v[148:151], v[186:189], v[60:63]
	v_mfma_f32_16x16x32_bf16 v[44:47], v[144:147], v[190:193], v[44:47]
	v_mfma_f32_16x16x32_bf16 v[44:47], v[148:151], v[194:197], v[44:47]
	v_mfma_f32_16x16x32_bf16 v[28:31], v[144:147], v[198:201], v[28:31]
	v_mfma_f32_16x16x32_bf16 v[28:31], v[148:151], v[202:205], v[28:31]
	v_mfma_f32_16x16x32_bf16 v[12:15], v[144:147], v[206:209], v[12:15]
	v_mfma_f32_16x16x32_bf16 v[12:15], v[148:151], v[210:213], v[12:15]
	v_mfma_f32_16x16x32_bf16 v[56:59], v[152:155], v[182:185], v[56:59]
	v_mfma_f32_16x16x32_bf16 v[56:59], v[156:159], v[186:189], v[56:59]
	v_mfma_f32_16x16x32_bf16 v[40:43], v[152:155], v[190:193], v[40:43]
	v_mfma_f32_16x16x32_bf16 v[40:43], v[156:159], v[194:197], v[40:43]
	v_mfma_f32_16x16x32_bf16 v[24:27], v[152:155], v[198:201], v[24:27]
	v_mfma_f32_16x16x32_bf16 v[24:27], v[156:159], v[202:205], v[24:27]
	v_mfma_f32_16x16x32_bf16 v[8:11], v[152:155], v[206:209], v[8:11]
	v_mfma_f32_16x16x32_bf16 v[8:11], v[156:159], v[210:213], v[8:11]
	v_mfma_f32_16x16x32_bf16 v[52:55], v[160:163], v[182:185], v[52:55]
	v_mfma_f32_16x16x32_bf16 v[52:55], v[164:167], v[186:189], v[52:55]
	v_mfma_f32_16x16x32_bf16 v[36:39], v[160:163], v[190:193], v[36:39]
	v_mfma_f32_16x16x32_bf16 v[36:39], v[164:167], v[194:197], v[36:39]
	v_mfma_f32_16x16x32_bf16 v[20:23], v[160:163], v[198:201], v[20:23]
	v_mfma_f32_16x16x32_bf16 v[20:23], v[164:167], v[202:205], v[20:23]
	v_mfma_f32_16x16x32_bf16 v[4:7], v[160:163], v[206:209], v[4:7]
	v_mfma_f32_16x16x32_bf16 v[4:7], v[164:167], v[210:213], v[4:7]
	v_mfma_f32_16x16x32_bf16 v[48:51], v[170:173], v[182:185], v[48:51]
	v_mfma_f32_16x16x32_bf16 v[48:51], v[178:181], v[186:189], v[48:51]
	v_mfma_f32_16x16x32_bf16 v[32:35], v[170:173], v[190:193], v[32:35]
	v_mfma_f32_16x16x32_bf16 v[32:35], v[178:181], v[194:197], v[32:35]
	v_mfma_f32_16x16x32_bf16 v[16:19], v[170:173], v[198:201], v[16:19]
	v_mfma_f32_16x16x32_bf16 v[16:19], v[178:181], v[202:205], v[16:19]
	v_mfma_f32_16x16x32_bf16 v[0:3], v[170:173], v[206:209], v[0:3]
	v_mfma_f32_16x16x32_bf16 v[0:3], v[178:181], v[210:213], v[0:3]
	s_barrier
	s_setprio 0
	s_add_i32 s3, s3, 2
	s_add_u32 s70, s70, 0x100
	s_addc_u32 s71, s71, 0
	s_add_u32 s40, s40, 0x100
	s_addc_u32 s2, s2, 0
	s_cmp_gt_u32 s3, 29
	s_cbranch_scc0 .LBB0_983
	s_and_b64 vcc, exec, s[56:57]
	s_cbranch_vccz .LBB0_986
	s_barrier

; #define PG8_STAGE(bufoff, gbase, voff) do { _Pragma("unroll") for (int _i = 0; _i < 2; ++_i) \
;         __builtin_amdgcn_global_load_lds((const unsigned*)((const char*)(gbase) + (voff)[_i]), (PG8_LAS unsigned*)(lds + (bufoff) + ldsw + _i * 8192), 16, 0, 0); } while (0)
; #define PG8_LDA(dst, b, h) do { _Pragma("unroll") for (int m = 0; m < 4; ++m) _Pragma("unroll") for (int k = 0; k < 2; ++k) dst[m][k] = *(const PG8_LAS bf16x8*)(lds + PG8_SA(b, h) + aoff + m * 2048 + k * 1024); } while (0)
; #define PG8_LDB(dst, b, h) do { _Pragma("unroll") for (int n = 0; n < 2; ++n) _Pragma("unroll") for (int k = 0; k < 2; ++k) dst[n][k] = *(const PG8_LAS bf16x8*)(lds + PG8_SB(b, h) + boff + n * 2048 + k * 1024); } while (0)
; #define PG8_MMA(ai, bj, At, Bt) do { __builtin_amdgcn_s_setprio(1); _Pragma("unroll") for (int m = 0; m < 4; ++m) _Pragma("unroll") for (int n = 0; n < 2; ++n) _Pragma("unroll") for (int k = 0; k < 2; ++k) \
;         acc[ai][bj][m][n] = __builtin_amdgcn_mfma_f32_16x16x32_bf16(Bt[n][k], At[m][k], acc[ai][bj][m][n], 0, 0, 0); __builtin_amdgcn_s_setprio(0); } while (0)
; #define PG8_WAIT_V(n) asm volatile("s_waitcnt vmcnt(" #n ")" ::: "memory")
; #define PG8_WAIT_L(n) asm volatile("s_waitcnt lgkmcnt(" #n ")" ::: "memory")
; #define PG8_BAR __builtin_amdgcn_s_barrier()
; #define PG8_SCHED __builtin_amdgcn_sched_barrier(0)
;     ...
;             PG8_LDB(B0, 0, 0); PG8_LDB(B1, 0, 1); PG8_SCHED; PG8_LDA(At, 0, 0); PG8_STAGE(PG8_SA(1, 1), a1 + hstep, voffA);
;             PG8_WAIT_V(8); PG8_WAIT_L(0); PG8_BAR; PG8_MMA(0, 0, At, B0); PG8_MMA(0, 1, At, B1); PG8_BAR; PG8_SCHED;
;             PG8_LDA(At, 0, 1); PG8_STAGE(PG8_SB(0, 0), b2, voffB); PG8_STAGE(PG8_SB(0, 1), b2 + hstep, voffB); PG8_STAGE(PG8_SA(0, 0), a2, voffA);
;             PG8_WAIT_V(8); PG8_WAIT_L(0); PG8_BAR; PG8_MMA(1, 0, At, B0); PG8_MMA(1, 1, At, B1); PG8_BAR; PG8_SCHED;
.LBB0_1066:
	s_add_u32 s62, s60, 0xffffff00
	s_addc_u32 s63, s61, -1
	s_add_i32 s26, 0, 0x10000
	s_cmpk_eq_i32 s3, 0x54
	s_cselect_b32 s67, s5, s63
	s_cselect_b32 s66, s4, s62
	s_cselect_b32 s65, s59, s25
	s_cselect_b32 s64, s58, s2
	s_add_i32 s28, 0, 0x14000
	v_add_u32_e32 v152, s26, v166
	v_add_u32_e32 v164, s28, v166
	ds_read_b128 v[128:131], v152
	ds_read_b128 v[132:135], v152 offset:1024
	ds_read_b128 v[148:151], v152 offset:2048
	ds_read_b128 v[152:155], v152 offset:3072
	ds_read_b128 v[156:159], v164
	ds_read_b128 v[160:163], v164 offset:1024
	ds_read_b128 v[170:173], v164 offset:2048
	ds_read_b128 v[178:181], v164 offset:3072
	s_add_i32 m0, s13, 0xc000
	ds_read_b128 v[184:187], v183
	ds_read_b128 v[188:191], v183 offset:1024
	ds_read_b128 v[192:195], v183 offset:2048
	ds_read_b128 v[196:199], v183 offset:3072
	ds_read_b128 v[200:203], v183 offset:4096
	ds_read_b128 v[204:207], v183 offset:5120
	ds_read_b128 v[208:211], v183 offset:6144
	ds_read_b128 v[212:215], v183 offset:7168
	global_load_lds_dwordx4 v144, s[60:61]
	s_add_i32 m0, s13, 0xe000
	s_nop 0
	global_load_lds_dwordx4 v146, s[60:61]
	s_waitcnt vmcnt(8)
	s_waitcnt lgkmcnt(0)
	s_setprio 1
	s_barrier
	v_mfma_f32_16x16x32_bf16 v[124:127], v[128:131], v[184:187], v[124:127]
	v_mfma_f32_16x16x32_bf16 v[124:127], v[132:135], v[188:191], v[124:127]
	v_mfma_f32_16x16x32_bf16 v[112:115], v[128:131], v[192:195], v[112:115]
	v_mfma_f32_16x16x32_bf16 v[112:115], v[132:135], v[196:199], v[112:115]
	v_mfma_f32_16x16x32_bf16 v[92:95], v[128:131], v[200:203], v[92:95]
	v_mfma_f32_16x16x32_bf16 v[92:95], v[132:135], v[204:207], v[92:95]
	v_mfma_f32_16x16x32_bf16 v[80:83], v[128:131], v[208:211], v[80:83]
	v_mfma_f32_16x16x32_bf16 v[80:83], v[132:135], v[212:215], v[80:83]
	v_mfma_f32_16x16x32_bf16 v[120:123], v[148:151], v[184:187], v[120:123]
	v_mfma_f32_16x16x32_bf16 v[120:123], v[152:155], v[188:191], v[120:123]
	v_mfma_f32_16x16x32_bf16 v[104:107], v[148:151], v[192:195], v[104:107]
	v_mfma_f32_16x16x32_bf16 v[104:107], v[152:155], v[196:199], v[104:107]
	v_mfma_f32_16x16x32_bf16 v[88:91], v[148:151], v[200:203], v[88:91]
	v_mfma_f32_16x16x32_bf16 v[88:91], v[152:155], v[204:207], v[88:91]
	v_mfma_f32_16x16x32_bf16 v[72:75], v[148:151], v[208:211], v[72:75]
	v_mfma_f32_16x16x32_bf16 v[72:75], v[152:155], v[212:215], v[72:75]
	v_mfma_f32_16x16x32_bf16 v[116:119], v[156:159], v[184:187], v[116:119]
	v_mfma_f32_16x16x32_bf16 v[116:119], v[160:163], v[188:191], v[116:119]
	v_mfma_f32_16x16x32_bf16 v[100:103], v[156:159], v[192:195], v[100:103]
	v_mfma_f32_16x16x32_bf16 v[100:103], v[160:163], v[196:199], v[100:103]
	v_mfma_f32_16x16x32_bf16 v[84:87], v[156:159], v[200:203], v[84:87]
	v_mfma_f32_16x16x32_bf16 v[84:87], v[160:163], v[204:207], v[84:87]
	v_mfma_f32_16x16x32_bf16 v[68:71], v[156:159], v[208:211], v[68:71]
	v_mfma_f32_16x16x32_bf16 v[68:71], v[160:163], v[212:215], v[68:71]
	v_mfma_f32_16x16x32_bf16 v[108:111], v[170:173], v[184:187], v[108:111]
	v_mfma_f32_16x16x32_bf16 v[108:111], v[178:181], v[188:191], v[108:111]
	v_mfma_f32_16x16x32_bf16 v[96:99], v[170:173], v[192:195], v[96:99]
	v_mfma_f32_16x16x32_bf16 v[96:99], v[178:181], v[196:199], v[96:99]
	v_mfma_f32_16x16x32_bf16 v[76:79], v[170:173], v[200:203], v[76:79]
	v_mfma_f32_16x16x32_bf16 v[76:79], v[178:181], v[204:207], v[76:79]
	v_mfma_f32_16x16x32_bf16 v[64:67], v[170:173], v[208:211], v[64:67]
	v_mfma_f32_16x16x32_bf16 v[64:67], v[178:181], v[212:215], v[64:67]
	s_barrier
	s_setprio 0
	s_add_i32 s26, s26, s10
	s_mov_b32 m0, s26
	ds_read_b128 v[184:187], v183 offset:16384
	ds_read_b128 v[188:191], v183 offset:17408
	ds_read_b128 v[192:195], v183 offset:18432
	ds_read_b128 v[196:199], v183 offset:19456
	ds_read_b128 v[200:203], v183 offset:20480
	ds_read_b128 v[204:207], v183 offset:21504
	ds_read_b128 v[208:211], v183 offset:22528
	ds_read_b128 v[212:215], v183 offset:23552
	global_load_lds_dwordx4 v138, s[64:65]
	s_add_i32 m0, s26, 0x2000
	s_add_u32 s42, s64, 0x160000
	s_addc_u32 s43, s65, 0
	s_add_i32 s26, s28, s10
	global_load_lds_dwordx4 v142, s[64:65]
	s_mov_b32 m0, s26
	s_nop 0
	global_load_lds_dwordx4 v138, s[42:43]
	s_add_i32 m0, s26, 0x2000
	s_nop 0
	global_load_lds_dwordx4 v142, s[42:43]
	s_mov_b32 m0, s13
	s_nop 0
	global_load_lds_dwordx4 v136, s[66:67]
	s_mov_b32 m0, s18
	s_nop 0
	global_load_lds_dwordx4 v140, s[66:67]
	s_waitcnt vmcnt(8)
	s_waitcnt lgkmcnt(0)
	s_setprio 1
	s_barrier
	v_mfma_f32_16x16x32_bf16 v[60:63], v[128:131], v[184:187], v[60:63]
	v_mfma_f32_16x16x32_bf16 v[60:63], v[132:135], v[188:191], v[60:63]
	v_mfma_f32_16x16x32_bf16 v[48:51], v[128:131], v[192:195], v[48:51]
	v_mfma_f32_16x16x32_bf16 v[48:51], v[132:135], v[196:199], v[48:51]
	v_mfma_f32_16x16x32_bf16 v[28:31], v[128:131], v[200:203], v[28:31]
	v_mfma_f32_16x16x32_bf16 v[28:31], v[132:135], v[204:207], v[28:31]
	v_mfma_f32_16x16x32_bf16 v[16:19], v[128:131], v[208:211], v[16:19]
	v_mfma_f32_16x16x32_bf16 v[16:19], v[132:135], v[212:215], v[16:19]
	v_mfma_f32_16x16x32_bf16 v[56:59], v[148:151], v[184:187], v[56:59]
	v_mfma_f32_16x16x32_bf16 v[56:59], v[152:155], v[188:191], v[56:59]
	v_mfma_f32_16x16x32_bf16 v[40:43], v[148:151], v[192:195], v[40:43]
	v_mfma_f32_16x16x32_bf16 v[40:43], v[152:155], v[196:199], v[40:43]
	v_mfma_f32_16x16x32_bf16 v[24:27], v[148:151], v[200:203], v[24:27]
	v_mfma_f32_16x16x32_bf16 v[24:27], v[152:155], v[204:207], v[24:27]
	v_mfma_f32_16x16x32_bf16 v[8:11], v[148:151], v[208:211], v[8:11]
	v_mfma_f32_16x16x32_bf16 v[8:11], v[152:155], v[212:215], v[8:11]
	v_mfma_f32_16x16x32_bf16 v[52:55], v[156:159], v[184:187], v[52:55]
	v_mfma_f32_16x16x32_bf16 v[52:55], v[160:163], v[188:191], v[52:55]
	v_mfma_f32_16x16x32_bf16 v[36:39], v[156:159], v[192:195], v[36:39]
	v_mfma_f32_16x16x32_bf16 v[36:39], v[160:163], v[196:199], v[36:39]
	v_mfma_f32_16x16x32_bf16 v[20:23], v[156:159], v[200:203], v[20:23]
	v_mfma_f32_16x16x32_bf16 v[20:23], v[160:163], v[204:207], v[20:23]
	v_mfma_f32_16x16x32_bf16 v[4:7], v[156:159], v[208:211], v[4:7]
	v_mfma_f32_16x16x32_bf16 v[4:7], v[160:163], v[212:215], v[4:7]
	v_mfma_f32_16x16x32_bf16 v[44:47], v[170:173], v[184:187], v[44:47]
	v_mfma_f32_16x16x32_bf16 v[44:47], v[178:181], v[188:191], v[44:47]
	v_mfma_f32_16x16x32_bf16 v[32:35], v[170:173], v[192:195], v[32:35]
	v_mfma_f32_16x16x32_bf16 v[32:35], v[178:181], v[196:199], v[32:35]
	v_mfma_f32_16x16x32_bf16 v[12:15], v[170:173], v[200:203], v[12:15]
	v_mfma_f32_16x16x32_bf16 v[12:15], v[178:181], v[204:207], v[12:15]
	v_mfma_f32_16x16x32_bf16 v[0:3], v[170:173], v[208:211], v[0:3]
	v_mfma_f32_16x16x32_bf16 v[0:3], v[178:181], v[212:215], v[0:3]
	s_barrier
; #define PG8_STAGE(bufoff, gbase, voff) do { _Pragma("unroll") for (int _i = 0; _i < 2; ++_i) \
;         __builtin_amdgcn_global_load_lds((const unsigned*)((const char*)(gbase) + (voff)[_i]), (PG8_LAS unsigned*)(lds + (bufoff) + ldsw + _i * 8192), 16, 0, 0); } while (0)
; #define PG8_LDA(dst, b, h) do { _Pragma("unroll") for (int m = 0; m < 4; ++m) _Pragma("unroll") for (int k = 0; k < 2; ++k) dst[m][k] = *(const PG8_LAS bf16x8*)(lds + PG8_SA(b, h) + aoff + m * 2048 + k * 1024); } while (0)
; #define PG8_LDB(dst, b, h) do { _Pragma("unroll") for (int n = 0; n < 2; ++n) _Pragma("unroll") for (int k = 0; k < 2; ++k) dst[n][k] = *(const PG8_LAS bf16x8*)(lds + PG8_SB(b, h) + boff + n * 2048 + k * 1024); } while (0)
; #define PG8_MMA(ai, bj, At, Bt) do { __builtin_amdgcn_s_setprio(1); _Pragma("unroll") for (int m = 0; m < 4; ++m) _Pragma("unroll") for (int n = 0; n < 2; ++n) _Pragma("unroll") for (int k = 0; k < 2; ++k) \
;         acc[ai][bj][m][n] = __builtin_amdgcn_mfma_f32_16x16x32_bf16(Bt[n][k], At[m][k], acc[ai][bj][m][n], 0, 0, 0); __builtin_amdgcn_s_setprio(0); } while (0)
; #define PG8_WAIT_V(n) asm volatile("s_waitcnt vmcnt(" #n ")" ::: "memory")
; #define PG8_WAIT_L(n) asm volatile("s_waitcnt lgkmcnt(" #n ")" ::: "memory")
; #define PG8_BAR __builtin_amdgcn_s_barrier()
; #define PG8_SCHED __builtin_amdgcn_sched_barrier(0)
;     ...
;             PG8_LDB(B0, 1, 0); PG8_LDB(B1, 1, 1); PG8_SCHED; PG8_LDA(At, 1, 0); PG8_STAGE(PG8_SA(0, 1), a2 + hstep, voffA);
;             PG8_WAIT_V(8); PG8_WAIT_L(0); PG8_BAR; PG8_MMA(0, 0, At, B0); PG8_MMA(0, 1, At, B1); PG8_BAR; PG8_SCHED;
;             PG8_LDA(At, 1, 1); PG8_STAGE(PG8_SB(1, 0), b3, voffB); PG8_STAGE(PG8_SB(1, 1), b3 + hstep, voffB); PG8_STAGE(PG8_SA(1, 0), a3, voffA);
;             PG8_WAIT_V(8); PG8_WAIT_L(0); PG8_BAR; PG8_MMA(1, 0, At, B0); PG8_MMA(1, 1, At, B1); PG8_BAR; PG8_SCHED;
	s_setprio 0
	s_add_i32 s26, 0, 0x18000
	s_add_i32 s28, 0, 0x1c000
	v_add_u32_e32 v152, s26, v166
	v_add_u32_e32 v168, s28, v166
	ds_read_b128 v[128:131], v152
	ds_read_b128 v[132:135], v152 offset:1024
	ds_read_b128 v[148:151], v152 offset:2048
	ds_read_b128 v[152:155], v152 offset:3072
	ds_read_b128 v[156:159], v168
	ds_read_b128 v[160:163], v168 offset:1024
	ds_read_b128 v[170:173], v168 offset:2048
	ds_read_b128 v[178:181], v168 offset:3072
	s_add_u32 s42, s66, 0x160000
	s_addc_u32 s43, s67, 0
	s_mov_b32 m0, s19
	ds_read_b128 v[184:187], v183 offset:32768
	ds_read_b128 v[188:191], v183 offset:33792
	ds_read_b128 v[192:195], v183 offset:34816
	ds_read_b128 v[196:199], v183 offset:35840
	ds_read_b128 v[200:203], v183 offset:36864
	ds_read_b128 v[204:207], v183 offset:37888
	ds_read_b128 v[208:211], v183 offset:38912
	ds_read_b128 v[212:215], v183 offset:39936
	global_load_lds_dwordx4 v136, s[42:43]
	s_mov_b32 m0, s20
	s_nop 0
	global_load_lds_dwordx4 v140, s[42:43]
	s_waitcnt vmcnt(8)
	s_waitcnt lgkmcnt(0)
	s_setprio 1
	s_barrier
	v_mfma_f32_16x16x32_bf16 v[124:127], v[128:131], v[184:187], v[124:127]
	v_mfma_f32_16x16x32_bf16 v[124:127], v[132:135], v[188:191], v[124:127]
	v_mfma_f32_16x16x32_bf16 v[112:115], v[128:131], v[192:195], v[112:115]
	v_mfma_f32_16x16x32_bf16 v[112:115], v[132:135], v[196:199], v[112:115]
	v_mfma_f32_16x16x32_bf16 v[92:95], v[128:131], v[200:203], v[92:95]
	v_mfma_f32_16x16x32_bf16 v[92:95], v[132:135], v[204:207], v[92:95]
	v_mfma_f32_16x16x32_bf16 v[80:83], v[128:131], v[208:211], v[80:83]
	v_mfma_f32_16x16x32_bf16 v[80:83], v[132:135], v[212:215], v[80:83]
	v_mfma_f32_16x16x32_bf16 v[120:123], v[148:151], v[184:187], v[120:123]
	v_mfma_f32_16x16x32_bf16 v[120:123], v[152:155], v[188:191], v[120:123]
	v_mfma_f32_16x16x32_bf16 v[104:107], v[148:151], v[192:195], v[104:107]
	v_mfma_f32_16x16x32_bf16 v[104:107], v[152:155], v[196:199], v[104:107]
	v_mfma_f32_16x16x32_bf16 v[88:91], v[148:151], v[200:203], v[88:91]
	v_mfma_f32_16x16x32_bf16 v[88:91], v[152:155], v[204:207], v[88:91]
	v_mfma_f32_16x16x32_bf16 v[72:75], v[148:151], v[208:211], v[72:75]
	v_mfma_f32_16x16x32_bf16 v[72:75], v[152:155], v[212:215], v[72:75]
	v_mfma_f32_16x16x32_bf16 v[116:119], v[156:159], v[184:187], v[116:119]
	v_mfma_f32_16x16x32_bf16 v[116:119], v[160:163], v[188:191], v[116:119]
	v_mfma_f32_16x16x32_bf16 v[100:103], v[156:159], v[192:195], v[100:103]
	v_mfma_f32_16x16x32_bf16 v[100:103], v[160:163], v[196:199], v[100:103]
	v_mfma_f32_16x16x32_bf16 v[84:87], v[156:159], v[200:203], v[84:87]
	v_mfma_f32_16x16x32_bf16 v[84:87], v[160:163], v[204:207], v[84:87]
	v_mfma_f32_16x16x32_bf16 v[68:71], v[156:159], v[208:211], v[68:71]
	v_mfma_f32_16x16x32_bf16 v[68:71], v[160:163], v[212:215], v[68:71]
	v_mfma_f32_16x16x32_bf16 v[108:111], v[170:173], v[184:187], v[108:111]
	v_mfma_f32_16x16x32_bf16 v[108:111], v[178:181], v[188:191], v[108:111]
	v_mfma_f32_16x16x32_bf16 v[96:99], v[170:173], v[192:195], v[96:99]
	v_mfma_f32_16x16x32_bf16 v[96:99], v[178:181], v[196:199], v[96:99]
	v_mfma_f32_16x16x32_bf16 v[76:79], v[170:173], v[200:203], v[76:79]
	v_mfma_f32_16x16x32_bf16 v[76:79], v[178:181], v[204:207], v[76:79]
	v_mfma_f32_16x16x32_bf16 v[64:67], v[170:173], v[208:211], v[64:67]
	v_mfma_f32_16x16x32_bf16 v[64:67], v[178:181], v[212:215], v[64:67]
	s_barrier
	s_setprio 0
	s_add_i32 s26, s26, s10
	s_mov_b32 m0, s26
	ds_read_b128 v[184:187], v183 offset:49152
	ds_read_b128 v[188:191], v183 offset:50176
	ds_read_b128 v[192:195], v183 offset:51200
	ds_read_b128 v[196:199], v183 offset:52224
	ds_read_b128 v[200:203], v183 offset:53248
	ds_read_b128 v[204:207], v183 offset:54272
	ds_read_b128 v[208:211], v183 offset:55296
	ds_read_b128 v[212:215], v183 offset:56320
	s_add_u32 s100, s64, s38
	s_addc_u32 s101, s65, s39
	global_load_lds_dwordx4 v138, s[100:101]
	s_add_i32 m0, s26, 0x2000
	s_add_u32 s42, s64, 0x15ff80
	s_addc_u32 s43, s65, 0
	s_add_i32 s26, s28, s10
	global_load_lds_dwordx4 v142, s[100:101]
	s_mov_b32 m0, s26
	s_nop 0
	global_load_lds_dwordx4 v138, s[42:43]
	s_add_i32 m0, s26, 0x2000
	s_nop 0
	global_load_lds_dwordx4 v142, s[42:43]
	s_mov_b32 m0, s12
	s_nop 0
	s_add_u32 s100, s66, s38
	s_addc_u32 s101, s67, s39
	global_load_lds_dwordx4 v136, s[100:101]
	s_mov_b32 m0, s21
	s_nop 0
	global_load_lds_dwordx4 v140, s[100:101]
	s_waitcnt vmcnt(8)
	s_waitcnt lgkmcnt(0)
	s_setprio 1
	s_barrier
	v_mfma_f32_16x16x32_bf16 v[60:63], v[128:131], v[184:187], v[60:63]
	v_mfma_f32_16x16x32_bf16 v[60:63], v[132:135], v[188:191], v[60:63]
	v_mfma_f32_16x16x32_bf16 v[48:51], v[128:131], v[192:195], v[48:51]
	v_mfma_f32_16x16x32_bf16 v[48:51], v[132:135], v[196:199], v[48:51]
	v_mfma_f32_16x16x32_bf16 v[28:31], v[128:131], v[200:203], v[28:31]
	v_mfma_f32_16x16x32_bf16 v[28:31], v[132:135], v[204:207], v[28:31]
	v_mfma_f32_16x16x32_bf16 v[16:19], v[128:131], v[208:211], v[16:19]
	v_mfma_f32_16x16x32_bf16 v[16:19], v[132:135], v[212:215], v[16:19]
	v_mfma_f32_16x16x32_bf16 v[56:59], v[148:151], v[184:187], v[56:59]
	v_mfma_f32_16x16x32_bf16 v[56:59], v[152:155], v[188:191], v[56:59]
	v_mfma_f32_16x16x32_bf16 v[40:43], v[148:151], v[192:195], v[40:43]
	v_mfma_f32_16x16x32_bf16 v[40:43], v[152:155], v[196:199], v[40:43]
	v_mfma_f32_16x16x32_bf16 v[24:27], v[148:151], v[200:203], v[24:27]
	v_mfma_f32_16x16x32_bf16 v[24:27], v[152:155], v[204:207], v[24:27]
	v_mfma_f32_16x16x32_bf16 v[8:11], v[148:151], v[208:211], v[8:11]
	v_mfma_f32_16x16x32_bf16 v[8:11], v[152:155], v[212:215], v[8:11]
	v_mfma_f32_16x16x32_bf16 v[52:55], v[156:159], v[184:187], v[52:55]
	v_mfma_f32_16x16x32_bf16 v[52:55], v[160:163], v[188:191], v[52:55]
	v_mfma_f32_16x16x32_bf16 v[36:39], v[156:159], v[192:195], v[36:39]
	v_mfma_f32_16x16x32_bf16 v[36:39], v[160:163], v[196:199], v[36:39]
	v_mfma_f32_16x16x32_bf16 v[20:23], v[156:159], v[200:203], v[20:23]
	v_mfma_f32_16x16x32_bf16 v[20:23], v[160:163], v[204:207], v[20:23]
	v_mfma_f32_16x16x32_bf16 v[4:7], v[156:159], v[208:211], v[4:7]
	v_mfma_f32_16x16x32_bf16 v[4:7], v[160:163], v[212:215], v[4:7]
	v_mfma_f32_16x16x32_bf16 v[44:47], v[170:173], v[184:187], v[44:47]
	v_mfma_f32_16x16x32_bf16 v[44:47], v[178:181], v[188:191], v[44:47]
	v_mfma_f32_16x16x32_bf16 v[32:35], v[170:173], v[192:195], v[32:35]
	v_mfma_f32_16x16x32_bf16 v[32:35], v[178:181], v[196:199], v[32:35]
	v_mfma_f32_16x16x32_bf16 v[12:15], v[170:173], v[200:203], v[12:15]
	v_mfma_f32_16x16x32_bf16 v[12:15], v[178:181], v[204:207], v[12:15]
	v_mfma_f32_16x16x32_bf16 v[0:3], v[170:173], v[208:211], v[0:3]
	v_mfma_f32_16x16x32_bf16 v[0:3], v[178:181], v[212:215], v[0:3]
	s_barrier
	s_setprio 0
	s_add_i32 s3, s3, 2
	s_add_u32 s2, s2, 0xffffff00
	s_addc_u32 s25, s25, -1
	s_cmpk_gt_u32 s3, 0x55
	s_mov_b64 s[60:61], s[62:63]
	s_cbranch_scc0 .LBB0_1066
	s_and_b64 vcc, exec, s[56:57]
	s_cbranch_vccz .LBB0_1069
	s_barrier
